# residual GEMM phases (FFN-down, out-proj) hand-written with 128x256 macro-tiles + LDS-DMA ring + own gated-residual/rowsq epilogue
# speedup vs baseline: 1.0530x; 1.0145x over previous
.LBB0_6:
	s_load_dwordx2 s[12:13], s[84:85], 0xd60
	s_load_dwordx2 s[10:11], s[84:85], 0xd68
	v_lshrrev_b32_e32 v3, 20, v0
	v_lshrrev_b32_e32 v0, 10, v0
	v_or_b32_e32 v0, v0, v3
	s_waitcnt lgkmcnt(0)
	s_cmp_gt_i32 s13, -1
	s_cselect_b64 s[4:5], -1, 0
	v_writelane_b32 v248, s4, 6
	v_mov_b32_e32 v196, 1
	v_mov_b32_e32 v197, 0x3ecc95a3
	v_writelane_b32 v248, s5, 7
	s_add_u32 s4, s0, 0x7c74300
	s_addc_u32 s5, s1, 0
	v_writelane_b32 v248, s4, 8
	v_mov_b32_e32 v198, 0x358637bd
	v_mov_b32_e32 v199, 0x3f4ccccd
	v_writelane_b32 v248, s5, 9
	s_add_u32 s4, s0, 0x7c74500
	s_addc_u32 s5, s1, 0
	v_writelane_b32 v248, s4, 10
	v_mov_b32_e32 v170, 0x3f317218
	v_mov_b32_e32 v201, 0x7f800000
	v_writelane_b32 v248, s5, 11
	s_add_u32 s4, s0, 0x7c74600
	s_addc_u32 s5, s1, 0
	v_writelane_b32 v248, s4, 12
	v_mov_b32_e32 v202, 0x7fc00000
	v_mov_b32_e32 v203, 0xff800000
	v_writelane_b32 v248, s5, 13
	s_add_u32 s4, s0, 0x7c74700
	s_addc_u32 s5, s1, 0
	v_writelane_b32 v248, s4, 14
	v_mov_b32_e32 v204, 16
	v_mov_b32_e32 v205, 0x42800000
	v_writelane_b32 v248, s5, 15
	s_add_u32 s4, s0, 0x7c74800
	s_addc_u32 s5, s1, 0
	v_writelane_b32 v248, s4, 16
	v_not_b32_e32 v206, 63
	v_mov_b32_e32 v207, 0x400
	v_writelane_b32 v248, s5, 17
	s_add_u32 s4, s0, 0x7c74900
	s_addc_u32 s5, s1, 0
	v_writelane_b32 v248, s4, 18
	v_mov_b32_e32 v208, 0x200
	v_mov_b32_e32 v209, 0x19158100
	v_writelane_b32 v248, s5, 19
	s_add_u32 s4, s0, 0x7c74a00
	s_addc_u32 s5, s1, 0
	v_writelane_b32 v248, s4, 20
	v_mov_b32_e32 v210, 0x18558100
	s_movk_i32 s86, 0xffe0
	v_writelane_b32 v248, s5, 21
	s_add_u32 s4, s0, 0x7c74b00
	s_addc_u32 s5, s1, 0
	v_writelane_b32 v248, s4, 22
	s_movk_i32 s34, 0x90
	s_mov_b32 s94, 0x5040100
	v_writelane_b32 v248, s5, 23
	s_add_u32 s4, s0, 0x7c74c00
	s_addc_u32 s5, s1, 0
	v_writelane_b32 v248, s4, 24
	s_mov_b32 s31, 0x9000
	s_mov_b32 s30, 0x12000
	v_writelane_b32 v248, s5, 25
	s_add_u32 s4, s0, 0x7c74d00
	s_addc_u32 s5, s1, 0
	v_writelane_b32 v248, s4, 26
	s_mov_b32 s25, 0x1b000
	s_movk_i32 s22, 0xc0
	v_writelane_b32 v248, s5, 27
	s_add_u32 s4, s0, 0x7c74e00
	s_addc_u32 s5, s1, 0
	v_writelane_b32 v248, s4, 28
	s_mov_b32 s27, 0x3e38aa3b
	s_mov_b32 s96, s12
	v_writelane_b32 v248, s5, 29
	s_add_u32 s4, s0, 0x7c74f00
	s_addc_u32 s5, s1, 0
	v_writelane_b32 v248, s4, 30
	s_mov_b64 s[36:37], 0x80
	s_mov_b64 s[38:39], 0x4000
	v_writelane_b32 v248, s5, 31
	s_add_u32 s4, s0, 0x7c75000
	s_addc_u32 s5, s1, 0
	v_writelane_b32 v248, s4, 32
	s_nop 1
	v_writelane_b32 v248, s5, 33
	s_add_u32 s4, s0, 0x7c75100
	s_addc_u32 s5, s1, 0
	v_writelane_b32 v248, s4, 34
	s_nop 1
	v_writelane_b32 v248, s5, 35
	s_add_u32 s4, s0, 0x7c75200
	s_addc_u32 s5, s1, 0
	v_writelane_b32 v248, s4, 36
	s_nop 1
	v_writelane_b32 v248, s5, 37
	s_add_u32 s4, s0, 0x7c75300
	s_addc_u32 s5, s1, 0
	v_writelane_b32 v248, s4, 38
	s_nop 1
	v_writelane_b32 v248, s5, 39
	s_add_u32 s4, s0, 0x7c75400
	s_addc_u32 s5, s1, 0
	v_writelane_b32 v248, s4, 40
	s_cmp_eq_u32 s8, 15
	s_nop 0
	v_writelane_b32 v248, s5, 41
	s_cselect_b64 s[4:5], -1, 0
	v_writelane_b32 v248, s4, 42
	s_cmp_eq_u32 s8, 14
	s_nop 0
	v_writelane_b32 v248, s5, 43
	s_cselect_b64 s[4:5], -1, 0
	v_writelane_b32 v248, s4, 44
	s_cmp_eq_u32 s8, 13
	s_nop 0
	v_writelane_b32 v248, s5, 45
	s_cselect_b64 s[4:5], -1, 0
	v_writelane_b32 v248, s4, 46
	s_cmp_eq_u32 s8, 12
	s_nop 0
	v_writelane_b32 v248, s5, 47
	s_cselect_b64 s[4:5], -1, 0
	v_writelane_b32 v248, s4, 48
	s_cmp_eq_u32 s8, 11
	s_nop 0
	v_writelane_b32 v248, s5, 49
	s_cselect_b64 s[4:5], -1, 0
	v_writelane_b32 v248, s4, 50
	s_cmp_eq_u32 s8, 10
	s_nop 0
	v_writelane_b32 v248, s5, 51
	s_cselect_b64 s[4:5], -1, 0
	v_writelane_b32 v248, s4, 52
	s_cmp_eq_u32 s8, 9
	s_nop 0
	v_writelane_b32 v248, s5, 53
	s_cselect_b64 s[4:5], -1, 0
	v_writelane_b32 v248, s4, 54
	s_cmp_eq_u32 s8, 8
	s_nop 0
	v_writelane_b32 v248, s5, 55
	s_cselect_b64 s[4:5], -1, 0
	v_writelane_b32 v248, s4, 56
	s_cmp_eq_u32 s8, 7
	s_nop 0
	v_writelane_b32 v248, s5, 57
	s_cselect_b64 s[4:5], -1, 0
	v_writelane_b32 v248, s4, 58
	s_cmp_eq_u32 s8, 6
	s_nop 0
	v_writelane_b32 v248, s5, 59
	s_cselect_b64 s[4:5], -1, 0
	v_writelane_b32 v248, s4, 60
	s_cmp_eq_u32 s8, 5
	s_nop 0
	v_writelane_b32 v248, s5, 61
	s_cselect_b64 s[4:5], -1, 0
	v_writelane_b32 v248, s4, 62
	s_cmp_eq_u32 s8, 4
	s_nop 0
	v_writelane_b32 v248, s5, 63
	s_cselect_b64 s[4:5], -1, 0
	v_writelane_b32 v247, s4, 0
	s_cmp_eq_u32 s8, 3
	s_nop 0
	v_writelane_b32 v247, s5, 1
	s_cselect_b64 s[4:5], -1, 0
	v_writelane_b32 v247, s4, 2
	s_cmp_eq_u32 s8, 2
	s_nop 0
	v_writelane_b32 v247, s5, 3
	s_cselect_b64 s[4:5], -1, 0
	v_writelane_b32 v247, s4, 4
	s_cmp_eq_u32 s8, 1
	s_nop 0
	v_writelane_b32 v247, s5, 5
	s_cselect_b64 s[4:5], -1, 0
	v_writelane_b32 v247, s4, 6
	s_cmp_eq_u32 s8, 0
	s_nop 0
	v_writelane_b32 v247, s5, 7
	s_cselect_b64 s[4:5], -1, 0
	v_writelane_b32 v247, s4, 8
	s_nop 1
	v_writelane_b32 v247, s5, 9
	s_lshl_b32 s4, s8, 8
	s_add_u32 s2, s2, s4
	s_addc_u32 s3, s3, 0
	s_add_u32 s4, s2, 0x1400
	s_addc_u32 s5, s3, 0
	v_writelane_b32 v247, s4, 10
	s_add_u32 s2, s2, 0x2400
	s_addc_u32 s3, s3, 0
	v_writelane_b32 v247, s5, 11
	v_writelane_b32 v247, s2, 12
	s_nop 1
	v_writelane_b32 v247, s3, 13
	s_add_u32 s2, s0, 0x7c77500
	s_addc_u32 s3, s1, 0
	v_writelane_b32 v247, s2, 14
	s_add_u32 s0, s0, 0x7c77600
	s_addc_u32 s1, s1, 0
	v_writelane_b32 v247, s3, 15
	v_writelane_b32 v247, s0, 16
	s_and_b32 s2, s82, 7
	s_lshr_b32 s23, s10, 3
	v_writelane_b32 v247, s1, 17
	s_lshl_b32 s0, s82, 2
	v_writelane_b32 v247, s0, 18
	s_lshr_b32 s0, s82, 3
	s_lshl_b32 s14, s10, 2
	s_cmpk_lt_u32 s82, 0x300
	s_mov_b32 s3, 0
	s_cselect_b64 s[4:5], -1, 0
	s_mov_b32 s83, s3
	v_writelane_b32 v247, s4, 19
	v_cvt_f32_u32_e32 v1, s23
	s_mul_i32 s26, s2, 12
	v_writelane_b32 v247, s5, 20
	s_lshl_b64 s[4:5], s[82:83], 16
	v_writelane_b32 v247, s4, 21
	s_cmpk_lt_u32 s82, 0x380
	s_mov_b32 s83, s0
	v_writelane_b32 v247, s5, 22
	s_cselect_b64 s[0:1], -1, 0
	v_writelane_b32 v247, s0, 23
	s_cmpk_lt_u32 s82, 0x240
	v_rcp_iflag_f32_e32 v1, v1
	v_writelane_b32 v247, s1, 24
	s_cselect_b64 s[0:1], -1, 0
	v_writelane_b32 v247, s0, 25
	s_cmpk_lt_u32 s82, 0x1080
	v_mul_f32_e32 v1, 0x4f7ffffe, v1
	v_writelane_b32 v247, s1, 26
	s_cselect_b64 s[0:1], -1, 0
	v_writelane_b32 v247, s0, 27
	s_lshr_b32 s9, s10, 1
	v_cvt_u32_f32_e32 v1, v1
	v_writelane_b32 v247, s1, 28
	s_and_b32 s0, s82, 1
	s_cmpk_lt_u32 s82, 0x6000
	s_cselect_b64 s[4:5], -1, 0
	v_writelane_b32 v247, s4, 29
	s_lshr_b32 s13, s82, 1
	s_lshl_b32 s6, s0, 4
	v_writelane_b32 v247, s5, 30
	v_writelane_b32 v247, s0, 31
	s_lshl_b32 s7, s0, 8
	s_lshl_b32 s0, s82, 8
	s_lshl_b32 s16, s10, 8
	s_cmp_eq_u32 s82, 0
	v_writelane_b32 v247, s0, 32
	s_cselect_b64 s[0:1], -1, 0
	v_writelane_b32 v247, s0, 33
	s_cmpk_lt_i32 s82, 0x240
	s_mov_b32 s17, s16
	v_writelane_b32 v247, s1, 34
	s_cselect_b64 s[0:1], -1, 0
	v_writelane_b32 v247, s0, 35
	s_lshl_b32 s24, s10, 9
	s_mov_b32 s28, s24
	v_writelane_b32 v247, s1, 36
	s_sub_i32 s0, 0, s23
	v_readfirstlane_b32 s1, v1
	s_mul_i32 s0, s0, s1
	s_mul_hi_u32 s0, s1, s0
	s_add_i32 s4, s1, s0
	s_mov_b32 s1, -1
	s_mov_b32 s0, s3
	s_and_b64 s[0:1], s[16:17], s[0:1]
	v_writelane_b32 v247, s0, 37
	s_nop 1
	v_writelane_b32 v247, s1, 38
	s_mul_hi_u32 s0, s4, 0x60
	s_mul_i32 s0, s0, s23
	s_sub_i32 s0, 0x60, s0
	s_sub_i32 s1, s0, s23
	s_cmp_ge_u32 s0, s23
	s_cselect_b32 s0, s1, s0
	s_sub_i32 s1, s0, s23
	s_cmp_ge_u32 s0, s23
	s_cselect_b32 s8, s1, s0
	s_mov_b32 s8, 48
	v_mov_b32_e32 v1, s8
	s_cmp_eq_u32 s8, 0
	v_sub_co_u32_e32 v1, vcc, s83, v1
	s_cselect_b64 s[0:1], -1, 0
	s_xor_b64 s[4:5], vcc, -1
	s_or_b64 s[0:1], s[0:1], s[4:5]
	v_writelane_b32 v247, s0, 39
	v_readfirstlane_b32 s4, v1
	v_cvt_f32_u32_e32 v1, s16
	v_writelane_b32 v247, s1, 40
	s_load_dword s1, s[84:85], 0xd70
	s_mul_i32 s0, s11, s10
	v_rcp_iflag_f32_e32 v1, v1
	s_mov_b32 s5, 0x2d000
	s_waitcnt lgkmcnt(0)
	s_mul_i32 s0, s0, s1
	v_writelane_b32 v247, s0, 41
	s_sub_i32 s0, s23, s8
	s_mul_i32 s1, s0, s2
	s_add_i32 s1, s4, s1
	v_mul_f32_e32 v1, 0x4f7ffffe, v1
	v_writelane_b32 v247, s1, 42
	v_cvt_u32_f32_e32 v1, v1
	s_lshl_b32 s95, s0, 3
	s_and_b32 s0, s10, -2
	v_writelane_b32 v247, s0, 43
	s_lshl_b32 s0, s83, 5
	s_sub_i32 s1, 0, s16
	v_writelane_b32 v247, s0, 44
	s_lshl_b32 s0, s23, 5
	s_bitcmp1_b32 s82, 3
	v_mul_lo_u32 v2, s1, v1
	v_writelane_b32 v247, s0, 45
	s_cselect_b64 s[0:1], -1, 0
	v_writelane_b32 v247, s0, 46
	s_bitcmp1_b32 s10, 3
	v_mul_hi_u32 v2, v1, v2
	v_writelane_b32 v247, s1, 47
	s_cselect_b64 s[0:1], -1, 0
	v_writelane_b32 v247, s0, 48
	s_ashr_i32 s15, s14, 31
	v_add_u32_e32 v195, v1, v2
	v_writelane_b32 v247, s1, 49
	s_lshl_b32 s0, s13, 9
	s_or_b32 s0, s0, s7
	v_writelane_b32 v247, s0, 50
	s_add_i32 s0, s13, s9
	s_lshl_b32 s0, s0, 9
	s_or_b32 s0, s0, s7
	v_writelane_b32 v247, s0, 51
	s_movk_i32 s0, 0x3ff
	v_and_or_b32 v0, v0, s0, v194
	s_mul_i32 s0, s2, 14
	v_writelane_b32 v247, s0, 52
	v_writelane_b32 v247, s14, 53
	s_lshl_b32 s0, s6, 2
	s_ashr_i32 s17, s16, 31
	v_writelane_b32 v247, s15, 54
	v_writelane_b32 v247, s0, 55
	s_lshl_b32 s0, s9, 11
	v_writelane_b32 v247, s0, 56
	s_lshl_b32 s0, s9, 10
	v_writelane_b32 v247, s0, 57
	s_lshl_b32 s0, s9, 6
	v_writelane_b32 v247, s0, 58
	v_writelane_b32 v247, s13, 59
	s_lshl_b32 s0, s13, 5
	v_writelane_b32 v247, s0, 60
	s_lshl_b32 s0, s9, 7
	v_writelane_b32 v247, s0, 61
	v_writelane_b32 v247, s9, 62
	s_lshl_b32 s0, s9, 5
	v_writelane_b32 v247, s0, 63
	s_lshl_b32 s0, s82, 10
	v_writelane_b32 v246, s0, 0
	s_add_i32 s0, 16, 0x6c00
	v_writelane_b32 v246, s0, 1
	s_add_i32 s0, 16, 0x2400
	v_writelane_b32 v246, s0, 2
	v_cmp_eq_u32_e64 s[0:1], 0, v0
	s_lshl_b32 s29, s10, 10
	v_mbcnt_lo_u32_b32 v2, -1, 0
	v_writelane_b32 v246, s0, 3
	s_lshl_b64 s[42:43], s[16:17], 2
	v_mov_b32_e32 v1, 0
	v_writelane_b32 v246, s1, 4
	s_mov_b32 s0, s16
	v_writelane_b32 v246, s0, 5
	v_mbcnt_hi_u32_b32 v200, -1, v2
	s_mov_b32 s7, 0x3e16c740
	v_writelane_b32 v246, s1, 6
	s_lshl_b64 s[0:1], s[14:15], 12
	v_writelane_b32 v246, s0, 7
	s_movk_i32 s4, 0x1600
	s_nop 0
	v_writelane_b32 v246, s1, 8
	v_writelane_b32 v246, s82, 9
	s_nop 1
	v_writelane_b32 v246, s83, 10
	v_writelane_b32 v246, s84, 11
	s_nop 1
	v_writelane_b32 v246, s85, 12
	v_writelane_b32 v246, s83, 13
	v_writelane_b32 v246, s23, 14
	v_writelane_b32 v246, s24, 15
	v_writelane_b32 v246, s26, 16
	v_writelane_b32 v246, s28, 17
	v_writelane_b32 v246, s29, 18
	v_writelane_b32 v246, s42, 19
	s_nop 1
	v_writelane_b32 v246, s43, 20
	s_branch .LBB0_9

.LBB0_259:
	s_andn2_b64 vcc, exec, s[10:11]
	s_cbranch_vccnz .LBB0_418
	v_readlane_b32 s8, v247, 19
	v_readlane_b32 s9, v247, 20
	s_mov_b64 s[56:57], s[84:85]
	s_andn2_b64 vcc, exec, s[8:9]
	s_cbranch_vccnz .LBB0_327
	s_load_dwordx2 s[40:41], s[56:57], 0x108
	v_readlane_b32 s2, v246, 27
	v_readlane_b32 s8, v246, 21
	s_add_i32 s2, s2, 2
	v_readlane_b32 s9, v246, 22
	s_and_b64 s[8:9], s[8:9], exec
	s_mov_b32 s6, 0x10b98100
	s_cselect_b32 s6, s6, 0x11c18100
	s_lshl_b64 s[8:9], s[0:1], 21
	s_waitcnt lgkmcnt(0)
	s_add_u32 s42, s40, 0x14958100
	s_mul_hi_i32 s10, s2, 0xc0000
	s_mul_i32 s2, s2, 0xc0000
	s_addc_u32 s43, s41, 0
	s_add_u32 s2, s40, s2
	s_addc_u32 s10, s41, s10
	s_add_u32 s44, s2, 0x7200000
	s_addc_u32 s45, s10, 0
	s_add_u32 s2, s40, s6
	s_addc_u32 s6, s41, 0
	s_add_u32 s46, s2, s8
	s_addc_u32 s47, s6, s9
	s_add_u32 s8, s40, 0x7bc5000
	s_addc_u32 s9, s41, 0
	v_readlane_b32 s12, v247, 44
	s_mov_b32 s13, s83
	v_and_b32_e32 v177, 63, v194
	v_lshrrev_b32_e32 v178, 6, v194
	v_lshrrev_b32_e32 v160, 2, v194
	v_lshlrev_b32_e32 v160, 11, v160
	v_and_b32_e32 v179, 3, v177
	v_bfe_u32 v180, v177, 4, 2
	v_xor_b32_e32 v179, v179, v180
	v_lshl_add_u32 v160, v179, 4, v160
	v_add_u32_e32 v161, 0x20000, v160
	v_and_b32_e32 v174, 31, v177
	v_lshrrev_b32_e32 v182, 5, v177
	v_bfe_u32 v183, v174, 2, 2
	v_xor_b32_e32 v184, v182, v183
	v_xor_b32_e32 v185, 2, v184
	v_lshrrev_b32_e32 v186, 1, v178
	v_and_b32_e32 v187, 1, v178
	v_lshl_add_u32 v188, v186, 6, v174
	v_lshl_add_u32 v189, v187, 6, v174
	v_lshlrev_b32_e32 v188, 6, v188
	v_lshlrev_b32_e32 v189, 6, v189
	v_lshl_add_u32 v154, v184, 4, v188
	v_lshl_add_u32 v155, v185, 4, v188
	v_lshl_add_u32 v156, v184, 4, v189
	v_lshl_add_u32 v157, v185, 4, v189
	v_add_u32_e32 v158, 0x2000, v156
	v_add_u32_e32 v159, 0x2000, v157
	v_lshlrev_b32_e32 v190, 6, v186
	v_lshl_add_u32 v190, v182, 2, v190
	v_lshl_add_u32 v191, v187, 6, v174
	v_lshlrev_b32_e32 v192, 12, v190
	v_lshl_add_u32 v162, v191, 2, v192
	v_add_u32_e32 v163, 0x1000, v162
	v_add_u32_e32 v164, 0x2000, v162
	v_add_u32_e32 v165, 0x3000, v162
	v_lshlrev_b32_e32 v166, 2, v191
	v_mul_u32_u24_e32 v167, 0xc000, v187
	v_lshl_add_u32 v167, v190, 2, v167
	v_xor_b32_e32 v168, 16, v177
	v_lshlrev_b32_e32 v168, 2, v168
	v_xor_b32_e32 v169, 8, v177
	v_lshlrev_b32_e32 v169, 2, v169
	v_xor_b32_e32 v171, 4, v177
	v_lshlrev_b32_e32 v171, 2, v171
	v_xor_b32_e32 v172, 2, v177
	v_lshlrev_b32_e32 v172, 2, v172
	v_xor_b32_e32 v173, 1, v177
	v_lshlrev_b32_e32 v173, 2, v173
	v_readfirstlane_b32 s65, v194
	s_nop 0
	s_lshl_b32 s65, s65, 4
	s_add_u32 s65, s65, 16
	s_mov_b32 s16, s83
.Lhw_outproj_tloop:
	s_cmpk_gt_u32 s16, 47
	s_cbranch_scc1 .Lhw_outproj_exit
	v_readlane_b32 s6, v246, 16
	s_lshr_b32 s2, s16, 2
	s_and_b32 s15, s16, 3
	s_add_i32 s6, s6, s2
	s_lshl_b32 s6, s6, 7
	s_lshl_b32 s15, s15, 8
	s_mul_i32 vcc_lo, s6, 0x800
	s_add_u32 s66, s42, vcc_lo
	s_addc_u32 s67, s43, 0
	s_mul_i32 vcc_lo, s15, 0x800
	s_add_u32 s62, s46, vcc_lo
	s_addc_u32 s63, s47, 0
	s_add_u32 s18, s62, 0x40000
	s_addc_u32 s19, s63, 0
	s_barrier
	s_add_u32 m0, s65, 0x0
	s_nop 0
	global_load_lds_dwordx4 v160, s[66:67]
	s_add_u32 m0, s65, 0x1000
	s_nop 0
	global_load_lds_dwordx4 v161, s[66:67]
	s_add_u32 m0, s65, 0x2000
	s_nop 0
	global_load_lds_dwordx4 v160, s[62:63]
	s_add_u32 m0, s65, 0x3000
	s_nop 0
	global_load_lds_dwordx4 v161, s[62:63]
	s_add_u32 m0, s65, 0x4000
	s_nop 0
	global_load_lds_dwordx4 v160, s[18:19]
	s_add_u32 m0, s65, 0x5000
	s_nop 0
	global_load_lds_dwordx4 v161, s[18:19]
	s_add_u32 s66, s66, 64
	s_addc_u32 s67, s67, 0
	s_add_u32 s62, s62, 64
	s_addc_u32 s63, s63, 0
	s_add_u32 s18, s18, 64
	s_addc_u32 s19, s19, 0
	s_add_u32 m0, s65, 0x6000
	s_nop 0
	global_load_lds_dwordx4 v160, s[66:67]
	s_add_u32 m0, s65, 0x7000
	s_nop 0
	global_load_lds_dwordx4 v161, s[66:67]
	s_add_u32 m0, s65, 0x8000
	s_nop 0
	global_load_lds_dwordx4 v160, s[62:63]
	s_add_u32 m0, s65, 0x9000
	s_nop 0
	global_load_lds_dwordx4 v161, s[62:63]
	s_add_u32 m0, s65, 0xa000
	s_nop 0
	global_load_lds_dwordx4 v160, s[18:19]
	s_add_u32 m0, s65, 0xb000
	s_nop 0
	global_load_lds_dwordx4 v161, s[18:19]
	s_add_u32 s66, s66, 64
	s_addc_u32 s67, s67, 0
	s_add_u32 s62, s62, 64
	s_addc_u32 s63, s63, 0
	s_add_u32 s18, s18, 64
	s_addc_u32 s19, s19, 0
	v_mov_b32_e32 v2, 0
	v_mov_b32_e32 v3, 0
	v_mov_b32_e32 v4, 0
	v_mov_b32_e32 v5, 0
	v_mov_b32_e32 v6, 0
	v_mov_b32_e32 v7, 0
	v_mov_b32_e32 v8, 0
	v_mov_b32_e32 v9, 0
	v_mov_b32_e32 v10, 0
	v_mov_b32_e32 v11, 0
	v_mov_b32_e32 v12, 0
	v_mov_b32_e32 v13, 0
	v_mov_b32_e32 v14, 0
	v_mov_b32_e32 v15, 0
	v_mov_b32_e32 v16, 0
	v_mov_b32_e32 v17, 0
	v_mov_b32_e32 v18, 0
	v_mov_b32_e32 v19, 0
	v_mov_b32_e32 v20, 0
	v_mov_b32_e32 v21, 0
	v_mov_b32_e32 v22, 0
	v_mov_b32_e32 v23, 0
	v_mov_b32_e32 v24, 0
	v_mov_b32_e32 v25, 0
	v_mov_b32_e32 v26, 0
	v_mov_b32_e32 v27, 0
	v_mov_b32_e32 v28, 0
	v_mov_b32_e32 v29, 0
	v_mov_b32_e32 v30, 0
	v_mov_b32_e32 v31, 0
	v_mov_b32_e32 v32, 0
	v_mov_b32_e32 v33, 0
	v_mov_b32_e32 v34, 0
	v_mov_b32_e32 v35, 0
	v_mov_b32_e32 v36, 0
	v_mov_b32_e32 v37, 0
	v_mov_b32_e32 v38, 0
	v_mov_b32_e32 v39, 0
	v_mov_b32_e32 v40, 0
	v_mov_b32_e32 v41, 0
	v_mov_b32_e32 v42, 0
	v_mov_b32_e32 v43, 0
	v_mov_b32_e32 v44, 0
	v_mov_b32_e32 v45, 0
	v_mov_b32_e32 v46, 0
	v_mov_b32_e32 v47, 0
	v_mov_b32_e32 v48, 0
	v_mov_b32_e32 v49, 0
	v_mov_b32_e32 v50, 0
	v_mov_b32_e32 v51, 0
	v_mov_b32_e32 v52, 0
	v_mov_b32_e32 v53, 0
	v_mov_b32_e32 v54, 0
	v_mov_b32_e32 v55, 0
	v_mov_b32_e32 v56, 0
	v_mov_b32_e32 v57, 0
	v_mov_b32_e32 v58, 0
	v_mov_b32_e32 v59, 0
	v_mov_b32_e32 v60, 0
	v_mov_b32_e32 v61, 0
	v_mov_b32_e32 v62, 0
	v_mov_b32_e32 v63, 0
	v_mov_b32_e32 v64, 0
	v_mov_b32_e32 v65, 0
	v_mov_b32_e32 v66, 0
	v_mov_b32_e32 v67, 0
	v_mov_b32_e32 v68, 0
	v_mov_b32_e32 v69, 0
	v_mov_b32_e32 v70, 0
	v_mov_b32_e32 v71, 0
	v_mov_b32_e32 v72, 0
	v_mov_b32_e32 v73, 0
	v_mov_b32_e32 v74, 0
	v_mov_b32_e32 v75, 0
	v_mov_b32_e32 v76, 0
	v_mov_b32_e32 v77, 0
	v_mov_b32_e32 v78, 0
	v_mov_b32_e32 v79, 0
	v_mov_b32_e32 v80, 0
	v_mov_b32_e32 v81, 0
	v_mov_b32_e32 v82, 0
	v_mov_b32_e32 v83, 0
	v_mov_b32_e32 v84, 0
	v_mov_b32_e32 v85, 0
	v_mov_b32_e32 v86, 0
	v_mov_b32_e32 v87, 0
	v_mov_b32_e32 v88, 0
	v_mov_b32_e32 v89, 0
	v_mov_b32_e32 v90, 0
	v_mov_b32_e32 v91, 0
	v_mov_b32_e32 v92, 0
	v_mov_b32_e32 v93, 0
	v_mov_b32_e32 v94, 0
	v_mov_b32_e32 v95, 0
	v_mov_b32_e32 v96, 0
	v_mov_b32_e32 v97, 0
	v_mov_b32_e32 v98, 0
	v_mov_b32_e32 v99, 0
	v_mov_b32_e32 v100, 0
	v_mov_b32_e32 v101, 0
	v_mov_b32_e32 v102, 0
	v_mov_b32_e32 v103, 0
	v_mov_b32_e32 v104, 0
	v_mov_b32_e32 v105, 0
	v_mov_b32_e32 v106, 0
	v_mov_b32_e32 v107, 0
	v_mov_b32_e32 v108, 0
	v_mov_b32_e32 v109, 0
	v_mov_b32_e32 v110, 0
	v_mov_b32_e32 v111, 0
	v_mov_b32_e32 v112, 0
	v_mov_b32_e32 v113, 0
	v_mov_b32_e32 v114, 0
	v_mov_b32_e32 v115, 0
	v_mov_b32_e32 v116, 0
	v_mov_b32_e32 v117, 0
	v_mov_b32_e32 v118, 0
	v_mov_b32_e32 v119, 0
	v_mov_b32_e32 v120, 0
	v_mov_b32_e32 v121, 0
	v_mov_b32_e32 v122, 0
	v_mov_b32_e32 v123, 0
	v_mov_b32_e32 v124, 0
	v_mov_b32_e32 v125, 0
	v_mov_b32_e32 v126, 0
	v_mov_b32_e32 v127, 0
	v_mov_b32_e32 v128, 0
	v_mov_b32_e32 v129, 0
	s_waitcnt vmcnt(6)
	s_barrier
	ds_read_b128 v[130:133], v154 offset:16
	ds_read_b128 v[138:141], v156 offset:8208
	ds_read_b128 v[142:145], v156 offset:10256
	ds_read_b128 v[134:137], v154 offset:2064
	ds_read_b128 v[146:149], v158 offset:8208
	ds_read_b128 v[150:153], v158 offset:10256
	s_mov_b32 s59, 10
.Lhw_outproj_loop:
	s_waitcnt vmcnt(0)
	s_barrier
	s_waitcnt lgkmcnt(0)
	v_mfma_f32_32x32x16_bf16 v[2:17], v[130:133], v[138:141], v[2:17]
	ds_read_b128 v[212:215], v155 offset:16
	s_add_u32 m0, s65, 0xc000
	v_mfma_f32_32x32x16_bf16 v[18:33], v[130:133], v[142:145], v[18:33]
	ds_read_b128 v[220:223], v157 offset:8208
	global_load_lds_dwordx4 v160, s[66:67]
	v_mfma_f32_32x32x16_bf16 v[34:49], v[134:137], v[138:141], v[34:49]
	ds_read_b128 v[224:227], v157 offset:10256
	s_add_u32 m0, s65, 0xd000
	v_mfma_f32_32x32x16_bf16 v[50:65], v[134:137], v[142:145], v[50:65]
	ds_read_b128 v[216:219], v155 offset:2064
	global_load_lds_dwordx4 v161, s[66:67]
	v_mfma_f32_32x32x16_bf16 v[66:81], v[130:133], v[146:149], v[66:81]
	ds_read_b128 v[228:231], v159 offset:8208
	s_add_u32 m0, s65, 0xe000
	v_mfma_f32_32x32x16_bf16 v[82:97], v[130:133], v[150:153], v[82:97]
	ds_read_b128 v[232:235], v159 offset:10256
	global_load_lds_dwordx4 v160, s[62:63]
	v_mfma_f32_32x32x16_bf16 v[98:113], v[134:137], v[146:149], v[98:113]
	s_add_u32 m0, s65, 0xf000
	v_mfma_f32_32x32x16_bf16 v[114:129], v[134:137], v[150:153], v[114:129]
	global_load_lds_dwordx4 v161, s[62:63]
	s_waitcnt lgkmcnt(4)
	v_mfma_f32_32x32x16_bf16 v[2:17], v[212:215], v[220:223], v[2:17]
	s_add_u32 m0, s65, 0x10000
	ds_read_b128 v[130:133], v154 offset:24592
	s_waitcnt lgkmcnt(4)
	v_mfma_f32_32x32x16_bf16 v[18:33], v[212:215], v[224:227], v[18:33]
	global_load_lds_dwordx4 v160, s[18:19]
	ds_read_b128 v[138:141], v156 offset:32784
	s_waitcnt lgkmcnt(4)
	v_mfma_f32_32x32x16_bf16 v[34:49], v[216:219], v[220:223], v[34:49]
	s_add_u32 m0, s65, 0x11000
	ds_read_b128 v[142:145], v156 offset:34832
	s_waitcnt lgkmcnt(5)
	v_mfma_f32_32x32x16_bf16 v[50:65], v[216:219], v[224:227], v[50:65]
	global_load_lds_dwordx4 v161, s[18:19]
	ds_read_b128 v[134:137], v154 offset:26640
	s_waitcnt lgkmcnt(5)
	v_mfma_f32_32x32x16_bf16 v[66:81], v[212:215], v[228:231], v[66:81]
	s_add_u32 s66, s66, 64
	s_addc_u32 s67, s67, 0
	ds_read_b128 v[146:149], v158 offset:32784
	s_waitcnt lgkmcnt(5)
	v_mfma_f32_32x32x16_bf16 v[82:97], v[212:215], v[232:235], v[82:97]
	s_add_u32 s62, s62, 64
	s_addc_u32 s63, s63, 0
	ds_read_b128 v[150:153], v158 offset:34832
	s_waitcnt lgkmcnt(7)
	v_mfma_f32_32x32x16_bf16 v[98:113], v[216:219], v[228:231], v[98:113]
	s_add_u32 s18, s18, 64
	s_addc_u32 s19, s19, 0
	s_waitcnt lgkmcnt(6)
	v_mfma_f32_32x32x16_bf16 v[114:129], v[216:219], v[232:235], v[114:129]
	s_waitcnt vmcnt(0)
	s_barrier
	s_waitcnt lgkmcnt(0)
	v_mfma_f32_32x32x16_bf16 v[2:17], v[130:133], v[138:141], v[2:17]
	ds_read_b128 v[212:215], v155 offset:24592
	s_add_u32 m0, s65, 0x0
	v_mfma_f32_32x32x16_bf16 v[18:33], v[130:133], v[142:145], v[18:33]
	ds_read_b128 v[220:223], v157 offset:32784
	global_load_lds_dwordx4 v160, s[66:67]
	v_mfma_f32_32x32x16_bf16 v[34:49], v[134:137], v[138:141], v[34:49]
	ds_read_b128 v[224:227], v157 offset:34832
	s_add_u32 m0, s65, 0x1000
	v_mfma_f32_32x32x16_bf16 v[50:65], v[134:137], v[142:145], v[50:65]
	ds_read_b128 v[216:219], v155 offset:26640
	global_load_lds_dwordx4 v161, s[66:67]
	v_mfma_f32_32x32x16_bf16 v[66:81], v[130:133], v[146:149], v[66:81]
	ds_read_b128 v[228:231], v159 offset:32784
	s_add_u32 m0, s65, 0x2000
	v_mfma_f32_32x32x16_bf16 v[82:97], v[130:133], v[150:153], v[82:97]
	ds_read_b128 v[232:235], v159 offset:34832
	global_load_lds_dwordx4 v160, s[62:63]
	v_mfma_f32_32x32x16_bf16 v[98:113], v[134:137], v[146:149], v[98:113]
	s_add_u32 m0, s65, 0x3000
	v_mfma_f32_32x32x16_bf16 v[114:129], v[134:137], v[150:153], v[114:129]
	global_load_lds_dwordx4 v161, s[62:63]
	s_waitcnt lgkmcnt(4)
	v_mfma_f32_32x32x16_bf16 v[2:17], v[212:215], v[220:223], v[2:17]
	s_add_u32 m0, s65, 0x4000
	ds_read_b128 v[130:133], v154 offset:49168
	s_waitcnt lgkmcnt(4)
	v_mfma_f32_32x32x16_bf16 v[18:33], v[212:215], v[224:227], v[18:33]
	global_load_lds_dwordx4 v160, s[18:19]
	ds_read_b128 v[138:141], v156 offset:57360
	s_waitcnt lgkmcnt(4)
	v_mfma_f32_32x32x16_bf16 v[34:49], v[216:219], v[220:223], v[34:49]
	s_add_u32 m0, s65, 0x5000
	ds_read_b128 v[142:145], v156 offset:59408
	s_waitcnt lgkmcnt(5)
	v_mfma_f32_32x32x16_bf16 v[50:65], v[216:219], v[224:227], v[50:65]
	global_load_lds_dwordx4 v161, s[18:19]
	ds_read_b128 v[134:137], v154 offset:51216
	s_waitcnt lgkmcnt(5)
	v_mfma_f32_32x32x16_bf16 v[66:81], v[212:215], v[228:231], v[66:81]
	s_add_u32 s66, s66, 64
	s_addc_u32 s67, s67, 0
	ds_read_b128 v[146:149], v158 offset:57360
	s_waitcnt lgkmcnt(5)
	v_mfma_f32_32x32x16_bf16 v[82:97], v[212:215], v[232:235], v[82:97]
	s_add_u32 s62, s62, 64
	s_addc_u32 s63, s63, 0
	ds_read_b128 v[150:153], v158 offset:59408
	s_waitcnt lgkmcnt(7)
	v_mfma_f32_32x32x16_bf16 v[98:113], v[216:219], v[228:231], v[98:113]
	s_add_u32 s18, s18, 64
	s_addc_u32 s19, s19, 0
	s_waitcnt lgkmcnt(6)
	v_mfma_f32_32x32x16_bf16 v[114:129], v[216:219], v[232:235], v[114:129]
	s_waitcnt vmcnt(0)
	s_barrier
	s_waitcnt lgkmcnt(0)
	v_mfma_f32_32x32x16_bf16 v[2:17], v[130:133], v[138:141], v[2:17]
	ds_read_b128 v[212:215], v155 offset:49168
	s_add_u32 m0, s65, 0x6000
	v_mfma_f32_32x32x16_bf16 v[18:33], v[130:133], v[142:145], v[18:33]
	ds_read_b128 v[220:223], v157 offset:57360
	global_load_lds_dwordx4 v160, s[66:67]
	v_mfma_f32_32x32x16_bf16 v[34:49], v[134:137], v[138:141], v[34:49]
	ds_read_b128 v[224:227], v157 offset:59408
	s_add_u32 m0, s65, 0x7000
	v_mfma_f32_32x32x16_bf16 v[50:65], v[134:137], v[142:145], v[50:65]
	ds_read_b128 v[216:219], v155 offset:51216
	global_load_lds_dwordx4 v161, s[66:67]
	v_mfma_f32_32x32x16_bf16 v[66:81], v[130:133], v[146:149], v[66:81]
	ds_read_b128 v[228:231], v159 offset:57360
	s_add_u32 m0, s65, 0x8000
	v_mfma_f32_32x32x16_bf16 v[82:97], v[130:133], v[150:153], v[82:97]
	ds_read_b128 v[232:235], v159 offset:59408
	global_load_lds_dwordx4 v160, s[62:63]
	v_mfma_f32_32x32x16_bf16 v[98:113], v[134:137], v[146:149], v[98:113]
	s_add_u32 m0, s65, 0x9000
	v_mfma_f32_32x32x16_bf16 v[114:129], v[134:137], v[150:153], v[114:129]
	global_load_lds_dwordx4 v161, s[62:63]
	s_waitcnt lgkmcnt(4)
	v_mfma_f32_32x32x16_bf16 v[2:17], v[212:215], v[220:223], v[2:17]
	s_add_u32 m0, s65, 0xa000
	ds_read_b128 v[130:133], v154 offset:16
	s_waitcnt lgkmcnt(4)
	v_mfma_f32_32x32x16_bf16 v[18:33], v[212:215], v[224:227], v[18:33]
	global_load_lds_dwordx4 v160, s[18:19]
	ds_read_b128 v[138:141], v156 offset:8208
	s_waitcnt lgkmcnt(4)
	v_mfma_f32_32x32x16_bf16 v[34:49], v[216:219], v[220:223], v[34:49]
	s_add_u32 m0, s65, 0xb000
	ds_read_b128 v[142:145], v156 offset:10256
	s_waitcnt lgkmcnt(5)
	v_mfma_f32_32x32x16_bf16 v[50:65], v[216:219], v[224:227], v[50:65]
	global_load_lds_dwordx4 v161, s[18:19]
	ds_read_b128 v[134:137], v154 offset:2064
	s_waitcnt lgkmcnt(5)
	v_mfma_f32_32x32x16_bf16 v[66:81], v[212:215], v[228:231], v[66:81]
	s_add_u32 s66, s66, 64
	s_addc_u32 s67, s67, 0
	ds_read_b128 v[146:149], v158 offset:8208
	s_waitcnt lgkmcnt(5)
	v_mfma_f32_32x32x16_bf16 v[82:97], v[212:215], v[232:235], v[82:97]
	s_add_u32 s62, s62, 64
	s_addc_u32 s63, s63, 0
	ds_read_b128 v[150:153], v158 offset:10256
	s_waitcnt lgkmcnt(7)
	v_mfma_f32_32x32x16_bf16 v[98:113], v[216:219], v[228:231], v[98:113]
	s_add_u32 s18, s18, 64
	s_addc_u32 s19, s19, 0
	s_waitcnt lgkmcnt(6)
	v_mfma_f32_32x32x16_bf16 v[114:129], v[216:219], v[232:235], v[114:129]
	s_sub_u32 s59, s59, 1
	s_cmp_lg_u32 s59, 0
	s_cbranch_scc1 .Lhw_outproj_loop
	s_waitcnt vmcnt(0)
	s_barrier
	s_waitcnt lgkmcnt(0)
	v_mfma_f32_32x32x16_bf16 v[2:17], v[130:133], v[138:141], v[2:17]
	ds_read_b128 v[212:215], v155 offset:16
	v_mfma_f32_32x32x16_bf16 v[18:33], v[130:133], v[142:145], v[18:33]
	ds_read_b128 v[220:223], v157 offset:8208
	v_mfma_f32_32x32x16_bf16 v[34:49], v[134:137], v[138:141], v[34:49]
	ds_read_b128 v[224:227], v157 offset:10256
	v_mfma_f32_32x32x16_bf16 v[50:65], v[134:137], v[142:145], v[50:65]
	ds_read_b128 v[216:219], v155 offset:2064
	v_mfma_f32_32x32x16_bf16 v[66:81], v[130:133], v[146:149], v[66:81]
	ds_read_b128 v[228:231], v159 offset:8208
	v_mfma_f32_32x32x16_bf16 v[82:97], v[130:133], v[150:153], v[82:97]
	ds_read_b128 v[232:235], v159 offset:10256
	v_mfma_f32_32x32x16_bf16 v[98:113], v[134:137], v[146:149], v[98:113]
	v_mfma_f32_32x32x16_bf16 v[114:129], v[134:137], v[150:153], v[114:129]
	s_waitcnt lgkmcnt(4)
	v_mfma_f32_32x32x16_bf16 v[2:17], v[212:215], v[220:223], v[2:17]
	ds_read_b128 v[130:133], v154 offset:24592
	s_waitcnt lgkmcnt(4)
	v_mfma_f32_32x32x16_bf16 v[18:33], v[212:215], v[224:227], v[18:33]
	ds_read_b128 v[138:141], v156 offset:32784
	s_waitcnt lgkmcnt(4)
	v_mfma_f32_32x32x16_bf16 v[34:49], v[216:219], v[220:223], v[34:49]
	ds_read_b128 v[142:145], v156 offset:34832
	s_waitcnt lgkmcnt(5)
	v_mfma_f32_32x32x16_bf16 v[50:65], v[216:219], v[224:227], v[50:65]
	ds_read_b128 v[134:137], v154 offset:26640
	s_waitcnt lgkmcnt(5)
	v_mfma_f32_32x32x16_bf16 v[66:81], v[212:215], v[228:231], v[66:81]
	ds_read_b128 v[146:149], v158 offset:32784
	s_waitcnt lgkmcnt(5)
	v_mfma_f32_32x32x16_bf16 v[82:97], v[212:215], v[232:235], v[82:97]
	ds_read_b128 v[150:153], v158 offset:34832
	s_waitcnt lgkmcnt(7)
	v_mfma_f32_32x32x16_bf16 v[98:113], v[216:219], v[228:231], v[98:113]
	s_waitcnt lgkmcnt(6)
	v_mfma_f32_32x32x16_bf16 v[114:129], v[216:219], v[232:235], v[114:129]
	s_waitcnt lgkmcnt(0)
	v_mfma_f32_32x32x16_bf16 v[2:17], v[130:133], v[138:141], v[2:17]
	ds_read_b128 v[212:215], v155 offset:24592
	v_mfma_f32_32x32x16_bf16 v[18:33], v[130:133], v[142:145], v[18:33]
	ds_read_b128 v[220:223], v157 offset:32784
	v_mfma_f32_32x32x16_bf16 v[34:49], v[134:137], v[138:141], v[34:49]
	ds_read_b128 v[224:227], v157 offset:34832
	v_mfma_f32_32x32x16_bf16 v[50:65], v[134:137], v[142:145], v[50:65]
	ds_read_b128 v[216:219], v155 offset:26640
	v_mfma_f32_32x32x16_bf16 v[66:81], v[130:133], v[146:149], v[66:81]
	ds_read_b128 v[228:231], v159 offset:32784
	v_mfma_f32_32x32x16_bf16 v[82:97], v[130:133], v[150:153], v[82:97]
	ds_read_b128 v[232:235], v159 offset:34832
	v_mfma_f32_32x32x16_bf16 v[98:113], v[134:137], v[146:149], v[98:113]
	v_mfma_f32_32x32x16_bf16 v[114:129], v[134:137], v[150:153], v[114:129]
	s_waitcnt lgkmcnt(4)
	v_mfma_f32_32x32x16_bf16 v[2:17], v[212:215], v[220:223], v[2:17]
	s_waitcnt lgkmcnt(3)
	v_mfma_f32_32x32x16_bf16 v[18:33], v[212:215], v[224:227], v[18:33]
	s_waitcnt lgkmcnt(2)
	v_mfma_f32_32x32x16_bf16 v[34:49], v[216:219], v[220:223], v[34:49]
	s_waitcnt lgkmcnt(2)
	v_mfma_f32_32x32x16_bf16 v[50:65], v[216:219], v[224:227], v[50:65]
	s_waitcnt lgkmcnt(1)
	v_mfma_f32_32x32x16_bf16 v[66:81], v[212:215], v[228:231], v[66:81]
	s_waitcnt lgkmcnt(0)
	v_mfma_f32_32x32x16_bf16 v[82:97], v[212:215], v[232:235], v[82:97]
	s_waitcnt lgkmcnt(1)
	v_mfma_f32_32x32x16_bf16 v[98:113], v[216:219], v[228:231], v[98:113]
	s_waitcnt lgkmcnt(0)
	v_mfma_f32_32x32x16_bf16 v[114:129], v[216:219], v[232:235], v[114:129]
	s_nop 7
	s_nop 7
	s_sub_i32 s2, s6, 0x1000
	s_ashr_i32 s2, s2, 11
	s_add_i32 s2, s2, 1
	s_max_i32 s2, s2, 0
	v_readlane_b32 s17, v246, 28
	s_nop 0
	s_add_i32 s2, s2, s17
	s_mul_i32 s2, s2, 0x9000
	s_lshl_b32 s17, s15, 2
	s_add_u32 s2, s2, s17
	s_add_u32 s60, s8, s2
	s_addc_u32 s61, s9, 0
	s_lshr_b32 s2, s15, 7
	s_mul_i32 s2, s2, 0x18000
	s_lshl_b32 s20, s6, 2
	s_add_u32 s2, s2, s20
	s_add_u32 s10, s44, s2
	s_addc_u32 s11, s45, 0
	s_lshl_b32 s2, s6, 12
	s_add_u32 s2, s2, s17
	s_add_u32 s48, s40, s2
	s_addc_u32 s49, s41, 0
	global_load_dword v175, v166, s[60:61]
	global_load_dword v176, v166, s[60:61] offset:128
	global_load_dword v130, v162, s[48:49]
	global_load_dword v212, v162, s[48:49] offset:128
	global_load_dword v131, v163, s[48:49]
	global_load_dword v213, v163, s[48:49] offset:128
	global_load_dword v132, v164, s[48:49]
	global_load_dword v214, v164, s[48:49] offset:128
	global_load_dword v133, v165, s[48:49]
	global_load_dword v215, v165, s[48:49] offset:128
	s_add_u32 s48, s48, 0x8000
	s_addc_u32 s49, s49, 0
	global_load_dword v134, v162, s[48:49]
	global_load_dword v216, v162, s[48:49] offset:128
	global_load_dword v135, v163, s[48:49]
	global_load_dword v217, v163, s[48:49] offset:128
	global_load_dword v136, v164, s[48:49]
	global_load_dword v218, v164, s[48:49] offset:128
	global_load_dword v137, v165, s[48:49]
	global_load_dword v219, v165, s[48:49] offset:128
	s_add_u32 s48, s48, 0x8000
	s_addc_u32 s49, s49, 0
	global_load_dword v138, v162, s[48:49]
	global_load_dword v220, v162, s[48:49] offset:128
	global_load_dword v139, v163, s[48:49]
	global_load_dword v221, v163, s[48:49] offset:128
	global_load_dword v140, v164, s[48:49]
	global_load_dword v222, v164, s[48:49] offset:128
	global_load_dword v141, v165, s[48:49]
	global_load_dword v223, v165, s[48:49] offset:128
	s_add_u32 s48, s48, 0x8000
	s_addc_u32 s49, s49, 0
	global_load_dword v142, v162, s[48:49]
	global_load_dword v224, v162, s[48:49] offset:128
	global_load_dword v143, v163, s[48:49]
	global_load_dword v225, v163, s[48:49] offset:128
	global_load_dword v144, v164, s[48:49]
	global_load_dword v226, v164, s[48:49] offset:128
	global_load_dword v145, v165, s[48:49]
	global_load_dword v227, v165, s[48:49] offset:128
	s_sub_u32 s48, s48, 0x18000
	s_subb_u32 s49, s49, 0
	s_waitcnt vmcnt(32)
	s_waitcnt vmcnt(30)
	v_fmac_f32_e32 v130, v2, v175
	v_fmac_f32_e32 v212, v18, v176
	global_store_dword v162, v130, s[48:49]
	global_store_dword v162, v212, s[48:49] offset:128
	s_waitcnt vmcnt(30)
	v_fmac_f32_e32 v131, v3, v175
	v_fmac_f32_e32 v213, v19, v176
	global_store_dword v163, v131, s[48:49]
	global_store_dword v163, v213, s[48:49] offset:128
	s_waitcnt vmcnt(30)
	v_fmac_f32_e32 v132, v4, v175
	v_fmac_f32_e32 v214, v20, v176
	global_store_dword v164, v132, s[48:49]
	global_store_dword v164, v214, s[48:49] offset:128
	s_waitcnt vmcnt(30)
	v_fmac_f32_e32 v133, v5, v175
	v_fmac_f32_e32 v215, v21, v176
	global_store_dword v165, v133, s[48:49]
	global_store_dword v165, v215, s[48:49] offset:128
	s_add_u32 s48, s48, 0x8000
	s_addc_u32 s49, s49, 0
	s_waitcnt vmcnt(30)
	v_fmac_f32_e32 v134, v6, v175
	v_fmac_f32_e32 v216, v22, v176
	global_store_dword v162, v134, s[48:49]
	global_store_dword v162, v216, s[48:49] offset:128
	s_waitcnt vmcnt(30)
	v_fmac_f32_e32 v135, v7, v175
	v_fmac_f32_e32 v217, v23, v176
	global_store_dword v163, v135, s[48:49]
	global_store_dword v163, v217, s[48:49] offset:128
	s_waitcnt vmcnt(30)
	v_fmac_f32_e32 v136, v8, v175
	v_fmac_f32_e32 v218, v24, v176
	global_store_dword v164, v136, s[48:49]
	global_store_dword v164, v218, s[48:49] offset:128
	s_waitcnt vmcnt(30)
	v_fmac_f32_e32 v137, v9, v175
	v_fmac_f32_e32 v219, v25, v176
	global_store_dword v165, v137, s[48:49]
	global_store_dword v165, v219, s[48:49] offset:128
	s_add_u32 s48, s48, 0x8000
	s_addc_u32 s49, s49, 0
	s_waitcnt vmcnt(30)
	v_fmac_f32_e32 v138, v10, v175
	v_fmac_f32_e32 v220, v26, v176
	global_store_dword v162, v138, s[48:49]
	global_store_dword v162, v220, s[48:49] offset:128
	s_waitcnt vmcnt(30)
	v_fmac_f32_e32 v139, v11, v175
	v_fmac_f32_e32 v221, v27, v176
	global_store_dword v163, v139, s[48:49]
	global_store_dword v163, v221, s[48:49] offset:128
	s_waitcnt vmcnt(30)
	v_fmac_f32_e32 v140, v12, v175
	v_fmac_f32_e32 v222, v28, v176
	global_store_dword v164, v140, s[48:49]
	global_store_dword v164, v222, s[48:49] offset:128
	s_waitcnt vmcnt(30)
	v_fmac_f32_e32 v141, v13, v175
	v_fmac_f32_e32 v223, v29, v176
	global_store_dword v165, v141, s[48:49]
	global_store_dword v165, v223, s[48:49] offset:128
	s_add_u32 s48, s48, 0x8000
	s_addc_u32 s49, s49, 0
	s_waitcnt vmcnt(30)
	v_fmac_f32_e32 v142, v14, v175
	v_fmac_f32_e32 v224, v30, v176
	global_store_dword v162, v142, s[48:49]
	global_store_dword v162, v224, s[48:49] offset:128
	s_waitcnt vmcnt(30)
	v_fmac_f32_e32 v143, v15, v175
	v_fmac_f32_e32 v225, v31, v176
	global_store_dword v163, v143, s[48:49]
	global_store_dword v163, v225, s[48:49] offset:128
	s_waitcnt vmcnt(30)
	v_fmac_f32_e32 v144, v16, v175
	v_fmac_f32_e32 v226, v32, v176
	global_store_dword v164, v144, s[48:49]
	global_store_dword v164, v226, s[48:49] offset:128
	s_waitcnt vmcnt(30)
	v_fmac_f32_e32 v145, v17, v175
	v_fmac_f32_e32 v227, v33, v176
	global_store_dword v165, v145, s[48:49]
	global_store_dword v165, v227, s[48:49] offset:128
	s_sub_u32 s48, s48, 0x18000
	s_subb_u32 s49, s49, 0
	v_mul_f32_e32 v130, v130, v130
	v_fmac_f32_e32 v130, v212, v212
	v_mul_f32_e32 v131, v131, v131
	v_fmac_f32_e32 v131, v213, v213
	v_mul_f32_e32 v132, v132, v132
	v_fmac_f32_e32 v132, v214, v214
	v_mul_f32_e32 v133, v133, v133
	v_fmac_f32_e32 v133, v215, v215
	v_mul_f32_e32 v134, v134, v134
	v_fmac_f32_e32 v134, v216, v216
	v_mul_f32_e32 v135, v135, v135
	v_fmac_f32_e32 v135, v217, v217
	v_mul_f32_e32 v136, v136, v136
	v_fmac_f32_e32 v136, v218, v218
	v_mul_f32_e32 v137, v137, v137
	v_fmac_f32_e32 v137, v219, v219
	v_mul_f32_e32 v138, v138, v138
	v_fmac_f32_e32 v138, v220, v220
	v_mul_f32_e32 v139, v139, v139
	v_fmac_f32_e32 v139, v221, v221
	v_mul_f32_e32 v140, v140, v140
	v_fmac_f32_e32 v140, v222, v222
	v_mul_f32_e32 v141, v141, v141
	v_fmac_f32_e32 v141, v223, v223
	v_mul_f32_e32 v142, v142, v142
	v_fmac_f32_e32 v142, v224, v224
	v_mul_f32_e32 v143, v143, v143
	v_fmac_f32_e32 v143, v225, v225
	v_mul_f32_e32 v144, v144, v144
	v_fmac_f32_e32 v144, v226, v226
	v_mul_f32_e32 v145, v145, v145
	v_fmac_f32_e32 v145, v227, v227
	s_waitcnt lgkmcnt(0)
	ds_bpermute_b32 v212, v168, v130
	ds_bpermute_b32 v213, v168, v131
	ds_bpermute_b32 v214, v168, v132
	ds_bpermute_b32 v215, v168, v133
	ds_bpermute_b32 v216, v168, v134
	ds_bpermute_b32 v217, v168, v135
	ds_bpermute_b32 v218, v168, v136
	ds_bpermute_b32 v219, v168, v137
	s_waitcnt lgkmcnt(7)
	v_add_f32_e32 v130, v130, v212
	s_waitcnt lgkmcnt(6)
	v_add_f32_e32 v131, v131, v213
	s_waitcnt lgkmcnt(5)
	v_add_f32_e32 v132, v132, v214
	s_waitcnt lgkmcnt(4)
	v_add_f32_e32 v133, v133, v215
	s_waitcnt lgkmcnt(3)
	v_add_f32_e32 v134, v134, v216
	s_waitcnt lgkmcnt(2)
	v_add_f32_e32 v135, v135, v217
	s_waitcnt lgkmcnt(1)
	v_add_f32_e32 v136, v136, v218
	s_waitcnt lgkmcnt(0)
	v_add_f32_e32 v137, v137, v219
	ds_bpermute_b32 v212, v169, v130
	ds_bpermute_b32 v213, v169, v131
	ds_bpermute_b32 v214, v169, v132
	ds_bpermute_b32 v215, v169, v133
	ds_bpermute_b32 v216, v169, v134
	ds_bpermute_b32 v217, v169, v135
	ds_bpermute_b32 v218, v169, v136
	ds_bpermute_b32 v219, v169, v137
	s_waitcnt lgkmcnt(7)
	v_add_f32_e32 v130, v130, v212
	s_waitcnt lgkmcnt(6)
	v_add_f32_e32 v131, v131, v213
	s_waitcnt lgkmcnt(5)
	v_add_f32_e32 v132, v132, v214
	s_waitcnt lgkmcnt(4)
	v_add_f32_e32 v133, v133, v215
	s_waitcnt lgkmcnt(3)
	v_add_f32_e32 v134, v134, v216
	s_waitcnt lgkmcnt(2)
	v_add_f32_e32 v135, v135, v217
	s_waitcnt lgkmcnt(1)
	v_add_f32_e32 v136, v136, v218
	s_waitcnt lgkmcnt(0)
	v_add_f32_e32 v137, v137, v219
	ds_bpermute_b32 v212, v171, v130
	ds_bpermute_b32 v213, v171, v131
	ds_bpermute_b32 v214, v171, v132
	ds_bpermute_b32 v215, v171, v133
	ds_bpermute_b32 v216, v171, v134
	ds_bpermute_b32 v217, v171, v135
	ds_bpermute_b32 v218, v171, v136
	ds_bpermute_b32 v219, v171, v137
	s_waitcnt lgkmcnt(7)
	v_add_f32_e32 v130, v130, v212
	s_waitcnt lgkmcnt(6)
	v_add_f32_e32 v131, v131, v213
	s_waitcnt lgkmcnt(5)
	v_add_f32_e32 v132, v132, v214
	s_waitcnt lgkmcnt(4)
	v_add_f32_e32 v133, v133, v215
	s_waitcnt lgkmcnt(3)
	v_add_f32_e32 v134, v134, v216
	s_waitcnt lgkmcnt(2)
	v_add_f32_e32 v135, v135, v217
	s_waitcnt lgkmcnt(1)
	v_add_f32_e32 v136, v136, v218
	s_waitcnt lgkmcnt(0)
	v_add_f32_e32 v137, v137, v219
	ds_bpermute_b32 v212, v172, v130
	ds_bpermute_b32 v213, v172, v131
	ds_bpermute_b32 v214, v172, v132
	ds_bpermute_b32 v215, v172, v133
	ds_bpermute_b32 v216, v172, v134
	ds_bpermute_b32 v217, v172, v135
	ds_bpermute_b32 v218, v172, v136
	ds_bpermute_b32 v219, v172, v137
	s_waitcnt lgkmcnt(7)
	v_add_f32_e32 v130, v130, v212
	s_waitcnt lgkmcnt(6)
	v_add_f32_e32 v131, v131, v213
	s_waitcnt lgkmcnt(5)
	v_add_f32_e32 v132, v132, v214
	s_waitcnt lgkmcnt(4)
	v_add_f32_e32 v133, v133, v215
	s_waitcnt lgkmcnt(3)
	v_add_f32_e32 v134, v134, v216
	s_waitcnt lgkmcnt(2)
	v_add_f32_e32 v135, v135, v217
	s_waitcnt lgkmcnt(1)
	v_add_f32_e32 v136, v136, v218
	s_waitcnt lgkmcnt(0)
	v_add_f32_e32 v137, v137, v219
	ds_bpermute_b32 v212, v173, v130
	ds_bpermute_b32 v213, v173, v131
	ds_bpermute_b32 v214, v173, v132
	ds_bpermute_b32 v215, v173, v133
	ds_bpermute_b32 v216, v173, v134
	ds_bpermute_b32 v217, v173, v135
	ds_bpermute_b32 v218, v173, v136
	ds_bpermute_b32 v219, v173, v137
	s_waitcnt lgkmcnt(7)
	v_add_f32_e32 v130, v130, v212
	s_waitcnt lgkmcnt(6)
	v_add_f32_e32 v131, v131, v213
	s_waitcnt lgkmcnt(5)
	v_add_f32_e32 v132, v132, v214
	s_waitcnt lgkmcnt(4)
	v_add_f32_e32 v133, v133, v215
	s_waitcnt lgkmcnt(3)
	v_add_f32_e32 v134, v134, v216
	s_waitcnt lgkmcnt(2)
	v_add_f32_e32 v135, v135, v217
	s_waitcnt lgkmcnt(1)
	v_add_f32_e32 v136, v136, v218
	s_waitcnt lgkmcnt(0)
	v_add_f32_e32 v137, v137, v219
	ds_bpermute_b32 v220, v168, v138
	ds_bpermute_b32 v221, v168, v139
	ds_bpermute_b32 v222, v168, v140
	ds_bpermute_b32 v223, v168, v141
	ds_bpermute_b32 v224, v168, v142
	ds_bpermute_b32 v225, v168, v143
	ds_bpermute_b32 v226, v168, v144
	ds_bpermute_b32 v227, v168, v145
	s_waitcnt lgkmcnt(7)
	v_add_f32_e32 v138, v138, v220
	s_waitcnt lgkmcnt(6)
	v_add_f32_e32 v139, v139, v221
	s_waitcnt lgkmcnt(5)
	v_add_f32_e32 v140, v140, v222
	s_waitcnt lgkmcnt(4)
	v_add_f32_e32 v141, v141, v223
	s_waitcnt lgkmcnt(3)
	v_add_f32_e32 v142, v142, v224
	s_waitcnt lgkmcnt(2)
	v_add_f32_e32 v143, v143, v225
	s_waitcnt lgkmcnt(1)
	v_add_f32_e32 v144, v144, v226
	s_waitcnt lgkmcnt(0)
	v_add_f32_e32 v145, v145, v227
	ds_bpermute_b32 v220, v169, v138
	ds_bpermute_b32 v221, v169, v139
	ds_bpermute_b32 v222, v169, v140
	ds_bpermute_b32 v223, v169, v141
	ds_bpermute_b32 v224, v169, v142
	ds_bpermute_b32 v225, v169, v143
	ds_bpermute_b32 v226, v169, v144
	ds_bpermute_b32 v227, v169, v145
	s_waitcnt lgkmcnt(7)
	v_add_f32_e32 v138, v138, v220
	s_waitcnt lgkmcnt(6)
	v_add_f32_e32 v139, v139, v221
	s_waitcnt lgkmcnt(5)
	v_add_f32_e32 v140, v140, v222
	s_waitcnt lgkmcnt(4)
	v_add_f32_e32 v141, v141, v223
	s_waitcnt lgkmcnt(3)
	v_add_f32_e32 v142, v142, v224
	s_waitcnt lgkmcnt(2)
	v_add_f32_e32 v143, v143, v225
	s_waitcnt lgkmcnt(1)
	v_add_f32_e32 v144, v144, v226
	s_waitcnt lgkmcnt(0)
	v_add_f32_e32 v145, v145, v227
	ds_bpermute_b32 v220, v171, v138
	ds_bpermute_b32 v221, v171, v139
	ds_bpermute_b32 v222, v171, v140
	ds_bpermute_b32 v223, v171, v141
	ds_bpermute_b32 v224, v171, v142
	ds_bpermute_b32 v225, v171, v143
	ds_bpermute_b32 v226, v171, v144
	ds_bpermute_b32 v227, v171, v145
	s_waitcnt lgkmcnt(7)
	v_add_f32_e32 v138, v138, v220
	s_waitcnt lgkmcnt(6)
	v_add_f32_e32 v139, v139, v221
	s_waitcnt lgkmcnt(5)
	v_add_f32_e32 v140, v140, v222
	s_waitcnt lgkmcnt(4)
	v_add_f32_e32 v141, v141, v223
	s_waitcnt lgkmcnt(3)
	v_add_f32_e32 v142, v142, v224
	s_waitcnt lgkmcnt(2)
	v_add_f32_e32 v143, v143, v225
	s_waitcnt lgkmcnt(1)
	v_add_f32_e32 v144, v144, v226
	s_waitcnt lgkmcnt(0)
	v_add_f32_e32 v145, v145, v227
	ds_bpermute_b32 v220, v172, v138
	ds_bpermute_b32 v221, v172, v139
	ds_bpermute_b32 v222, v172, v140
	ds_bpermute_b32 v223, v172, v141
	ds_bpermute_b32 v224, v172, v142
	ds_bpermute_b32 v225, v172, v143
	ds_bpermute_b32 v226, v172, v144
	ds_bpermute_b32 v227, v172, v145
	s_waitcnt lgkmcnt(7)
	v_add_f32_e32 v138, v138, v220
	s_waitcnt lgkmcnt(6)
	v_add_f32_e32 v139, v139, v221
	s_waitcnt lgkmcnt(5)
	v_add_f32_e32 v140, v140, v222
	s_waitcnt lgkmcnt(4)
	v_add_f32_e32 v141, v141, v223
	s_waitcnt lgkmcnt(3)
	v_add_f32_e32 v142, v142, v224
	s_waitcnt lgkmcnt(2)
	v_add_f32_e32 v143, v143, v225
	s_waitcnt lgkmcnt(1)
	v_add_f32_e32 v144, v144, v226
	s_waitcnt lgkmcnt(0)
	v_add_f32_e32 v145, v145, v227
	ds_bpermute_b32 v220, v173, v138
	ds_bpermute_b32 v221, v173, v139
	ds_bpermute_b32 v222, v173, v140
	ds_bpermute_b32 v223, v173, v141
	ds_bpermute_b32 v224, v173, v142
	ds_bpermute_b32 v225, v173, v143
	ds_bpermute_b32 v226, v173, v144
	ds_bpermute_b32 v227, v173, v145
	s_waitcnt lgkmcnt(7)
	v_add_f32_e32 v138, v138, v220
	s_waitcnt lgkmcnt(6)
	v_add_f32_e32 v139, v139, v221
	s_waitcnt lgkmcnt(5)
	v_add_f32_e32 v140, v140, v222
	s_waitcnt lgkmcnt(4)
	v_add_f32_e32 v141, v141, v223
	s_waitcnt lgkmcnt(3)
	v_add_f32_e32 v142, v142, v224
	s_waitcnt lgkmcnt(2)
	v_add_f32_e32 v143, v143, v225
	s_waitcnt lgkmcnt(1)
	v_add_f32_e32 v144, v144, v226
	s_waitcnt lgkmcnt(0)
	v_add_f32_e32 v145, v145, v227
	v_cmp_eq_u32_e32 vcc, 0, v174
	s_and_saveexec_b64 s[58:59], vcc
	global_store_dword v167, v130, s[10:11]
	global_store_dword v167, v131, s[10:11] offset:4
	global_store_dword v167, v132, s[10:11] offset:8
	global_store_dword v167, v133, s[10:11] offset:12
	global_store_dword v167, v134, s[10:11] offset:32
	global_store_dword v167, v135, s[10:11] offset:36
	global_store_dword v167, v136, s[10:11] offset:40
	global_store_dword v167, v137, s[10:11] offset:44
	global_store_dword v167, v138, s[10:11] offset:64
	global_store_dword v167, v139, s[10:11] offset:68
	global_store_dword v167, v140, s[10:11] offset:72
	global_store_dword v167, v141, s[10:11] offset:76
	global_store_dword v167, v142, s[10:11] offset:96
	global_store_dword v167, v143, s[10:11] offset:100
	global_store_dword v167, v144, s[10:11] offset:104
	global_store_dword v167, v145, s[10:11] offset:108
	s_mov_b64 exec, -1
	s_add_u32 s48, s48, 0x20000
	s_addc_u32 s49, s49, 0
	global_load_dword v130, v162, s[48:49]
	global_load_dword v212, v162, s[48:49] offset:128
	global_load_dword v131, v163, s[48:49]
	global_load_dword v213, v163, s[48:49] offset:128
	global_load_dword v132, v164, s[48:49]
	global_load_dword v214, v164, s[48:49] offset:128
	global_load_dword v133, v165, s[48:49]
	global_load_dword v215, v165, s[48:49] offset:128
	s_add_u32 s48, s48, 0x8000
	s_addc_u32 s49, s49, 0
	global_load_dword v134, v162, s[48:49]
	global_load_dword v216, v162, s[48:49] offset:128
	global_load_dword v135, v163, s[48:49]
	global_load_dword v217, v163, s[48:49] offset:128
	global_load_dword v136, v164, s[48:49]
	global_load_dword v218, v164, s[48:49] offset:128
	global_load_dword v137, v165, s[48:49]
	global_load_dword v219, v165, s[48:49] offset:128
	s_add_u32 s48, s48, 0x8000
	s_addc_u32 s49, s49, 0
	global_load_dword v138, v162, s[48:49]
	global_load_dword v220, v162, s[48:49] offset:128
	global_load_dword v139, v163, s[48:49]
	global_load_dword v221, v163, s[48:49] offset:128
	global_load_dword v140, v164, s[48:49]
	global_load_dword v222, v164, s[48:49] offset:128
	global_load_dword v141, v165, s[48:49]
	global_load_dword v223, v165, s[48:49] offset:128
	s_add_u32 s48, s48, 0x8000
	s_addc_u32 s49, s49, 0
	global_load_dword v142, v162, s[48:49]
	global_load_dword v224, v162, s[48:49] offset:128
	global_load_dword v143, v163, s[48:49]
	global_load_dword v225, v163, s[48:49] offset:128
	global_load_dword v144, v164, s[48:49]
	global_load_dword v226, v164, s[48:49] offset:128
	global_load_dword v145, v165, s[48:49]
	global_load_dword v227, v165, s[48:49] offset:128
	s_sub_u32 s48, s48, 0x18000
	s_subb_u32 s49, s49, 0
	s_waitcnt vmcnt(30)
	v_fmac_f32_e32 v130, v34, v175
	v_fmac_f32_e32 v212, v50, v176
	global_store_dword v162, v130, s[48:49]
	global_store_dword v162, v212, s[48:49] offset:128
	s_waitcnt vmcnt(30)
	v_fmac_f32_e32 v131, v35, v175
	v_fmac_f32_e32 v213, v51, v176
	global_store_dword v163, v131, s[48:49]
	global_store_dword v163, v213, s[48:49] offset:128
	s_waitcnt vmcnt(30)
	v_fmac_f32_e32 v132, v36, v175
	v_fmac_f32_e32 v214, v52, v176
	global_store_dword v164, v132, s[48:49]
	global_store_dword v164, v214, s[48:49] offset:128
	s_waitcnt vmcnt(30)
	v_fmac_f32_e32 v133, v37, v175
	v_fmac_f32_e32 v215, v53, v176
	global_store_dword v165, v133, s[48:49]
	global_store_dword v165, v215, s[48:49] offset:128
	s_add_u32 s48, s48, 0x8000
	s_addc_u32 s49, s49, 0
	s_waitcnt vmcnt(30)
	v_fmac_f32_e32 v134, v38, v175
	v_fmac_f32_e32 v216, v54, v176
	global_store_dword v162, v134, s[48:49]
	global_store_dword v162, v216, s[48:49] offset:128
	s_waitcnt vmcnt(30)
	v_fmac_f32_e32 v135, v39, v175
	v_fmac_f32_e32 v217, v55, v176
	global_store_dword v163, v135, s[48:49]
	global_store_dword v163, v217, s[48:49] offset:128
	s_waitcnt vmcnt(30)
	v_fmac_f32_e32 v136, v40, v175
	v_fmac_f32_e32 v218, v56, v176
	global_store_dword v164, v136, s[48:49]
	global_store_dword v164, v218, s[48:49] offset:128
	s_waitcnt vmcnt(30)
	v_fmac_f32_e32 v137, v41, v175
	v_fmac_f32_e32 v219, v57, v176
	global_store_dword v165, v137, s[48:49]
	global_store_dword v165, v219, s[48:49] offset:128
	s_add_u32 s48, s48, 0x8000
	s_addc_u32 s49, s49, 0
	s_waitcnt vmcnt(30)
	v_fmac_f32_e32 v138, v42, v175
	v_fmac_f32_e32 v220, v58, v176
	global_store_dword v162, v138, s[48:49]
	global_store_dword v162, v220, s[48:49] offset:128
	s_waitcnt vmcnt(30)
	v_fmac_f32_e32 v139, v43, v175
	v_fmac_f32_e32 v221, v59, v176
	global_store_dword v163, v139, s[48:49]
	global_store_dword v163, v221, s[48:49] offset:128
	s_waitcnt vmcnt(30)
	v_fmac_f32_e32 v140, v44, v175
	v_fmac_f32_e32 v222, v60, v176
	global_store_dword v164, v140, s[48:49]
	global_store_dword v164, v222, s[48:49] offset:128
	s_waitcnt vmcnt(30)
	v_fmac_f32_e32 v141, v45, v175
	v_fmac_f32_e32 v223, v61, v176
	global_store_dword v165, v141, s[48:49]
	global_store_dword v165, v223, s[48:49] offset:128
	s_add_u32 s48, s48, 0x8000
	s_addc_u32 s49, s49, 0
	s_waitcnt vmcnt(30)
	v_fmac_f32_e32 v142, v46, v175
	v_fmac_f32_e32 v224, v62, v176
	global_store_dword v162, v142, s[48:49]
	global_store_dword v162, v224, s[48:49] offset:128
	s_waitcnt vmcnt(30)
	v_fmac_f32_e32 v143, v47, v175
	v_fmac_f32_e32 v225, v63, v176
	global_store_dword v163, v143, s[48:49]
	global_store_dword v163, v225, s[48:49] offset:128
	s_waitcnt vmcnt(30)
	v_fmac_f32_e32 v144, v48, v175
	v_fmac_f32_e32 v226, v64, v176
	global_store_dword v164, v144, s[48:49]
	global_store_dword v164, v226, s[48:49] offset:128
	s_waitcnt vmcnt(30)
	v_fmac_f32_e32 v145, v49, v175
	v_fmac_f32_e32 v227, v65, v176
	global_store_dword v165, v145, s[48:49]
	global_store_dword v165, v227, s[48:49] offset:128
	s_sub_u32 s48, s48, 0x18000
	s_subb_u32 s49, s49, 0
	v_mul_f32_e32 v130, v130, v130
	v_fmac_f32_e32 v130, v212, v212
	v_mul_f32_e32 v131, v131, v131
	v_fmac_f32_e32 v131, v213, v213
	v_mul_f32_e32 v132, v132, v132
	v_fmac_f32_e32 v132, v214, v214
	v_mul_f32_e32 v133, v133, v133
	v_fmac_f32_e32 v133, v215, v215
	v_mul_f32_e32 v134, v134, v134
	v_fmac_f32_e32 v134, v216, v216
	v_mul_f32_e32 v135, v135, v135
	v_fmac_f32_e32 v135, v217, v217
	v_mul_f32_e32 v136, v136, v136
	v_fmac_f32_e32 v136, v218, v218
	v_mul_f32_e32 v137, v137, v137
	v_fmac_f32_e32 v137, v219, v219
	v_mul_f32_e32 v138, v138, v138
	v_fmac_f32_e32 v138, v220, v220
	v_mul_f32_e32 v139, v139, v139
	v_fmac_f32_e32 v139, v221, v221
	v_mul_f32_e32 v140, v140, v140
	v_fmac_f32_e32 v140, v222, v222
	v_mul_f32_e32 v141, v141, v141
	v_fmac_f32_e32 v141, v223, v223
	v_mul_f32_e32 v142, v142, v142
	v_fmac_f32_e32 v142, v224, v224
	v_mul_f32_e32 v143, v143, v143
	v_fmac_f32_e32 v143, v225, v225
	v_mul_f32_e32 v144, v144, v144
	v_fmac_f32_e32 v144, v226, v226
	v_mul_f32_e32 v145, v145, v145
	v_fmac_f32_e32 v145, v227, v227
	s_waitcnt lgkmcnt(0)
	ds_bpermute_b32 v212, v168, v130
	ds_bpermute_b32 v213, v168, v131
	ds_bpermute_b32 v214, v168, v132
	ds_bpermute_b32 v215, v168, v133
	ds_bpermute_b32 v216, v168, v134
	ds_bpermute_b32 v217, v168, v135
	ds_bpermute_b32 v218, v168, v136
	ds_bpermute_b32 v219, v168, v137
	s_waitcnt lgkmcnt(7)
	v_add_f32_e32 v130, v130, v212
	s_waitcnt lgkmcnt(6)
	v_add_f32_e32 v131, v131, v213
	s_waitcnt lgkmcnt(5)
	v_add_f32_e32 v132, v132, v214
	s_waitcnt lgkmcnt(4)
	v_add_f32_e32 v133, v133, v215
	s_waitcnt lgkmcnt(3)
	v_add_f32_e32 v134, v134, v216
	s_waitcnt lgkmcnt(2)
	v_add_f32_e32 v135, v135, v217
	s_waitcnt lgkmcnt(1)
	v_add_f32_e32 v136, v136, v218
	s_waitcnt lgkmcnt(0)
	v_add_f32_e32 v137, v137, v219
	ds_bpermute_b32 v212, v169, v130
	ds_bpermute_b32 v213, v169, v131
	ds_bpermute_b32 v214, v169, v132
	ds_bpermute_b32 v215, v169, v133
	ds_bpermute_b32 v216, v169, v134
	ds_bpermute_b32 v217, v169, v135
	ds_bpermute_b32 v218, v169, v136
	ds_bpermute_b32 v219, v169, v137
	s_waitcnt lgkmcnt(7)
	v_add_f32_e32 v130, v130, v212
	s_waitcnt lgkmcnt(6)
	v_add_f32_e32 v131, v131, v213
	s_waitcnt lgkmcnt(5)
	v_add_f32_e32 v132, v132, v214
	s_waitcnt lgkmcnt(4)
	v_add_f32_e32 v133, v133, v215
	s_waitcnt lgkmcnt(3)
	v_add_f32_e32 v134, v134, v216
	s_waitcnt lgkmcnt(2)
	v_add_f32_e32 v135, v135, v217
	s_waitcnt lgkmcnt(1)
	v_add_f32_e32 v136, v136, v218
	s_waitcnt lgkmcnt(0)
	v_add_f32_e32 v137, v137, v219
	ds_bpermute_b32 v212, v171, v130
	ds_bpermute_b32 v213, v171, v131
	ds_bpermute_b32 v214, v171, v132
	ds_bpermute_b32 v215, v171, v133
	ds_bpermute_b32 v216, v171, v134
	ds_bpermute_b32 v217, v171, v135
	ds_bpermute_b32 v218, v171, v136
	ds_bpermute_b32 v219, v171, v137
	s_waitcnt lgkmcnt(7)
	v_add_f32_e32 v130, v130, v212
	s_waitcnt lgkmcnt(6)
	v_add_f32_e32 v131, v131, v213
	s_waitcnt lgkmcnt(5)
	v_add_f32_e32 v132, v132, v214
	s_waitcnt lgkmcnt(4)
	v_add_f32_e32 v133, v133, v215
	s_waitcnt lgkmcnt(3)
	v_add_f32_e32 v134, v134, v216
	s_waitcnt lgkmcnt(2)
	v_add_f32_e32 v135, v135, v217
	s_waitcnt lgkmcnt(1)
	v_add_f32_e32 v136, v136, v218
	s_waitcnt lgkmcnt(0)
	v_add_f32_e32 v137, v137, v219
	ds_bpermute_b32 v212, v172, v130
	ds_bpermute_b32 v213, v172, v131
	ds_bpermute_b32 v214, v172, v132
	ds_bpermute_b32 v215, v172, v133
	ds_bpermute_b32 v216, v172, v134
	ds_bpermute_b32 v217, v172, v135
	ds_bpermute_b32 v218, v172, v136
	ds_bpermute_b32 v219, v172, v137
	s_waitcnt lgkmcnt(7)
	v_add_f32_e32 v130, v130, v212
	s_waitcnt lgkmcnt(6)
	v_add_f32_e32 v131, v131, v213
	s_waitcnt lgkmcnt(5)
	v_add_f32_e32 v132, v132, v214
	s_waitcnt lgkmcnt(4)
	v_add_f32_e32 v133, v133, v215
	s_waitcnt lgkmcnt(3)
	v_add_f32_e32 v134, v134, v216
	s_waitcnt lgkmcnt(2)
	v_add_f32_e32 v135, v135, v217
	s_waitcnt lgkmcnt(1)
	v_add_f32_e32 v136, v136, v218
	s_waitcnt lgkmcnt(0)
	v_add_f32_e32 v137, v137, v219
	ds_bpermute_b32 v212, v173, v130
	ds_bpermute_b32 v213, v173, v131
	ds_bpermute_b32 v214, v173, v132
	ds_bpermute_b32 v215, v173, v133
	ds_bpermute_b32 v216, v173, v134
	ds_bpermute_b32 v217, v173, v135
	ds_bpermute_b32 v218, v173, v136
	ds_bpermute_b32 v219, v173, v137
	s_waitcnt lgkmcnt(7)
	v_add_f32_e32 v130, v130, v212
	s_waitcnt lgkmcnt(6)
	v_add_f32_e32 v131, v131, v213
	s_waitcnt lgkmcnt(5)
	v_add_f32_e32 v132, v132, v214
	s_waitcnt lgkmcnt(4)
	v_add_f32_e32 v133, v133, v215
	s_waitcnt lgkmcnt(3)
	v_add_f32_e32 v134, v134, v216
	s_waitcnt lgkmcnt(2)
	v_add_f32_e32 v135, v135, v217
	s_waitcnt lgkmcnt(1)
	v_add_f32_e32 v136, v136, v218
	s_waitcnt lgkmcnt(0)
	v_add_f32_e32 v137, v137, v219
	ds_bpermute_b32 v220, v168, v138
	ds_bpermute_b32 v221, v168, v139
	ds_bpermute_b32 v222, v168, v140
	ds_bpermute_b32 v223, v168, v141
	ds_bpermute_b32 v224, v168, v142
	ds_bpermute_b32 v225, v168, v143
	ds_bpermute_b32 v226, v168, v144
	ds_bpermute_b32 v227, v168, v145
	s_waitcnt lgkmcnt(7)
	v_add_f32_e32 v138, v138, v220
	s_waitcnt lgkmcnt(6)
	v_add_f32_e32 v139, v139, v221
	s_waitcnt lgkmcnt(5)
	v_add_f32_e32 v140, v140, v222
	s_waitcnt lgkmcnt(4)
	v_add_f32_e32 v141, v141, v223
	s_waitcnt lgkmcnt(3)
	v_add_f32_e32 v142, v142, v224
	s_waitcnt lgkmcnt(2)
	v_add_f32_e32 v143, v143, v225
	s_waitcnt lgkmcnt(1)
	v_add_f32_e32 v144, v144, v226
	s_waitcnt lgkmcnt(0)
	v_add_f32_e32 v145, v145, v227
	ds_bpermute_b32 v220, v169, v138
	ds_bpermute_b32 v221, v169, v139
	ds_bpermute_b32 v222, v169, v140
	ds_bpermute_b32 v223, v169, v141
	ds_bpermute_b32 v224, v169, v142
	ds_bpermute_b32 v225, v169, v143
	ds_bpermute_b32 v226, v169, v144
	ds_bpermute_b32 v227, v169, v145
	s_waitcnt lgkmcnt(7)
	v_add_f32_e32 v138, v138, v220
	s_waitcnt lgkmcnt(6)
	v_add_f32_e32 v139, v139, v221
	s_waitcnt lgkmcnt(5)
	v_add_f32_e32 v140, v140, v222
	s_waitcnt lgkmcnt(4)
	v_add_f32_e32 v141, v141, v223
	s_waitcnt lgkmcnt(3)
	v_add_f32_e32 v142, v142, v224
	s_waitcnt lgkmcnt(2)
	v_add_f32_e32 v143, v143, v225
	s_waitcnt lgkmcnt(1)
	v_add_f32_e32 v144, v144, v226
	s_waitcnt lgkmcnt(0)
	v_add_f32_e32 v145, v145, v227
	ds_bpermute_b32 v220, v171, v138
	ds_bpermute_b32 v221, v171, v139
	ds_bpermute_b32 v222, v171, v140
	ds_bpermute_b32 v223, v171, v141
	ds_bpermute_b32 v224, v171, v142
	ds_bpermute_b32 v225, v171, v143
	ds_bpermute_b32 v226, v171, v144
	ds_bpermute_b32 v227, v171, v145
	s_waitcnt lgkmcnt(7)
	v_add_f32_e32 v138, v138, v220
	s_waitcnt lgkmcnt(6)
	v_add_f32_e32 v139, v139, v221
	s_waitcnt lgkmcnt(5)
	v_add_f32_e32 v140, v140, v222
	s_waitcnt lgkmcnt(4)
	v_add_f32_e32 v141, v141, v223
	s_waitcnt lgkmcnt(3)
	v_add_f32_e32 v142, v142, v224
	s_waitcnt lgkmcnt(2)
	v_add_f32_e32 v143, v143, v225
	s_waitcnt lgkmcnt(1)
	v_add_f32_e32 v144, v144, v226
	s_waitcnt lgkmcnt(0)
	v_add_f32_e32 v145, v145, v227
	ds_bpermute_b32 v220, v172, v138
	ds_bpermute_b32 v221, v172, v139
	ds_bpermute_b32 v222, v172, v140
	ds_bpermute_b32 v223, v172, v141
	ds_bpermute_b32 v224, v172, v142
	ds_bpermute_b32 v225, v172, v143
	ds_bpermute_b32 v226, v172, v144
	ds_bpermute_b32 v227, v172, v145
	s_waitcnt lgkmcnt(7)
	v_add_f32_e32 v138, v138, v220
	s_waitcnt lgkmcnt(6)
	v_add_f32_e32 v139, v139, v221
	s_waitcnt lgkmcnt(5)
	v_add_f32_e32 v140, v140, v222
	s_waitcnt lgkmcnt(4)
	v_add_f32_e32 v141, v141, v223
	s_waitcnt lgkmcnt(3)
	v_add_f32_e32 v142, v142, v224
	s_waitcnt lgkmcnt(2)
	v_add_f32_e32 v143, v143, v225
	s_waitcnt lgkmcnt(1)
	v_add_f32_e32 v144, v144, v226
	s_waitcnt lgkmcnt(0)
	v_add_f32_e32 v145, v145, v227
	ds_bpermute_b32 v220, v173, v138
	ds_bpermute_b32 v221, v173, v139
	ds_bpermute_b32 v222, v173, v140
	ds_bpermute_b32 v223, v173, v141
	ds_bpermute_b32 v224, v173, v142
	ds_bpermute_b32 v225, v173, v143
	ds_bpermute_b32 v226, v173, v144
	ds_bpermute_b32 v227, v173, v145
	s_waitcnt lgkmcnt(7)
	v_add_f32_e32 v138, v138, v220
	s_waitcnt lgkmcnt(6)
	v_add_f32_e32 v139, v139, v221
	s_waitcnt lgkmcnt(5)
	v_add_f32_e32 v140, v140, v222
	s_waitcnt lgkmcnt(4)
	v_add_f32_e32 v141, v141, v223
	s_waitcnt lgkmcnt(3)
	v_add_f32_e32 v142, v142, v224
	s_waitcnt lgkmcnt(2)
	v_add_f32_e32 v143, v143, v225
	s_waitcnt lgkmcnt(1)
	v_add_f32_e32 v144, v144, v226
	s_waitcnt lgkmcnt(0)
	v_add_f32_e32 v145, v145, v227
	v_cmp_eq_u32_e32 vcc, 0, v174
	s_and_saveexec_b64 s[58:59], vcc
	global_store_dword v167, v130, s[10:11] offset:128
	global_store_dword v167, v131, s[10:11] offset:132
	global_store_dword v167, v132, s[10:11] offset:136
	global_store_dword v167, v133, s[10:11] offset:140
	global_store_dword v167, v134, s[10:11] offset:160
	global_store_dword v167, v135, s[10:11] offset:164
	global_store_dword v167, v136, s[10:11] offset:168
	global_store_dword v167, v137, s[10:11] offset:172
	global_store_dword v167, v138, s[10:11] offset:192
	global_store_dword v167, v139, s[10:11] offset:196
	global_store_dword v167, v140, s[10:11] offset:200
	global_store_dword v167, v141, s[10:11] offset:204
	global_store_dword v167, v142, s[10:11] offset:224
	global_store_dword v167, v143, s[10:11] offset:228
	global_store_dword v167, v144, s[10:11] offset:232
	global_store_dword v167, v145, s[10:11] offset:236
	s_mov_b64 exec, -1
	s_sub_u32 s48, s48, 0x20000
	s_subb_u32 s49, s49, 0
	s_add_u32 s60, s60, 0x200
	s_addc_u32 s61, s61, 0
	s_add_u32 s10, s10, 0x18000
	s_addc_u32 s11, s11, 0
	s_add_u32 s48, s48, 0x200
	s_addc_u32 s49, s49, 0
	global_load_dword v175, v166, s[60:61]
	global_load_dword v176, v166, s[60:61] offset:128
	global_load_dword v130, v162, s[48:49]
	global_load_dword v212, v162, s[48:49] offset:128
	global_load_dword v131, v163, s[48:49]
	global_load_dword v213, v163, s[48:49] offset:128
	global_load_dword v132, v164, s[48:49]
	global_load_dword v214, v164, s[48:49] offset:128
	global_load_dword v133, v165, s[48:49]
	global_load_dword v215, v165, s[48:49] offset:128
	s_add_u32 s48, s48, 0x8000
	s_addc_u32 s49, s49, 0
	global_load_dword v134, v162, s[48:49]
	global_load_dword v216, v162, s[48:49] offset:128
	global_load_dword v135, v163, s[48:49]
	global_load_dword v217, v163, s[48:49] offset:128
	global_load_dword v136, v164, s[48:49]
	global_load_dword v218, v164, s[48:49] offset:128
	global_load_dword v137, v165, s[48:49]
	global_load_dword v219, v165, s[48:49] offset:128
	s_add_u32 s48, s48, 0x8000
	s_addc_u32 s49, s49, 0
	global_load_dword v138, v162, s[48:49]
	global_load_dword v220, v162, s[48:49] offset:128
	global_load_dword v139, v163, s[48:49]
	global_load_dword v221, v163, s[48:49] offset:128
	global_load_dword v140, v164, s[48:49]
	global_load_dword v222, v164, s[48:49] offset:128
	global_load_dword v141, v165, s[48:49]
	global_load_dword v223, v165, s[48:49] offset:128
	s_add_u32 s48, s48, 0x8000
	s_addc_u32 s49, s49, 0
	global_load_dword v142, v162, s[48:49]
	global_load_dword v224, v162, s[48:49] offset:128
	global_load_dword v143, v163, s[48:49]
	global_load_dword v225, v163, s[48:49] offset:128
	global_load_dword v144, v164, s[48:49]
	global_load_dword v226, v164, s[48:49] offset:128
	global_load_dword v145, v165, s[48:49]
	global_load_dword v227, v165, s[48:49] offset:128
	s_sub_u32 s48, s48, 0x18000
	s_subb_u32 s49, s49, 0
	s_waitcnt vmcnt(32)
	s_waitcnt vmcnt(30)
	v_fmac_f32_e32 v130, v66, v175
	v_fmac_f32_e32 v212, v82, v176
	global_store_dword v162, v130, s[48:49]
	global_store_dword v162, v212, s[48:49] offset:128
	s_waitcnt vmcnt(30)
	v_fmac_f32_e32 v131, v67, v175
	v_fmac_f32_e32 v213, v83, v176
	global_store_dword v163, v131, s[48:49]
	global_store_dword v163, v213, s[48:49] offset:128
	s_waitcnt vmcnt(30)
	v_fmac_f32_e32 v132, v68, v175
	v_fmac_f32_e32 v214, v84, v176
	global_store_dword v164, v132, s[48:49]
	global_store_dword v164, v214, s[48:49] offset:128
	s_waitcnt vmcnt(30)
	v_fmac_f32_e32 v133, v69, v175
	v_fmac_f32_e32 v215, v85, v176
	global_store_dword v165, v133, s[48:49]
	global_store_dword v165, v215, s[48:49] offset:128
	s_add_u32 s48, s48, 0x8000
	s_addc_u32 s49, s49, 0
	s_waitcnt vmcnt(30)
	v_fmac_f32_e32 v134, v70, v175
	v_fmac_f32_e32 v216, v86, v176
	global_store_dword v162, v134, s[48:49]
	global_store_dword v162, v216, s[48:49] offset:128
	s_waitcnt vmcnt(30)
	v_fmac_f32_e32 v135, v71, v175
	v_fmac_f32_e32 v217, v87, v176
	global_store_dword v163, v135, s[48:49]
	global_store_dword v163, v217, s[48:49] offset:128
	s_waitcnt vmcnt(30)
	v_fmac_f32_e32 v136, v72, v175
	v_fmac_f32_e32 v218, v88, v176
	global_store_dword v164, v136, s[48:49]
	global_store_dword v164, v218, s[48:49] offset:128
	s_waitcnt vmcnt(30)
	v_fmac_f32_e32 v137, v73, v175
	v_fmac_f32_e32 v219, v89, v176
	global_store_dword v165, v137, s[48:49]
	global_store_dword v165, v219, s[48:49] offset:128
	s_add_u32 s48, s48, 0x8000
	s_addc_u32 s49, s49, 0
	s_waitcnt vmcnt(30)
	v_fmac_f32_e32 v138, v74, v175
	v_fmac_f32_e32 v220, v90, v176
	global_store_dword v162, v138, s[48:49]
	global_store_dword v162, v220, s[48:49] offset:128
	s_waitcnt vmcnt(30)
	v_fmac_f32_e32 v139, v75, v175
	v_fmac_f32_e32 v221, v91, v176
	global_store_dword v163, v139, s[48:49]
	global_store_dword v163, v221, s[48:49] offset:128
	s_waitcnt vmcnt(30)
	v_fmac_f32_e32 v140, v76, v175
	v_fmac_f32_e32 v222, v92, v176
	global_store_dword v164, v140, s[48:49]
	global_store_dword v164, v222, s[48:49] offset:128
	s_waitcnt vmcnt(30)
	v_fmac_f32_e32 v141, v77, v175
	v_fmac_f32_e32 v223, v93, v176
	global_store_dword v165, v141, s[48:49]
	global_store_dword v165, v223, s[48:49] offset:128
	s_add_u32 s48, s48, 0x8000
	s_addc_u32 s49, s49, 0
	s_waitcnt vmcnt(30)
	v_fmac_f32_e32 v142, v78, v175
	v_fmac_f32_e32 v224, v94, v176
	global_store_dword v162, v142, s[48:49]
	global_store_dword v162, v224, s[48:49] offset:128
	s_waitcnt vmcnt(30)
	v_fmac_f32_e32 v143, v79, v175
	v_fmac_f32_e32 v225, v95, v176
	global_store_dword v163, v143, s[48:49]
	global_store_dword v163, v225, s[48:49] offset:128
	s_waitcnt vmcnt(30)
	v_fmac_f32_e32 v144, v80, v175
	v_fmac_f32_e32 v226, v96, v176
	global_store_dword v164, v144, s[48:49]
	global_store_dword v164, v226, s[48:49] offset:128
	s_waitcnt vmcnt(30)
	v_fmac_f32_e32 v145, v81, v175
	v_fmac_f32_e32 v227, v97, v176
	global_store_dword v165, v145, s[48:49]
	global_store_dword v165, v227, s[48:49] offset:128
	s_sub_u32 s48, s48, 0x18000
	s_subb_u32 s49, s49, 0
	v_mul_f32_e32 v130, v130, v130
	v_fmac_f32_e32 v130, v212, v212
	v_mul_f32_e32 v131, v131, v131
	v_fmac_f32_e32 v131, v213, v213
	v_mul_f32_e32 v132, v132, v132
	v_fmac_f32_e32 v132, v214, v214
	v_mul_f32_e32 v133, v133, v133
	v_fmac_f32_e32 v133, v215, v215
	v_mul_f32_e32 v134, v134, v134
	v_fmac_f32_e32 v134, v216, v216
	v_mul_f32_e32 v135, v135, v135
	v_fmac_f32_e32 v135, v217, v217
	v_mul_f32_e32 v136, v136, v136
	v_fmac_f32_e32 v136, v218, v218
	v_mul_f32_e32 v137, v137, v137
	v_fmac_f32_e32 v137, v219, v219
	v_mul_f32_e32 v138, v138, v138
	v_fmac_f32_e32 v138, v220, v220
	v_mul_f32_e32 v139, v139, v139
	v_fmac_f32_e32 v139, v221, v221
	v_mul_f32_e32 v140, v140, v140
	v_fmac_f32_e32 v140, v222, v222
	v_mul_f32_e32 v141, v141, v141
	v_fmac_f32_e32 v141, v223, v223
	v_mul_f32_e32 v142, v142, v142
	v_fmac_f32_e32 v142, v224, v224
	v_mul_f32_e32 v143, v143, v143
	v_fmac_f32_e32 v143, v225, v225
	v_mul_f32_e32 v144, v144, v144
	v_fmac_f32_e32 v144, v226, v226
	v_mul_f32_e32 v145, v145, v145
	v_fmac_f32_e32 v145, v227, v227
	s_waitcnt lgkmcnt(0)
	ds_bpermute_b32 v212, v168, v130
	ds_bpermute_b32 v213, v168, v131
	ds_bpermute_b32 v214, v168, v132
	ds_bpermute_b32 v215, v168, v133
	ds_bpermute_b32 v216, v168, v134
	ds_bpermute_b32 v217, v168, v135
	ds_bpermute_b32 v218, v168, v136
	ds_bpermute_b32 v219, v168, v137
	s_waitcnt lgkmcnt(7)
	v_add_f32_e32 v130, v130, v212
	s_waitcnt lgkmcnt(6)
	v_add_f32_e32 v131, v131, v213
	s_waitcnt lgkmcnt(5)
	v_add_f32_e32 v132, v132, v214
	s_waitcnt lgkmcnt(4)
	v_add_f32_e32 v133, v133, v215
	s_waitcnt lgkmcnt(3)
	v_add_f32_e32 v134, v134, v216
	s_waitcnt lgkmcnt(2)
	v_add_f32_e32 v135, v135, v217
	s_waitcnt lgkmcnt(1)
	v_add_f32_e32 v136, v136, v218
	s_waitcnt lgkmcnt(0)
	v_add_f32_e32 v137, v137, v219
	ds_bpermute_b32 v212, v169, v130
	ds_bpermute_b32 v213, v169, v131
	ds_bpermute_b32 v214, v169, v132
	ds_bpermute_b32 v215, v169, v133
	ds_bpermute_b32 v216, v169, v134
	ds_bpermute_b32 v217, v169, v135
	ds_bpermute_b32 v218, v169, v136
	ds_bpermute_b32 v219, v169, v137
	s_waitcnt lgkmcnt(7)
	v_add_f32_e32 v130, v130, v212
	s_waitcnt lgkmcnt(6)
	v_add_f32_e32 v131, v131, v213
	s_waitcnt lgkmcnt(5)
	v_add_f32_e32 v132, v132, v214
	s_waitcnt lgkmcnt(4)
	v_add_f32_e32 v133, v133, v215
	s_waitcnt lgkmcnt(3)
	v_add_f32_e32 v134, v134, v216
	s_waitcnt lgkmcnt(2)
	v_add_f32_e32 v135, v135, v217
	s_waitcnt lgkmcnt(1)
	v_add_f32_e32 v136, v136, v218
	s_waitcnt lgkmcnt(0)
	v_add_f32_e32 v137, v137, v219
	ds_bpermute_b32 v212, v171, v130
	ds_bpermute_b32 v213, v171, v131
	ds_bpermute_b32 v214, v171, v132
	ds_bpermute_b32 v215, v171, v133
	ds_bpermute_b32 v216, v171, v134
	ds_bpermute_b32 v217, v171, v135
	ds_bpermute_b32 v218, v171, v136
	ds_bpermute_b32 v219, v171, v137
	s_waitcnt lgkmcnt(7)
	v_add_f32_e32 v130, v130, v212
	s_waitcnt lgkmcnt(6)
	v_add_f32_e32 v131, v131, v213
	s_waitcnt lgkmcnt(5)
	v_add_f32_e32 v132, v132, v214
	s_waitcnt lgkmcnt(4)
	v_add_f32_e32 v133, v133, v215
	s_waitcnt lgkmcnt(3)
	v_add_f32_e32 v134, v134, v216
	s_waitcnt lgkmcnt(2)
	v_add_f32_e32 v135, v135, v217
	s_waitcnt lgkmcnt(1)
	v_add_f32_e32 v136, v136, v218
	s_waitcnt lgkmcnt(0)
	v_add_f32_e32 v137, v137, v219
	ds_bpermute_b32 v212, v172, v130
	ds_bpermute_b32 v213, v172, v131
	ds_bpermute_b32 v214, v172, v132
	ds_bpermute_b32 v215, v172, v133
	ds_bpermute_b32 v216, v172, v134
	ds_bpermute_b32 v217, v172, v135
	ds_bpermute_b32 v218, v172, v136
	ds_bpermute_b32 v219, v172, v137
	s_waitcnt lgkmcnt(7)
	v_add_f32_e32 v130, v130, v212
	s_waitcnt lgkmcnt(6)
	v_add_f32_e32 v131, v131, v213
	s_waitcnt lgkmcnt(5)
	v_add_f32_e32 v132, v132, v214
	s_waitcnt lgkmcnt(4)
	v_add_f32_e32 v133, v133, v215
	s_waitcnt lgkmcnt(3)
	v_add_f32_e32 v134, v134, v216
	s_waitcnt lgkmcnt(2)
	v_add_f32_e32 v135, v135, v217
	s_waitcnt lgkmcnt(1)
	v_add_f32_e32 v136, v136, v218
	s_waitcnt lgkmcnt(0)
	v_add_f32_e32 v137, v137, v219
	ds_bpermute_b32 v212, v173, v130
	ds_bpermute_b32 v213, v173, v131
	ds_bpermute_b32 v214, v173, v132
	ds_bpermute_b32 v215, v173, v133
	ds_bpermute_b32 v216, v173, v134
	ds_bpermute_b32 v217, v173, v135
	ds_bpermute_b32 v218, v173, v136
	ds_bpermute_b32 v219, v173, v137
	s_waitcnt lgkmcnt(7)
	v_add_f32_e32 v130, v130, v212
	s_waitcnt lgkmcnt(6)
	v_add_f32_e32 v131, v131, v213
	s_waitcnt lgkmcnt(5)
	v_add_f32_e32 v132, v132, v214
	s_waitcnt lgkmcnt(4)
	v_add_f32_e32 v133, v133, v215
	s_waitcnt lgkmcnt(3)
	v_add_f32_e32 v134, v134, v216
	s_waitcnt lgkmcnt(2)
	v_add_f32_e32 v135, v135, v217
	s_waitcnt lgkmcnt(1)
	v_add_f32_e32 v136, v136, v218
	s_waitcnt lgkmcnt(0)
	v_add_f32_e32 v137, v137, v219
	ds_bpermute_b32 v220, v168, v138
	ds_bpermute_b32 v221, v168, v139
	ds_bpermute_b32 v222, v168, v140
	ds_bpermute_b32 v223, v168, v141
	ds_bpermute_b32 v224, v168, v142
	ds_bpermute_b32 v225, v168, v143
	ds_bpermute_b32 v226, v168, v144
	ds_bpermute_b32 v227, v168, v145
	s_waitcnt lgkmcnt(7)
	v_add_f32_e32 v138, v138, v220
	s_waitcnt lgkmcnt(6)
	v_add_f32_e32 v139, v139, v221
	s_waitcnt lgkmcnt(5)
	v_add_f32_e32 v140, v140, v222
	s_waitcnt lgkmcnt(4)
	v_add_f32_e32 v141, v141, v223
	s_waitcnt lgkmcnt(3)
	v_add_f32_e32 v142, v142, v224
	s_waitcnt lgkmcnt(2)
	v_add_f32_e32 v143, v143, v225
	s_waitcnt lgkmcnt(1)
	v_add_f32_e32 v144, v144, v226
	s_waitcnt lgkmcnt(0)
	v_add_f32_e32 v145, v145, v227
	ds_bpermute_b32 v220, v169, v138
	ds_bpermute_b32 v221, v169, v139
	ds_bpermute_b32 v222, v169, v140
	ds_bpermute_b32 v223, v169, v141
	ds_bpermute_b32 v224, v169, v142
	ds_bpermute_b32 v225, v169, v143
	ds_bpermute_b32 v226, v169, v144
	ds_bpermute_b32 v227, v169, v145
	s_waitcnt lgkmcnt(7)
	v_add_f32_e32 v138, v138, v220
	s_waitcnt lgkmcnt(6)
	v_add_f32_e32 v139, v139, v221
	s_waitcnt lgkmcnt(5)
	v_add_f32_e32 v140, v140, v222
	s_waitcnt lgkmcnt(4)
	v_add_f32_e32 v141, v141, v223
	s_waitcnt lgkmcnt(3)
	v_add_f32_e32 v142, v142, v224
	s_waitcnt lgkmcnt(2)
	v_add_f32_e32 v143, v143, v225
	s_waitcnt lgkmcnt(1)
	v_add_f32_e32 v144, v144, v226
	s_waitcnt lgkmcnt(0)
	v_add_f32_e32 v145, v145, v227
	ds_bpermute_b32 v220, v171, v138
	ds_bpermute_b32 v221, v171, v139
	ds_bpermute_b32 v222, v171, v140
	ds_bpermute_b32 v223, v171, v141
	ds_bpermute_b32 v224, v171, v142
	ds_bpermute_b32 v225, v171, v143
	ds_bpermute_b32 v226, v171, v144
	ds_bpermute_b32 v227, v171, v145
	s_waitcnt lgkmcnt(7)
	v_add_f32_e32 v138, v138, v220
	s_waitcnt lgkmcnt(6)
	v_add_f32_e32 v139, v139, v221
	s_waitcnt lgkmcnt(5)
	v_add_f32_e32 v140, v140, v222
	s_waitcnt lgkmcnt(4)
	v_add_f32_e32 v141, v141, v223
	s_waitcnt lgkmcnt(3)
	v_add_f32_e32 v142, v142, v224
	s_waitcnt lgkmcnt(2)
	v_add_f32_e32 v143, v143, v225
	s_waitcnt lgkmcnt(1)
	v_add_f32_e32 v144, v144, v226
	s_waitcnt lgkmcnt(0)
	v_add_f32_e32 v145, v145, v227
	ds_bpermute_b32 v220, v172, v138
	ds_bpermute_b32 v221, v172, v139
	ds_bpermute_b32 v222, v172, v140
	ds_bpermute_b32 v223, v172, v141
	ds_bpermute_b32 v224, v172, v142
	ds_bpermute_b32 v225, v172, v143
	ds_bpermute_b32 v226, v172, v144
	ds_bpermute_b32 v227, v172, v145
	s_waitcnt lgkmcnt(7)
	v_add_f32_e32 v138, v138, v220
	s_waitcnt lgkmcnt(6)
	v_add_f32_e32 v139, v139, v221
	s_waitcnt lgkmcnt(5)
	v_add_f32_e32 v140, v140, v222
	s_waitcnt lgkmcnt(4)
	v_add_f32_e32 v141, v141, v223
	s_waitcnt lgkmcnt(3)
	v_add_f32_e32 v142, v142, v224
	s_waitcnt lgkmcnt(2)
	v_add_f32_e32 v143, v143, v225
	s_waitcnt lgkmcnt(1)
	v_add_f32_e32 v144, v144, v226
	s_waitcnt lgkmcnt(0)
	v_add_f32_e32 v145, v145, v227
	ds_bpermute_b32 v220, v173, v138
	ds_bpermute_b32 v221, v173, v139
	ds_bpermute_b32 v222, v173, v140
	ds_bpermute_b32 v223, v173, v141
	ds_bpermute_b32 v224, v173, v142
	ds_bpermute_b32 v225, v173, v143
	ds_bpermute_b32 v226, v173, v144
	ds_bpermute_b32 v227, v173, v145
	s_waitcnt lgkmcnt(7)
	v_add_f32_e32 v138, v138, v220
	s_waitcnt lgkmcnt(6)
	v_add_f32_e32 v139, v139, v221
	s_waitcnt lgkmcnt(5)
	v_add_f32_e32 v140, v140, v222
	s_waitcnt lgkmcnt(4)
	v_add_f32_e32 v141, v141, v223
	s_waitcnt lgkmcnt(3)
	v_add_f32_e32 v142, v142, v224
	s_waitcnt lgkmcnt(2)
	v_add_f32_e32 v143, v143, v225
	s_waitcnt lgkmcnt(1)
	v_add_f32_e32 v144, v144, v226
	s_waitcnt lgkmcnt(0)
	v_add_f32_e32 v145, v145, v227
	v_cmp_eq_u32_e32 vcc, 0, v174
	s_and_saveexec_b64 s[58:59], vcc
	global_store_dword v167, v130, s[10:11]
	global_store_dword v167, v131, s[10:11] offset:4
	global_store_dword v167, v132, s[10:11] offset:8
	global_store_dword v167, v133, s[10:11] offset:12
	global_store_dword v167, v134, s[10:11] offset:32
	global_store_dword v167, v135, s[10:11] offset:36
	global_store_dword v167, v136, s[10:11] offset:40
	global_store_dword v167, v137, s[10:11] offset:44
	global_store_dword v167, v138, s[10:11] offset:64
	global_store_dword v167, v139, s[10:11] offset:68
	global_store_dword v167, v140, s[10:11] offset:72
	global_store_dword v167, v141, s[10:11] offset:76
	global_store_dword v167, v142, s[10:11] offset:96
	global_store_dword v167, v143, s[10:11] offset:100
	global_store_dword v167, v144, s[10:11] offset:104
	global_store_dword v167, v145, s[10:11] offset:108
	s_mov_b64 exec, -1
	s_add_u32 s48, s48, 0x20000
	s_addc_u32 s49, s49, 0
	global_load_dword v130, v162, s[48:49]
	global_load_dword v212, v162, s[48:49] offset:128
	global_load_dword v131, v163, s[48:49]
	global_load_dword v213, v163, s[48:49] offset:128
	global_load_dword v132, v164, s[48:49]
	global_load_dword v214, v164, s[48:49] offset:128
	global_load_dword v133, v165, s[48:49]
	global_load_dword v215, v165, s[48:49] offset:128
	s_add_u32 s48, s48, 0x8000
	s_addc_u32 s49, s49, 0
	global_load_dword v134, v162, s[48:49]
	global_load_dword v216, v162, s[48:49] offset:128
	global_load_dword v135, v163, s[48:49]
	global_load_dword v217, v163, s[48:49] offset:128
	global_load_dword v136, v164, s[48:49]
	global_load_dword v218, v164, s[48:49] offset:128
	global_load_dword v137, v165, s[48:49]
	global_load_dword v219, v165, s[48:49] offset:128
	s_add_u32 s48, s48, 0x8000
	s_addc_u32 s49, s49, 0
	global_load_dword v138, v162, s[48:49]
	global_load_dword v220, v162, s[48:49] offset:128
	global_load_dword v139, v163, s[48:49]
	global_load_dword v221, v163, s[48:49] offset:128
	global_load_dword v140, v164, s[48:49]
	global_load_dword v222, v164, s[48:49] offset:128
	global_load_dword v141, v165, s[48:49]
	global_load_dword v223, v165, s[48:49] offset:128
	s_add_u32 s48, s48, 0x8000
	s_addc_u32 s49, s49, 0
	global_load_dword v142, v162, s[48:49]
	global_load_dword v224, v162, s[48:49] offset:128
	global_load_dword v143, v163, s[48:49]
	global_load_dword v225, v163, s[48:49] offset:128
	global_load_dword v144, v164, s[48:49]
	global_load_dword v226, v164, s[48:49] offset:128
	global_load_dword v145, v165, s[48:49]
	global_load_dword v227, v165, s[48:49] offset:128
	s_sub_u32 s48, s48, 0x18000
	s_subb_u32 s49, s49, 0
	s_waitcnt vmcnt(30)
	v_fmac_f32_e32 v130, v98, v175
	v_fmac_f32_e32 v212, v114, v176
	global_store_dword v162, v130, s[48:49]
	global_store_dword v162, v212, s[48:49] offset:128
	s_waitcnt vmcnt(30)
	v_fmac_f32_e32 v131, v99, v175
	v_fmac_f32_e32 v213, v115, v176
	global_store_dword v163, v131, s[48:49]
	global_store_dword v163, v213, s[48:49] offset:128
	s_waitcnt vmcnt(30)
	v_fmac_f32_e32 v132, v100, v175
	v_fmac_f32_e32 v214, v116, v176
	global_store_dword v164, v132, s[48:49]
	global_store_dword v164, v214, s[48:49] offset:128
	s_waitcnt vmcnt(30)
	v_fmac_f32_e32 v133, v101, v175
	v_fmac_f32_e32 v215, v117, v176
	global_store_dword v165, v133, s[48:49]
	global_store_dword v165, v215, s[48:49] offset:128
	s_add_u32 s48, s48, 0x8000
	s_addc_u32 s49, s49, 0
	s_waitcnt vmcnt(30)
	v_fmac_f32_e32 v134, v102, v175
	v_fmac_f32_e32 v216, v118, v176
	global_store_dword v162, v134, s[48:49]
	global_store_dword v162, v216, s[48:49] offset:128
	s_waitcnt vmcnt(30)
	v_fmac_f32_e32 v135, v103, v175
	v_fmac_f32_e32 v217, v119, v176
	global_store_dword v163, v135, s[48:49]
	global_store_dword v163, v217, s[48:49] offset:128
	s_waitcnt vmcnt(30)
	v_fmac_f32_e32 v136, v104, v175
	v_fmac_f32_e32 v218, v120, v176
	global_store_dword v164, v136, s[48:49]
	global_store_dword v164, v218, s[48:49] offset:128
	s_waitcnt vmcnt(30)
	v_fmac_f32_e32 v137, v105, v175
	v_fmac_f32_e32 v219, v121, v176
	global_store_dword v165, v137, s[48:49]
	global_store_dword v165, v219, s[48:49] offset:128
	s_add_u32 s48, s48, 0x8000
	s_addc_u32 s49, s49, 0
	s_waitcnt vmcnt(30)
	v_fmac_f32_e32 v138, v106, v175
	v_fmac_f32_e32 v220, v122, v176
	global_store_dword v162, v138, s[48:49]
	global_store_dword v162, v220, s[48:49] offset:128
	s_waitcnt vmcnt(30)
	v_fmac_f32_e32 v139, v107, v175
	v_fmac_f32_e32 v221, v123, v176
	global_store_dword v163, v139, s[48:49]
	global_store_dword v163, v221, s[48:49] offset:128
	s_waitcnt vmcnt(30)
	v_fmac_f32_e32 v140, v108, v175
	v_fmac_f32_e32 v222, v124, v176
	global_store_dword v164, v140, s[48:49]
	global_store_dword v164, v222, s[48:49] offset:128
	s_waitcnt vmcnt(30)
	v_fmac_f32_e32 v141, v109, v175
	v_fmac_f32_e32 v223, v125, v176
	global_store_dword v165, v141, s[48:49]
	global_store_dword v165, v223, s[48:49] offset:128
	s_add_u32 s48, s48, 0x8000
	s_addc_u32 s49, s49, 0
	s_waitcnt vmcnt(30)
	v_fmac_f32_e32 v142, v110, v175
	v_fmac_f32_e32 v224, v126, v176
	global_store_dword v162, v142, s[48:49]
	global_store_dword v162, v224, s[48:49] offset:128
	s_waitcnt vmcnt(30)
	v_fmac_f32_e32 v143, v111, v175
	v_fmac_f32_e32 v225, v127, v176
	global_store_dword v163, v143, s[48:49]
	global_store_dword v163, v225, s[48:49] offset:128
	s_waitcnt vmcnt(30)
	v_fmac_f32_e32 v144, v112, v175
	v_fmac_f32_e32 v226, v128, v176
	global_store_dword v164, v144, s[48:49]
	global_store_dword v164, v226, s[48:49] offset:128
	s_waitcnt vmcnt(30)
	v_fmac_f32_e32 v145, v113, v175
	v_fmac_f32_e32 v227, v129, v176
	global_store_dword v165, v145, s[48:49]
	global_store_dword v165, v227, s[48:49] offset:128
	s_sub_u32 s48, s48, 0x18000
	s_subb_u32 s49, s49, 0
	v_mul_f32_e32 v130, v130, v130
	v_fmac_f32_e32 v130, v212, v212
	v_mul_f32_e32 v131, v131, v131
	v_fmac_f32_e32 v131, v213, v213
	v_mul_f32_e32 v132, v132, v132
	v_fmac_f32_e32 v132, v214, v214
	v_mul_f32_e32 v133, v133, v133
	v_fmac_f32_e32 v133, v215, v215
	v_mul_f32_e32 v134, v134, v134
	v_fmac_f32_e32 v134, v216, v216
	v_mul_f32_e32 v135, v135, v135
	v_fmac_f32_e32 v135, v217, v217
	v_mul_f32_e32 v136, v136, v136
	v_fmac_f32_e32 v136, v218, v218
	v_mul_f32_e32 v137, v137, v137
	v_fmac_f32_e32 v137, v219, v219
	v_mul_f32_e32 v138, v138, v138
	v_fmac_f32_e32 v138, v220, v220
	v_mul_f32_e32 v139, v139, v139
	v_fmac_f32_e32 v139, v221, v221
	v_mul_f32_e32 v140, v140, v140
	v_fmac_f32_e32 v140, v222, v222
	v_mul_f32_e32 v141, v141, v141
	v_fmac_f32_e32 v141, v223, v223
	v_mul_f32_e32 v142, v142, v142
	v_fmac_f32_e32 v142, v224, v224
	v_mul_f32_e32 v143, v143, v143
	v_fmac_f32_e32 v143, v225, v225
	v_mul_f32_e32 v144, v144, v144
	v_fmac_f32_e32 v144, v226, v226
	v_mul_f32_e32 v145, v145, v145
	v_fmac_f32_e32 v145, v227, v227
	s_waitcnt lgkmcnt(0)
	ds_bpermute_b32 v212, v168, v130
	ds_bpermute_b32 v213, v168, v131
	ds_bpermute_b32 v214, v168, v132
	ds_bpermute_b32 v215, v168, v133
	ds_bpermute_b32 v216, v168, v134
	ds_bpermute_b32 v217, v168, v135
	ds_bpermute_b32 v218, v168, v136
	ds_bpermute_b32 v219, v168, v137
	s_waitcnt lgkmcnt(7)
	v_add_f32_e32 v130, v130, v212
	s_waitcnt lgkmcnt(6)
	v_add_f32_e32 v131, v131, v213
	s_waitcnt lgkmcnt(5)
	v_add_f32_e32 v132, v132, v214
	s_waitcnt lgkmcnt(4)
	v_add_f32_e32 v133, v133, v215
	s_waitcnt lgkmcnt(3)
	v_add_f32_e32 v134, v134, v216
	s_waitcnt lgkmcnt(2)
	v_add_f32_e32 v135, v135, v217
	s_waitcnt lgkmcnt(1)
	v_add_f32_e32 v136, v136, v218
	s_waitcnt lgkmcnt(0)
	v_add_f32_e32 v137, v137, v219
	ds_bpermute_b32 v212, v169, v130
	ds_bpermute_b32 v213, v169, v131
	ds_bpermute_b32 v214, v169, v132
	ds_bpermute_b32 v215, v169, v133
	ds_bpermute_b32 v216, v169, v134
	ds_bpermute_b32 v217, v169, v135
	ds_bpermute_b32 v218, v169, v136
	ds_bpermute_b32 v219, v169, v137
	s_waitcnt lgkmcnt(7)
	v_add_f32_e32 v130, v130, v212
	s_waitcnt lgkmcnt(6)
	v_add_f32_e32 v131, v131, v213
	s_waitcnt lgkmcnt(5)
	v_add_f32_e32 v132, v132, v214
	s_waitcnt lgkmcnt(4)
	v_add_f32_e32 v133, v133, v215
	s_waitcnt lgkmcnt(3)
	v_add_f32_e32 v134, v134, v216
	s_waitcnt lgkmcnt(2)
	v_add_f32_e32 v135, v135, v217
	s_waitcnt lgkmcnt(1)
	v_add_f32_e32 v136, v136, v218
	s_waitcnt lgkmcnt(0)
	v_add_f32_e32 v137, v137, v219
	ds_bpermute_b32 v212, v171, v130
	ds_bpermute_b32 v213, v171, v131
	ds_bpermute_b32 v214, v171, v132
	ds_bpermute_b32 v215, v171, v133
	ds_bpermute_b32 v216, v171, v134
	ds_bpermute_b32 v217, v171, v135
	ds_bpermute_b32 v218, v171, v136
	ds_bpermute_b32 v219, v171, v137
	s_waitcnt lgkmcnt(7)
	v_add_f32_e32 v130, v130, v212
	s_waitcnt lgkmcnt(6)
	v_add_f32_e32 v131, v131, v213
	s_waitcnt lgkmcnt(5)
	v_add_f32_e32 v132, v132, v214
	s_waitcnt lgkmcnt(4)
	v_add_f32_e32 v133, v133, v215
	s_waitcnt lgkmcnt(3)
	v_add_f32_e32 v134, v134, v216
	s_waitcnt lgkmcnt(2)
	v_add_f32_e32 v135, v135, v217
	s_waitcnt lgkmcnt(1)
	v_add_f32_e32 v136, v136, v218
	s_waitcnt lgkmcnt(0)
	v_add_f32_e32 v137, v137, v219
	ds_bpermute_b32 v212, v172, v130
	ds_bpermute_b32 v213, v172, v131
	ds_bpermute_b32 v214, v172, v132
	ds_bpermute_b32 v215, v172, v133
	ds_bpermute_b32 v216, v172, v134
	ds_bpermute_b32 v217, v172, v135
	ds_bpermute_b32 v218, v172, v136
	ds_bpermute_b32 v219, v172, v137
	s_waitcnt lgkmcnt(7)
	v_add_f32_e32 v130, v130, v212
	s_waitcnt lgkmcnt(6)
	v_add_f32_e32 v131, v131, v213
	s_waitcnt lgkmcnt(5)
	v_add_f32_e32 v132, v132, v214
	s_waitcnt lgkmcnt(4)
	v_add_f32_e32 v133, v133, v215
	s_waitcnt lgkmcnt(3)
	v_add_f32_e32 v134, v134, v216
	s_waitcnt lgkmcnt(2)
	v_add_f32_e32 v135, v135, v217
	s_waitcnt lgkmcnt(1)
	v_add_f32_e32 v136, v136, v218
	s_waitcnt lgkmcnt(0)
	v_add_f32_e32 v137, v137, v219
	ds_bpermute_b32 v212, v173, v130
	ds_bpermute_b32 v213, v173, v131
	ds_bpermute_b32 v214, v173, v132
	ds_bpermute_b32 v215, v173, v133
	ds_bpermute_b32 v216, v173, v134
	ds_bpermute_b32 v217, v173, v135
	ds_bpermute_b32 v218, v173, v136
	ds_bpermute_b32 v219, v173, v137
	s_waitcnt lgkmcnt(7)
	v_add_f32_e32 v130, v130, v212
	s_waitcnt lgkmcnt(6)
	v_add_f32_e32 v131, v131, v213
	s_waitcnt lgkmcnt(5)
	v_add_f32_e32 v132, v132, v214
	s_waitcnt lgkmcnt(4)
	v_add_f32_e32 v133, v133, v215
	s_waitcnt lgkmcnt(3)
	v_add_f32_e32 v134, v134, v216
	s_waitcnt lgkmcnt(2)
	v_add_f32_e32 v135, v135, v217
	s_waitcnt lgkmcnt(1)
	v_add_f32_e32 v136, v136, v218
	s_waitcnt lgkmcnt(0)
	v_add_f32_e32 v137, v137, v219
	ds_bpermute_b32 v220, v168, v138
	ds_bpermute_b32 v221, v168, v139
	ds_bpermute_b32 v222, v168, v140
	ds_bpermute_b32 v223, v168, v141
	ds_bpermute_b32 v224, v168, v142
	ds_bpermute_b32 v225, v168, v143
	ds_bpermute_b32 v226, v168, v144
	ds_bpermute_b32 v227, v168, v145
	s_waitcnt lgkmcnt(7)
	v_add_f32_e32 v138, v138, v220
	s_waitcnt lgkmcnt(6)
	v_add_f32_e32 v139, v139, v221
	s_waitcnt lgkmcnt(5)
	v_add_f32_e32 v140, v140, v222
	s_waitcnt lgkmcnt(4)
	v_add_f32_e32 v141, v141, v223
	s_waitcnt lgkmcnt(3)
	v_add_f32_e32 v142, v142, v224
	s_waitcnt lgkmcnt(2)
	v_add_f32_e32 v143, v143, v225
	s_waitcnt lgkmcnt(1)
	v_add_f32_e32 v144, v144, v226
	s_waitcnt lgkmcnt(0)
	v_add_f32_e32 v145, v145, v227
	ds_bpermute_b32 v220, v169, v138
	ds_bpermute_b32 v221, v169, v139
	ds_bpermute_b32 v222, v169, v140
	ds_bpermute_b32 v223, v169, v141
	ds_bpermute_b32 v224, v169, v142
	ds_bpermute_b32 v225, v169, v143
	ds_bpermute_b32 v226, v169, v144
	ds_bpermute_b32 v227, v169, v145
	s_waitcnt lgkmcnt(7)
	v_add_f32_e32 v138, v138, v220
	s_waitcnt lgkmcnt(6)
	v_add_f32_e32 v139, v139, v221
	s_waitcnt lgkmcnt(5)
	v_add_f32_e32 v140, v140, v222
	s_waitcnt lgkmcnt(4)
	v_add_f32_e32 v141, v141, v223
	s_waitcnt lgkmcnt(3)
	v_add_f32_e32 v142, v142, v224
	s_waitcnt lgkmcnt(2)
	v_add_f32_e32 v143, v143, v225
	s_waitcnt lgkmcnt(1)
	v_add_f32_e32 v144, v144, v226
	s_waitcnt lgkmcnt(0)
	v_add_f32_e32 v145, v145, v227
	ds_bpermute_b32 v220, v171, v138
	ds_bpermute_b32 v221, v171, v139
	ds_bpermute_b32 v222, v171, v140
	ds_bpermute_b32 v223, v171, v141
	ds_bpermute_b32 v224, v171, v142
	ds_bpermute_b32 v225, v171, v143
	ds_bpermute_b32 v226, v171, v144
	ds_bpermute_b32 v227, v171, v145
	s_waitcnt lgkmcnt(7)
	v_add_f32_e32 v138, v138, v220
	s_waitcnt lgkmcnt(6)
	v_add_f32_e32 v139, v139, v221
	s_waitcnt lgkmcnt(5)
	v_add_f32_e32 v140, v140, v222
	s_waitcnt lgkmcnt(4)
	v_add_f32_e32 v141, v141, v223
	s_waitcnt lgkmcnt(3)
	v_add_f32_e32 v142, v142, v224
	s_waitcnt lgkmcnt(2)
	v_add_f32_e32 v143, v143, v225
	s_waitcnt lgkmcnt(1)
	v_add_f32_e32 v144, v144, v226
	s_waitcnt lgkmcnt(0)
	v_add_f32_e32 v145, v145, v227
	ds_bpermute_b32 v220, v172, v138
	ds_bpermute_b32 v221, v172, v139
	ds_bpermute_b32 v222, v172, v140
	ds_bpermute_b32 v223, v172, v141
	ds_bpermute_b32 v224, v172, v142
	ds_bpermute_b32 v225, v172, v143
	ds_bpermute_b32 v226, v172, v144
	ds_bpermute_b32 v227, v172, v145
	s_waitcnt lgkmcnt(7)
	v_add_f32_e32 v138, v138, v220
	s_waitcnt lgkmcnt(6)
	v_add_f32_e32 v139, v139, v221
	s_waitcnt lgkmcnt(5)
	v_add_f32_e32 v140, v140, v222
	s_waitcnt lgkmcnt(4)
	v_add_f32_e32 v141, v141, v223
	s_waitcnt lgkmcnt(3)
	v_add_f32_e32 v142, v142, v224
	s_waitcnt lgkmcnt(2)
	v_add_f32_e32 v143, v143, v225
	s_waitcnt lgkmcnt(1)
	v_add_f32_e32 v144, v144, v226
	s_waitcnt lgkmcnt(0)
	v_add_f32_e32 v145, v145, v227
	ds_bpermute_b32 v220, v173, v138
	ds_bpermute_b32 v221, v173, v139
	ds_bpermute_b32 v222, v173, v140
	ds_bpermute_b32 v223, v173, v141
	ds_bpermute_b32 v224, v173, v142
	ds_bpermute_b32 v225, v173, v143
	ds_bpermute_b32 v226, v173, v144
	ds_bpermute_b32 v227, v173, v145
	s_waitcnt lgkmcnt(7)
	v_add_f32_e32 v138, v138, v220
	s_waitcnt lgkmcnt(6)
	v_add_f32_e32 v139, v139, v221
	s_waitcnt lgkmcnt(5)
	v_add_f32_e32 v140, v140, v222
	s_waitcnt lgkmcnt(4)
	v_add_f32_e32 v141, v141, v223
	s_waitcnt lgkmcnt(3)
	v_add_f32_e32 v142, v142, v224
	s_waitcnt lgkmcnt(2)
	v_add_f32_e32 v143, v143, v225
	s_waitcnt lgkmcnt(1)
	v_add_f32_e32 v144, v144, v226
	s_waitcnt lgkmcnt(0)
	v_add_f32_e32 v145, v145, v227
	v_cmp_eq_u32_e32 vcc, 0, v174
	s_and_saveexec_b64 s[58:59], vcc
	global_store_dword v167, v130, s[10:11] offset:128
	global_store_dword v167, v131, s[10:11] offset:132
	global_store_dword v167, v132, s[10:11] offset:136
	global_store_dword v167, v133, s[10:11] offset:140
	global_store_dword v167, v134, s[10:11] offset:160
	global_store_dword v167, v135, s[10:11] offset:164
	global_store_dword v167, v136, s[10:11] offset:168
	global_store_dword v167, v137, s[10:11] offset:172
	global_store_dword v167, v138, s[10:11] offset:192
	global_store_dword v167, v139, s[10:11] offset:196
	global_store_dword v167, v140, s[10:11] offset:200
	global_store_dword v167, v141, s[10:11] offset:204
	global_store_dword v167, v142, s[10:11] offset:224
	global_store_dword v167, v143, s[10:11] offset:228
	global_store_dword v167, v144, s[10:11] offset:232
	global_store_dword v167, v145, s[10:11] offset:236
	s_mov_b64 exec, -1
	s_sub_u32 s48, s48, 0x20000
	s_subb_u32 s49, s49, 0
	v_readlane_b32 s2, v246, 14
	s_nop 0
	s_add_i32 s16, s16, s2
	s_branch .Lhw_outproj_tloop
.Lhw_outproj_exit:
	s_branch .LBB0_327
.LBB0_327:
	v_readlane_b32 s8, v246, 29
	v_readlane_b32 s9, v246, 30
	s_and_b64 vcc, exec, s[8:9]
	s_cbranch_vccz .LBB0_418
	v_readlane_b32 s8, v247, 39
	v_readlane_b32 s9, v247, 40
	s_andn2_b64 vcc, exec, s[8:9]
	s_cbranch_vccnz .LBB0_418
	s_lshl_b64 s[8:9], s[88:89], 4
	s_add_u32 s2, s56, s8
	s_addc_u32 s6, s57, s9
	s_add_u32 s10, s56, 0x160
	s_addc_u32 s11, s57, 0
	s_add_u32 s12, s56, 0xffffffc0
	s_addc_u32 s13, s57, -1
	s_mov_b64 s[14:15], 0
	s_mov_b64 s[18:19], -1
	s_branch .LBB0_331

.LBB0_2297:
	s_lshl_b32 s58, s88, 1
	v_readlane_b32 s0, v246, 25
	v_readlane_b32 s66, v246, 19
	s_cmp_gt_i32 s0, 1
	s_mov_b64 s[0:1], -1
	s_mov_b32 s59, 0x30000
	s_movk_i32 s62, 0xfff
	s_mov_b32 s63, 0x20000
	s_mov_b32 s64, 0xfffffc0
	s_movk_i32 s65, 0x1ff
	v_readlane_b32 s67, v246, 20
	s_cbranch_scc0 .LBB0_2457
	v_readlane_b32 s0, v246, 26
	v_readlane_b32 s10, v247, 19
	s_cmp_eq_u32 s0, 11
	v_readlane_b32 s11, v247, 20
	s_cselect_b64 s[8:9], -1, 0
	s_mov_b64 s[0:1], s[84:85]
	s_andn2_b64 vcc, exec, s[10:11]
	s_cbranch_vccnz .LBB0_2365
	v_cndmask_b32_e64 v0, 0, 1, s[8:9]
	s_load_dwordx2 s[40:41], s[0:1], 0x108
	v_readfirstlane_b32 s2, v0
	s_or_b32 s2, s58, s2
	s_and_b64 s[10:11], s[8:9], exec
	s_cselect_b32 s10, 3, 1
	v_readlane_b32 s11, v246, 27
	s_cselect_b32 s12, 8, 2
	s_add_i32 s10, s11, s10
	s_waitcnt lgkmcnt(0)
	s_add_u32 s42, s40, 0x3000000
	s_addc_u32 s43, s41, 0
	s_add_u32 s13, s40, 0x7bc0000
	s_addc_u32 s14, s41, 0
	s_mul_hi_i32 s11, s10, 0xc0000
	s_mul_i32 s10, s10, 0xc0000
	s_add_u32 s10, s40, s10
	s_addc_u32 s11, s41, s11
	s_add_u32 s44, s10, 0x7200000
	s_mul_hi_i32 s6, s2, 0x580000
	s_mul_i32 s2, s2, 0x580000
	s_addc_u32 s45, s11, 0
	s_add_u32 s2, s40, s2
	s_addc_u32 s6, s41, s6
	s_add_u32 s46, s2, 0xd478100
	s_addc_u32 s47, s6, 0
	v_readlane_b32 s15, v247, 44
	s_mov_b32 s16, s83
	s_lshl_b32 s2, s12, 12
	s_add_u32 s12, s13, s2
	s_addc_u32 s13, s14, 0
	v_and_b32_e32 v177, 63, v194
	v_lshrrev_b32_e32 v178, 6, v194
	v_lshrrev_b32_e32 v160, 2, v194
	v_mul_u32_u24_e32 v160, 0x1600, v160
	v_and_b32_e32 v179, 3, v177
	v_bfe_u32 v180, v177, 4, 2
	v_xor_b32_e32 v179, v179, v180
	v_lshl_add_u32 v160, v179, 4, v160
	v_add_u32_e32 v161, 0x58000, v160
	v_and_b32_e32 v174, 31, v177
	v_lshrrev_b32_e32 v182, 5, v177
	v_bfe_u32 v183, v174, 2, 2
	v_xor_b32_e32 v184, v182, v183
	v_xor_b32_e32 v185, 2, v184
	v_lshrrev_b32_e32 v186, 1, v178
	v_and_b32_e32 v187, 1, v178
	v_lshl_add_u32 v188, v186, 6, v174
	v_lshl_add_u32 v189, v187, 6, v174
	v_lshlrev_b32_e32 v188, 6, v188
	v_lshlrev_b32_e32 v189, 6, v189
	v_lshl_add_u32 v154, v184, 4, v188
	v_lshl_add_u32 v155, v185, 4, v188
	v_lshl_add_u32 v156, v184, 4, v189
	v_lshl_add_u32 v157, v185, 4, v189
	v_add_u32_e32 v158, 0x2000, v156
	v_add_u32_e32 v159, 0x2000, v157
	v_lshlrev_b32_e32 v190, 6, v186
	v_lshl_add_u32 v190, v182, 2, v190
	v_lshl_add_u32 v191, v187, 6, v174
	v_lshlrev_b32_e32 v192, 12, v190
	v_lshl_add_u32 v162, v191, 2, v192
	v_add_u32_e32 v163, 0x1000, v162
	v_add_u32_e32 v164, 0x2000, v162
	v_add_u32_e32 v165, 0x3000, v162
	v_lshlrev_b32_e32 v166, 2, v191
	v_mul_u32_u24_e32 v167, 0xc000, v187
	v_lshl_add_u32 v167, v190, 2, v167
	v_xor_b32_e32 v168, 16, v177
	v_lshlrev_b32_e32 v168, 2, v168
	v_xor_b32_e32 v169, 8, v177
	v_lshlrev_b32_e32 v169, 2, v169
	v_xor_b32_e32 v171, 4, v177
	v_lshlrev_b32_e32 v171, 2, v171
	v_xor_b32_e32 v172, 2, v177
	v_lshlrev_b32_e32 v172, 2, v172
	v_xor_b32_e32 v173, 1, v177
	v_lshlrev_b32_e32 v173, 2, v173
	v_readfirstlane_b32 s65, v194
	s_nop 0
	s_lshl_b32 s65, s65, 4
	s_add_u32 s65, s65, 16
	s_mov_b32 s16, s83
.Lhw_ffndown_tloop:
	s_cmpk_gt_u32 s16, 47
	s_cbranch_scc1 .Lhw_ffndown_exit
	v_readlane_b32 s6, v246, 16
	s_lshr_b32 s2, s16, 2
	s_and_b32 s15, s16, 3
	s_add_i32 s6, s6, s2
	s_lshl_b32 s6, s6, 7
	s_lshl_b32 s15, s15, 8
	s_mul_i32 vcc_lo, s6, 0x1600
	s_add_u32 s66, s42, vcc_lo
	s_addc_u32 s67, s43, 0
	s_mul_i32 vcc_lo, s15, 0x1600
	s_add_u32 s62, s46, vcc_lo
	s_addc_u32 s63, s47, 0
	s_add_u32 s18, s62, 0xb0000
	s_addc_u32 s19, s63, 0
	s_barrier
	s_add_u32 m0, s65, 0x0
	s_nop 0
	global_load_lds_dwordx4 v160, s[66:67]
	s_add_u32 m0, s65, 0x1000
	s_nop 0
	global_load_lds_dwordx4 v161, s[66:67]
	s_add_u32 m0, s65, 0x2000
	s_nop 0
	global_load_lds_dwordx4 v160, s[62:63]
	s_add_u32 m0, s65, 0x3000
	s_nop 0
	global_load_lds_dwordx4 v161, s[62:63]
	s_add_u32 m0, s65, 0x4000
	s_nop 0
	global_load_lds_dwordx4 v160, s[18:19]
	s_add_u32 m0, s65, 0x5000
	s_nop 0
	global_load_lds_dwordx4 v161, s[18:19]
	s_add_u32 s66, s66, 64
	s_addc_u32 s67, s67, 0
	s_add_u32 s62, s62, 64
	s_addc_u32 s63, s63, 0
	s_add_u32 s18, s18, 64
	s_addc_u32 s19, s19, 0
	s_add_u32 m0, s65, 0x6000
	s_nop 0
	global_load_lds_dwordx4 v160, s[66:67]
	s_add_u32 m0, s65, 0x7000
	s_nop 0
	global_load_lds_dwordx4 v161, s[66:67]
	s_add_u32 m0, s65, 0x8000
	s_nop 0
	global_load_lds_dwordx4 v160, s[62:63]
	s_add_u32 m0, s65, 0x9000
	s_nop 0
	global_load_lds_dwordx4 v161, s[62:63]
	s_add_u32 m0, s65, 0xa000
	s_nop 0
	global_load_lds_dwordx4 v160, s[18:19]
	s_add_u32 m0, s65, 0xb000
	s_nop 0
	global_load_lds_dwordx4 v161, s[18:19]
	s_add_u32 s66, s66, 64
	s_addc_u32 s67, s67, 0
	s_add_u32 s62, s62, 64
	s_addc_u32 s63, s63, 0
	s_add_u32 s18, s18, 64
	s_addc_u32 s19, s19, 0
	v_mov_b32_e32 v2, 0
	v_mov_b32_e32 v3, 0
	v_mov_b32_e32 v4, 0
	v_mov_b32_e32 v5, 0
	v_mov_b32_e32 v6, 0
	v_mov_b32_e32 v7, 0
	v_mov_b32_e32 v8, 0
	v_mov_b32_e32 v9, 0
	v_mov_b32_e32 v10, 0
	v_mov_b32_e32 v11, 0
	v_mov_b32_e32 v12, 0
	v_mov_b32_e32 v13, 0
	v_mov_b32_e32 v14, 0
	v_mov_b32_e32 v15, 0
	v_mov_b32_e32 v16, 0
	v_mov_b32_e32 v17, 0
	v_mov_b32_e32 v18, 0
	v_mov_b32_e32 v19, 0
	v_mov_b32_e32 v20, 0
	v_mov_b32_e32 v21, 0
	v_mov_b32_e32 v22, 0
	v_mov_b32_e32 v23, 0
	v_mov_b32_e32 v24, 0
	v_mov_b32_e32 v25, 0
	v_mov_b32_e32 v26, 0
	v_mov_b32_e32 v27, 0
	v_mov_b32_e32 v28, 0
	v_mov_b32_e32 v29, 0
	v_mov_b32_e32 v30, 0
	v_mov_b32_e32 v31, 0
	v_mov_b32_e32 v32, 0
	v_mov_b32_e32 v33, 0
	v_mov_b32_e32 v34, 0
	v_mov_b32_e32 v35, 0
	v_mov_b32_e32 v36, 0
	v_mov_b32_e32 v37, 0
	v_mov_b32_e32 v38, 0
	v_mov_b32_e32 v39, 0
	v_mov_b32_e32 v40, 0
	v_mov_b32_e32 v41, 0
	v_mov_b32_e32 v42, 0
	v_mov_b32_e32 v43, 0
	v_mov_b32_e32 v44, 0
	v_mov_b32_e32 v45, 0
	v_mov_b32_e32 v46, 0
	v_mov_b32_e32 v47, 0
	v_mov_b32_e32 v48, 0
	v_mov_b32_e32 v49, 0
	v_mov_b32_e32 v50, 0
	v_mov_b32_e32 v51, 0
	v_mov_b32_e32 v52, 0
	v_mov_b32_e32 v53, 0
	v_mov_b32_e32 v54, 0
	v_mov_b32_e32 v55, 0
	v_mov_b32_e32 v56, 0
	v_mov_b32_e32 v57, 0
	v_mov_b32_e32 v58, 0
	v_mov_b32_e32 v59, 0
	v_mov_b32_e32 v60, 0
	v_mov_b32_e32 v61, 0
	v_mov_b32_e32 v62, 0
	v_mov_b32_e32 v63, 0
	v_mov_b32_e32 v64, 0
	v_mov_b32_e32 v65, 0
	v_mov_b32_e32 v66, 0
	v_mov_b32_e32 v67, 0
	v_mov_b32_e32 v68, 0
	v_mov_b32_e32 v69, 0
	v_mov_b32_e32 v70, 0
	v_mov_b32_e32 v71, 0
	v_mov_b32_e32 v72, 0
	v_mov_b32_e32 v73, 0
	v_mov_b32_e32 v74, 0
	v_mov_b32_e32 v75, 0
	v_mov_b32_e32 v76, 0
	v_mov_b32_e32 v77, 0
	v_mov_b32_e32 v78, 0
	v_mov_b32_e32 v79, 0
	v_mov_b32_e32 v80, 0
	v_mov_b32_e32 v81, 0
	v_mov_b32_e32 v82, 0
	v_mov_b32_e32 v83, 0
	v_mov_b32_e32 v84, 0
	v_mov_b32_e32 v85, 0
	v_mov_b32_e32 v86, 0
	v_mov_b32_e32 v87, 0
	v_mov_b32_e32 v88, 0
	v_mov_b32_e32 v89, 0
	v_mov_b32_e32 v90, 0
	v_mov_b32_e32 v91, 0
	v_mov_b32_e32 v92, 0
	v_mov_b32_e32 v93, 0
	v_mov_b32_e32 v94, 0
	v_mov_b32_e32 v95, 0
	v_mov_b32_e32 v96, 0
	v_mov_b32_e32 v97, 0
	v_mov_b32_e32 v98, 0
	v_mov_b32_e32 v99, 0
	v_mov_b32_e32 v100, 0
	v_mov_b32_e32 v101, 0
	v_mov_b32_e32 v102, 0
	v_mov_b32_e32 v103, 0
	v_mov_b32_e32 v104, 0
	v_mov_b32_e32 v105, 0
	v_mov_b32_e32 v106, 0
	v_mov_b32_e32 v107, 0
	v_mov_b32_e32 v108, 0
	v_mov_b32_e32 v109, 0
	v_mov_b32_e32 v110, 0
	v_mov_b32_e32 v111, 0
	v_mov_b32_e32 v112, 0
	v_mov_b32_e32 v113, 0
	v_mov_b32_e32 v114, 0
	v_mov_b32_e32 v115, 0
	v_mov_b32_e32 v116, 0
	v_mov_b32_e32 v117, 0
	v_mov_b32_e32 v118, 0
	v_mov_b32_e32 v119, 0
	v_mov_b32_e32 v120, 0
	v_mov_b32_e32 v121, 0
	v_mov_b32_e32 v122, 0
	v_mov_b32_e32 v123, 0
	v_mov_b32_e32 v124, 0
	v_mov_b32_e32 v125, 0
	v_mov_b32_e32 v126, 0
	v_mov_b32_e32 v127, 0
	v_mov_b32_e32 v128, 0
	v_mov_b32_e32 v129, 0
	s_waitcnt vmcnt(6)
	s_barrier
	ds_read_b128 v[130:133], v154 offset:16
	ds_read_b128 v[138:141], v156 offset:8208
	ds_read_b128 v[142:145], v156 offset:10256
	ds_read_b128 v[134:137], v154 offset:2064
	ds_read_b128 v[146:149], v158 offset:8208
	ds_read_b128 v[150:153], v158 offset:10256
	s_mov_b32 s59, 28
.Lhw_ffndown_loop:
	s_waitcnt vmcnt(0)
	s_barrier
	s_waitcnt lgkmcnt(0)
	v_mfma_f32_32x32x16_bf16 v[2:17], v[130:133], v[138:141], v[2:17]
	ds_read_b128 v[212:215], v155 offset:16
	s_add_u32 m0, s65, 0xc000
	v_mfma_f32_32x32x16_bf16 v[18:33], v[130:133], v[142:145], v[18:33]
	ds_read_b128 v[220:223], v157 offset:8208
	global_load_lds_dwordx4 v160, s[66:67]
	v_mfma_f32_32x32x16_bf16 v[34:49], v[134:137], v[138:141], v[34:49]
	ds_read_b128 v[224:227], v157 offset:10256
	s_add_u32 m0, s65, 0xd000
	v_mfma_f32_32x32x16_bf16 v[50:65], v[134:137], v[142:145], v[50:65]
	ds_read_b128 v[216:219], v155 offset:2064
	global_load_lds_dwordx4 v161, s[66:67]
	v_mfma_f32_32x32x16_bf16 v[66:81], v[130:133], v[146:149], v[66:81]
	ds_read_b128 v[228:231], v159 offset:8208
	s_add_u32 m0, s65, 0xe000
	v_mfma_f32_32x32x16_bf16 v[82:97], v[130:133], v[150:153], v[82:97]
	ds_read_b128 v[232:235], v159 offset:10256
	global_load_lds_dwordx4 v160, s[62:63]
	v_mfma_f32_32x32x16_bf16 v[98:113], v[134:137], v[146:149], v[98:113]
	s_add_u32 m0, s65, 0xf000
	v_mfma_f32_32x32x16_bf16 v[114:129], v[134:137], v[150:153], v[114:129]
	global_load_lds_dwordx4 v161, s[62:63]
	s_waitcnt lgkmcnt(4)
	v_mfma_f32_32x32x16_bf16 v[2:17], v[212:215], v[220:223], v[2:17]
	s_add_u32 m0, s65, 0x10000
	ds_read_b128 v[130:133], v154 offset:24592
	s_waitcnt lgkmcnt(4)
	v_mfma_f32_32x32x16_bf16 v[18:33], v[212:215], v[224:227], v[18:33]
	global_load_lds_dwordx4 v160, s[18:19]
	ds_read_b128 v[138:141], v156 offset:32784
	s_waitcnt lgkmcnt(4)
	v_mfma_f32_32x32x16_bf16 v[34:49], v[216:219], v[220:223], v[34:49]
	s_add_u32 m0, s65, 0x11000
	ds_read_b128 v[142:145], v156 offset:34832
	s_waitcnt lgkmcnt(5)
	v_mfma_f32_32x32x16_bf16 v[50:65], v[216:219], v[224:227], v[50:65]
	global_load_lds_dwordx4 v161, s[18:19]
	ds_read_b128 v[134:137], v154 offset:26640
	s_waitcnt lgkmcnt(5)
	v_mfma_f32_32x32x16_bf16 v[66:81], v[212:215], v[228:231], v[66:81]
	s_add_u32 s66, s66, 64
	s_addc_u32 s67, s67, 0
	ds_read_b128 v[146:149], v158 offset:32784
	s_waitcnt lgkmcnt(5)
	v_mfma_f32_32x32x16_bf16 v[82:97], v[212:215], v[232:235], v[82:97]
	s_add_u32 s62, s62, 64
	s_addc_u32 s63, s63, 0
	ds_read_b128 v[150:153], v158 offset:34832
	s_waitcnt lgkmcnt(7)
	v_mfma_f32_32x32x16_bf16 v[98:113], v[216:219], v[228:231], v[98:113]
	s_add_u32 s18, s18, 64
	s_addc_u32 s19, s19, 0
	s_waitcnt lgkmcnt(6)
	v_mfma_f32_32x32x16_bf16 v[114:129], v[216:219], v[232:235], v[114:129]
	s_waitcnt vmcnt(0)
	s_barrier
	s_waitcnt lgkmcnt(0)
	v_mfma_f32_32x32x16_bf16 v[2:17], v[130:133], v[138:141], v[2:17]
	ds_read_b128 v[212:215], v155 offset:24592
	s_add_u32 m0, s65, 0x0
	v_mfma_f32_32x32x16_bf16 v[18:33], v[130:133], v[142:145], v[18:33]
	ds_read_b128 v[220:223], v157 offset:32784
	global_load_lds_dwordx4 v160, s[66:67]
	v_mfma_f32_32x32x16_bf16 v[34:49], v[134:137], v[138:141], v[34:49]
	ds_read_b128 v[224:227], v157 offset:34832
	s_add_u32 m0, s65, 0x1000
	v_mfma_f32_32x32x16_bf16 v[50:65], v[134:137], v[142:145], v[50:65]
	ds_read_b128 v[216:219], v155 offset:26640
	global_load_lds_dwordx4 v161, s[66:67]
	v_mfma_f32_32x32x16_bf16 v[66:81], v[130:133], v[146:149], v[66:81]
	ds_read_b128 v[228:231], v159 offset:32784
	s_add_u32 m0, s65, 0x2000
	v_mfma_f32_32x32x16_bf16 v[82:97], v[130:133], v[150:153], v[82:97]
	ds_read_b128 v[232:235], v159 offset:34832
	global_load_lds_dwordx4 v160, s[62:63]
	v_mfma_f32_32x32x16_bf16 v[98:113], v[134:137], v[146:149], v[98:113]
	s_add_u32 m0, s65, 0x3000
	v_mfma_f32_32x32x16_bf16 v[114:129], v[134:137], v[150:153], v[114:129]
	global_load_lds_dwordx4 v161, s[62:63]
	s_waitcnt lgkmcnt(4)
	v_mfma_f32_32x32x16_bf16 v[2:17], v[212:215], v[220:223], v[2:17]
	s_add_u32 m0, s65, 0x4000
	ds_read_b128 v[130:133], v154 offset:49168
	s_waitcnt lgkmcnt(4)
	v_mfma_f32_32x32x16_bf16 v[18:33], v[212:215], v[224:227], v[18:33]
	global_load_lds_dwordx4 v160, s[18:19]
	ds_read_b128 v[138:141], v156 offset:57360
	s_waitcnt lgkmcnt(4)
	v_mfma_f32_32x32x16_bf16 v[34:49], v[216:219], v[220:223], v[34:49]
	s_add_u32 m0, s65, 0x5000
	ds_read_b128 v[142:145], v156 offset:59408
	s_waitcnt lgkmcnt(5)
	v_mfma_f32_32x32x16_bf16 v[50:65], v[216:219], v[224:227], v[50:65]
	global_load_lds_dwordx4 v161, s[18:19]
	ds_read_b128 v[134:137], v154 offset:51216
	s_waitcnt lgkmcnt(5)
	v_mfma_f32_32x32x16_bf16 v[66:81], v[212:215], v[228:231], v[66:81]
	s_add_u32 s66, s66, 64
	s_addc_u32 s67, s67, 0
	ds_read_b128 v[146:149], v158 offset:57360
	s_waitcnt lgkmcnt(5)
	v_mfma_f32_32x32x16_bf16 v[82:97], v[212:215], v[232:235], v[82:97]
	s_add_u32 s62, s62, 64
	s_addc_u32 s63, s63, 0
	ds_read_b128 v[150:153], v158 offset:59408
	s_waitcnt lgkmcnt(7)
	v_mfma_f32_32x32x16_bf16 v[98:113], v[216:219], v[228:231], v[98:113]
	s_add_u32 s18, s18, 64
	s_addc_u32 s19, s19, 0
	s_waitcnt lgkmcnt(6)
	v_mfma_f32_32x32x16_bf16 v[114:129], v[216:219], v[232:235], v[114:129]
	s_waitcnt vmcnt(0)
	s_barrier
	s_waitcnt lgkmcnt(0)
	v_mfma_f32_32x32x16_bf16 v[2:17], v[130:133], v[138:141], v[2:17]
	ds_read_b128 v[212:215], v155 offset:49168
	s_add_u32 m0, s65, 0x6000
	v_mfma_f32_32x32x16_bf16 v[18:33], v[130:133], v[142:145], v[18:33]
	ds_read_b128 v[220:223], v157 offset:57360
	global_load_lds_dwordx4 v160, s[66:67]
	v_mfma_f32_32x32x16_bf16 v[34:49], v[134:137], v[138:141], v[34:49]
	ds_read_b128 v[224:227], v157 offset:59408
	s_add_u32 m0, s65, 0x7000
	v_mfma_f32_32x32x16_bf16 v[50:65], v[134:137], v[142:145], v[50:65]
	ds_read_b128 v[216:219], v155 offset:51216
	global_load_lds_dwordx4 v161, s[66:67]
	v_mfma_f32_32x32x16_bf16 v[66:81], v[130:133], v[146:149], v[66:81]
	ds_read_b128 v[228:231], v159 offset:57360
	s_add_u32 m0, s65, 0x8000
	v_mfma_f32_32x32x16_bf16 v[82:97], v[130:133], v[150:153], v[82:97]
	ds_read_b128 v[232:235], v159 offset:59408
	global_load_lds_dwordx4 v160, s[62:63]
	v_mfma_f32_32x32x16_bf16 v[98:113], v[134:137], v[146:149], v[98:113]
	s_add_u32 m0, s65, 0x9000
	v_mfma_f32_32x32x16_bf16 v[114:129], v[134:137], v[150:153], v[114:129]
	global_load_lds_dwordx4 v161, s[62:63]
	s_waitcnt lgkmcnt(4)
	v_mfma_f32_32x32x16_bf16 v[2:17], v[212:215], v[220:223], v[2:17]
	s_add_u32 m0, s65, 0xa000
	ds_read_b128 v[130:133], v154 offset:16
	s_waitcnt lgkmcnt(4)
	v_mfma_f32_32x32x16_bf16 v[18:33], v[212:215], v[224:227], v[18:33]
	global_load_lds_dwordx4 v160, s[18:19]
	ds_read_b128 v[138:141], v156 offset:8208
	s_waitcnt lgkmcnt(4)
	v_mfma_f32_32x32x16_bf16 v[34:49], v[216:219], v[220:223], v[34:49]
	s_add_u32 m0, s65, 0xb000
	ds_read_b128 v[142:145], v156 offset:10256
	s_waitcnt lgkmcnt(5)
	v_mfma_f32_32x32x16_bf16 v[50:65], v[216:219], v[224:227], v[50:65]
	global_load_lds_dwordx4 v161, s[18:19]
	ds_read_b128 v[134:137], v154 offset:2064
	s_waitcnt lgkmcnt(5)
	v_mfma_f32_32x32x16_bf16 v[66:81], v[212:215], v[228:231], v[66:81]
	s_add_u32 s66, s66, 64
	s_addc_u32 s67, s67, 0
	ds_read_b128 v[146:149], v158 offset:8208
	s_waitcnt lgkmcnt(5)
	v_mfma_f32_32x32x16_bf16 v[82:97], v[212:215], v[232:235], v[82:97]
	s_add_u32 s62, s62, 64
	s_addc_u32 s63, s63, 0
	ds_read_b128 v[150:153], v158 offset:10256
	s_waitcnt lgkmcnt(7)
	v_mfma_f32_32x32x16_bf16 v[98:113], v[216:219], v[228:231], v[98:113]
	s_add_u32 s18, s18, 64
	s_addc_u32 s19, s19, 0
	s_waitcnt lgkmcnt(6)
	v_mfma_f32_32x32x16_bf16 v[114:129], v[216:219], v[232:235], v[114:129]
	s_sub_u32 s59, s59, 1
	s_cmp_lg_u32 s59, 0
	s_cbranch_scc1 .Lhw_ffndown_loop
	s_waitcnt vmcnt(0)
	s_barrier
	s_waitcnt lgkmcnt(0)
	v_mfma_f32_32x32x16_bf16 v[2:17], v[130:133], v[138:141], v[2:17]
	ds_read_b128 v[212:215], v155 offset:16
	s_add_u32 m0, s65, 0xc000
	v_mfma_f32_32x32x16_bf16 v[18:33], v[130:133], v[142:145], v[18:33]
	ds_read_b128 v[220:223], v157 offset:8208
	global_load_lds_dwordx4 v160, s[66:67]
	v_mfma_f32_32x32x16_bf16 v[34:49], v[134:137], v[138:141], v[34:49]
	ds_read_b128 v[224:227], v157 offset:10256
	s_add_u32 m0, s65, 0xd000
	v_mfma_f32_32x32x16_bf16 v[50:65], v[134:137], v[142:145], v[50:65]
	ds_read_b128 v[216:219], v155 offset:2064
	global_load_lds_dwordx4 v161, s[66:67]
	v_mfma_f32_32x32x16_bf16 v[66:81], v[130:133], v[146:149], v[66:81]
	ds_read_b128 v[228:231], v159 offset:8208
	s_add_u32 m0, s65, 0xe000
	v_mfma_f32_32x32x16_bf16 v[82:97], v[130:133], v[150:153], v[82:97]
	ds_read_b128 v[232:235], v159 offset:10256
	global_load_lds_dwordx4 v160, s[62:63]
	v_mfma_f32_32x32x16_bf16 v[98:113], v[134:137], v[146:149], v[98:113]
	s_add_u32 m0, s65, 0xf000
	v_mfma_f32_32x32x16_bf16 v[114:129], v[134:137], v[150:153], v[114:129]
	global_load_lds_dwordx4 v161, s[62:63]
	s_waitcnt lgkmcnt(4)
	v_mfma_f32_32x32x16_bf16 v[2:17], v[212:215], v[220:223], v[2:17]
	s_add_u32 m0, s65, 0x10000
	ds_read_b128 v[130:133], v154 offset:24592
	s_waitcnt lgkmcnt(4)
	v_mfma_f32_32x32x16_bf16 v[18:33], v[212:215], v[224:227], v[18:33]
	global_load_lds_dwordx4 v160, s[18:19]
	ds_read_b128 v[138:141], v156 offset:32784
	s_waitcnt lgkmcnt(4)
	v_mfma_f32_32x32x16_bf16 v[34:49], v[216:219], v[220:223], v[34:49]
	s_add_u32 m0, s65, 0x11000
	ds_read_b128 v[142:145], v156 offset:34832
	s_waitcnt lgkmcnt(5)
	v_mfma_f32_32x32x16_bf16 v[50:65], v[216:219], v[224:227], v[50:65]
	global_load_lds_dwordx4 v161, s[18:19]
	ds_read_b128 v[134:137], v154 offset:26640
	s_waitcnt lgkmcnt(5)
	v_mfma_f32_32x32x16_bf16 v[66:81], v[212:215], v[228:231], v[66:81]
	s_add_u32 s66, s66, 64
	s_addc_u32 s67, s67, 0
	ds_read_b128 v[146:149], v158 offset:32784
	s_waitcnt lgkmcnt(5)
	v_mfma_f32_32x32x16_bf16 v[82:97], v[212:215], v[232:235], v[82:97]
	s_add_u32 s62, s62, 64
	s_addc_u32 s63, s63, 0
	ds_read_b128 v[150:153], v158 offset:34832
	s_waitcnt lgkmcnt(7)
	v_mfma_f32_32x32x16_bf16 v[98:113], v[216:219], v[228:231], v[98:113]
	s_add_u32 s18, s18, 64
	s_addc_u32 s19, s19, 0
	s_waitcnt lgkmcnt(6)
	v_mfma_f32_32x32x16_bf16 v[114:129], v[216:219], v[232:235], v[114:129]
	s_waitcnt vmcnt(0)
	s_barrier
	s_waitcnt lgkmcnt(0)
	v_mfma_f32_32x32x16_bf16 v[2:17], v[130:133], v[138:141], v[2:17]
	ds_read_b128 v[212:215], v155 offset:24592
	s_add_u32 m0, s65, 0x0
	v_mfma_f32_32x32x16_bf16 v[18:33], v[130:133], v[142:145], v[18:33]
	ds_read_b128 v[220:223], v157 offset:32784
	global_load_lds_dwordx4 v160, s[66:67]
	v_mfma_f32_32x32x16_bf16 v[34:49], v[134:137], v[138:141], v[34:49]
	ds_read_b128 v[224:227], v157 offset:34832
	s_add_u32 m0, s65, 0x1000
	v_mfma_f32_32x32x16_bf16 v[50:65], v[134:137], v[142:145], v[50:65]
	ds_read_b128 v[216:219], v155 offset:26640
	global_load_lds_dwordx4 v161, s[66:67]
	v_mfma_f32_32x32x16_bf16 v[66:81], v[130:133], v[146:149], v[66:81]
	ds_read_b128 v[228:231], v159 offset:32784
	s_add_u32 m0, s65, 0x2000
	v_mfma_f32_32x32x16_bf16 v[82:97], v[130:133], v[150:153], v[82:97]
	ds_read_b128 v[232:235], v159 offset:34832
	global_load_lds_dwordx4 v160, s[62:63]
	v_mfma_f32_32x32x16_bf16 v[98:113], v[134:137], v[146:149], v[98:113]
	s_add_u32 m0, s65, 0x3000
	v_mfma_f32_32x32x16_bf16 v[114:129], v[134:137], v[150:153], v[114:129]
	global_load_lds_dwordx4 v161, s[62:63]
	s_waitcnt lgkmcnt(4)
	v_mfma_f32_32x32x16_bf16 v[2:17], v[212:215], v[220:223], v[2:17]
	s_add_u32 m0, s65, 0x4000
	ds_read_b128 v[130:133], v154 offset:49168
	s_waitcnt lgkmcnt(4)
	v_mfma_f32_32x32x16_bf16 v[18:33], v[212:215], v[224:227], v[18:33]
	global_load_lds_dwordx4 v160, s[18:19]
	ds_read_b128 v[138:141], v156 offset:57360
	s_waitcnt lgkmcnt(4)
	v_mfma_f32_32x32x16_bf16 v[34:49], v[216:219], v[220:223], v[34:49]
	s_add_u32 m0, s65, 0x5000
	ds_read_b128 v[142:145], v156 offset:59408
	s_waitcnt lgkmcnt(5)
	v_mfma_f32_32x32x16_bf16 v[50:65], v[216:219], v[224:227], v[50:65]
	global_load_lds_dwordx4 v161, s[18:19]
	ds_read_b128 v[134:137], v154 offset:51216
	s_waitcnt lgkmcnt(5)
	v_mfma_f32_32x32x16_bf16 v[66:81], v[212:215], v[228:231], v[66:81]
	s_add_u32 s66, s66, 64
	s_addc_u32 s67, s67, 0
	ds_read_b128 v[146:149], v158 offset:57360
	s_waitcnt lgkmcnt(5)
	v_mfma_f32_32x32x16_bf16 v[82:97], v[212:215], v[232:235], v[82:97]
	s_add_u32 s62, s62, 64
	s_addc_u32 s63, s63, 0
	ds_read_b128 v[150:153], v158 offset:59408
	s_waitcnt lgkmcnt(7)
	v_mfma_f32_32x32x16_bf16 v[98:113], v[216:219], v[228:231], v[98:113]
	s_add_u32 s18, s18, 64
	s_addc_u32 s19, s19, 0
	s_waitcnt lgkmcnt(6)
	v_mfma_f32_32x32x16_bf16 v[114:129], v[216:219], v[232:235], v[114:129]
	s_waitcnt vmcnt(0)
	s_barrier
	s_waitcnt lgkmcnt(0)
	v_mfma_f32_32x32x16_bf16 v[2:17], v[130:133], v[138:141], v[2:17]
	ds_read_b128 v[212:215], v155 offset:49168
	v_mfma_f32_32x32x16_bf16 v[18:33], v[130:133], v[142:145], v[18:33]
	ds_read_b128 v[220:223], v157 offset:57360
	v_mfma_f32_32x32x16_bf16 v[34:49], v[134:137], v[138:141], v[34:49]
	ds_read_b128 v[224:227], v157 offset:59408
	v_mfma_f32_32x32x16_bf16 v[50:65], v[134:137], v[142:145], v[50:65]
	ds_read_b128 v[216:219], v155 offset:51216
	v_mfma_f32_32x32x16_bf16 v[66:81], v[130:133], v[146:149], v[66:81]
	ds_read_b128 v[228:231], v159 offset:57360
	v_mfma_f32_32x32x16_bf16 v[82:97], v[130:133], v[150:153], v[82:97]
	ds_read_b128 v[232:235], v159 offset:59408
	v_mfma_f32_32x32x16_bf16 v[98:113], v[134:137], v[146:149], v[98:113]
	v_mfma_f32_32x32x16_bf16 v[114:129], v[134:137], v[150:153], v[114:129]
	s_waitcnt lgkmcnt(4)
	v_mfma_f32_32x32x16_bf16 v[2:17], v[212:215], v[220:223], v[2:17]
	ds_read_b128 v[130:133], v154 offset:16
	s_waitcnt lgkmcnt(4)
	v_mfma_f32_32x32x16_bf16 v[18:33], v[212:215], v[224:227], v[18:33]
	ds_read_b128 v[138:141], v156 offset:8208
	s_waitcnt lgkmcnt(4)
	v_mfma_f32_32x32x16_bf16 v[34:49], v[216:219], v[220:223], v[34:49]
	ds_read_b128 v[142:145], v156 offset:10256
	s_waitcnt lgkmcnt(5)
	v_mfma_f32_32x32x16_bf16 v[50:65], v[216:219], v[224:227], v[50:65]
	ds_read_b128 v[134:137], v154 offset:2064
	s_waitcnt lgkmcnt(5)
	v_mfma_f32_32x32x16_bf16 v[66:81], v[212:215], v[228:231], v[66:81]
	ds_read_b128 v[146:149], v158 offset:8208
	s_waitcnt lgkmcnt(5)
	v_mfma_f32_32x32x16_bf16 v[82:97], v[212:215], v[232:235], v[82:97]
	ds_read_b128 v[150:153], v158 offset:10256
	s_waitcnt lgkmcnt(7)
	v_mfma_f32_32x32x16_bf16 v[98:113], v[216:219], v[228:231], v[98:113]
	s_waitcnt lgkmcnt(6)
	v_mfma_f32_32x32x16_bf16 v[114:129], v[216:219], v[232:235], v[114:129]
	s_waitcnt lgkmcnt(0)
	v_mfma_f32_32x32x16_bf16 v[2:17], v[130:133], v[138:141], v[2:17]
	ds_read_b128 v[212:215], v155 offset:16
	v_mfma_f32_32x32x16_bf16 v[18:33], v[130:133], v[142:145], v[18:33]
	ds_read_b128 v[220:223], v157 offset:8208
	v_mfma_f32_32x32x16_bf16 v[34:49], v[134:137], v[138:141], v[34:49]
	ds_read_b128 v[224:227], v157 offset:10256
	v_mfma_f32_32x32x16_bf16 v[50:65], v[134:137], v[142:145], v[50:65]
	ds_read_b128 v[216:219], v155 offset:2064
	v_mfma_f32_32x32x16_bf16 v[66:81], v[130:133], v[146:149], v[66:81]
	ds_read_b128 v[228:231], v159 offset:8208
	v_mfma_f32_32x32x16_bf16 v[82:97], v[130:133], v[150:153], v[82:97]
	ds_read_b128 v[232:235], v159 offset:10256
	v_mfma_f32_32x32x16_bf16 v[98:113], v[134:137], v[146:149], v[98:113]
	v_mfma_f32_32x32x16_bf16 v[114:129], v[134:137], v[150:153], v[114:129]
	s_waitcnt lgkmcnt(4)
	v_mfma_f32_32x32x16_bf16 v[2:17], v[212:215], v[220:223], v[2:17]
	s_waitcnt lgkmcnt(3)
	v_mfma_f32_32x32x16_bf16 v[18:33], v[212:215], v[224:227], v[18:33]
	s_waitcnt lgkmcnt(2)
	v_mfma_f32_32x32x16_bf16 v[34:49], v[216:219], v[220:223], v[34:49]
	s_waitcnt lgkmcnt(2)
	v_mfma_f32_32x32x16_bf16 v[50:65], v[216:219], v[224:227], v[50:65]
	s_waitcnt lgkmcnt(1)
	v_mfma_f32_32x32x16_bf16 v[66:81], v[212:215], v[228:231], v[66:81]
	s_waitcnt lgkmcnt(0)
	v_mfma_f32_32x32x16_bf16 v[82:97], v[212:215], v[232:235], v[82:97]
	s_waitcnt lgkmcnt(1)
	v_mfma_f32_32x32x16_bf16 v[98:113], v[216:219], v[228:231], v[98:113]
	s_waitcnt lgkmcnt(0)
	v_mfma_f32_32x32x16_bf16 v[114:129], v[216:219], v[232:235], v[114:129]
	s_nop 7
	s_nop 7
	s_sub_i32 s2, s6, 0x1000
	s_ashr_i32 s2, s2, 11
	s_add_i32 s2, s2, 1
	s_max_i32 s2, s2, 0
	v_readlane_b32 s17, v246, 28
	s_nop 0
	s_add_i32 s2, s2, s17
	s_mul_i32 s2, s2, 0x9000
	s_lshl_b32 s17, s15, 2
	s_add_u32 s2, s2, s17
	s_add_u32 s60, s12, s2
	s_addc_u32 s61, s13, 0
	s_lshr_b32 s2, s15, 7
	s_mul_i32 s2, s2, 0x18000
	s_lshl_b32 s20, s6, 2
	s_add_u32 s2, s2, s20
	s_add_u32 s10, s44, s2
	s_addc_u32 s11, s45, 0
	s_lshl_b32 s2, s6, 12
	s_add_u32 s2, s2, s17
	s_add_u32 s48, s40, s2
	s_addc_u32 s49, s41, 0
	global_load_dword v175, v166, s[60:61]
	global_load_dword v176, v166, s[60:61] offset:128
	global_load_dword v130, v162, s[48:49]
	global_load_dword v212, v162, s[48:49] offset:128
	global_load_dword v131, v163, s[48:49]
	global_load_dword v213, v163, s[48:49] offset:128
	global_load_dword v132, v164, s[48:49]
	global_load_dword v214, v164, s[48:49] offset:128
	global_load_dword v133, v165, s[48:49]
	global_load_dword v215, v165, s[48:49] offset:128
	s_add_u32 s48, s48, 0x8000
	s_addc_u32 s49, s49, 0
	global_load_dword v134, v162, s[48:49]
	global_load_dword v216, v162, s[48:49] offset:128
	global_load_dword v135, v163, s[48:49]
	global_load_dword v217, v163, s[48:49] offset:128
	global_load_dword v136, v164, s[48:49]
	global_load_dword v218, v164, s[48:49] offset:128
	global_load_dword v137, v165, s[48:49]
	global_load_dword v219, v165, s[48:49] offset:128
	s_add_u32 s48, s48, 0x8000
	s_addc_u32 s49, s49, 0
	global_load_dword v138, v162, s[48:49]
	global_load_dword v220, v162, s[48:49] offset:128
	global_load_dword v139, v163, s[48:49]
	global_load_dword v221, v163, s[48:49] offset:128
	global_load_dword v140, v164, s[48:49]
	global_load_dword v222, v164, s[48:49] offset:128
	global_load_dword v141, v165, s[48:49]
	global_load_dword v223, v165, s[48:49] offset:128
	s_add_u32 s48, s48, 0x8000
	s_addc_u32 s49, s49, 0
	global_load_dword v142, v162, s[48:49]
	global_load_dword v224, v162, s[48:49] offset:128
	global_load_dword v143, v163, s[48:49]
	global_load_dword v225, v163, s[48:49] offset:128
	global_load_dword v144, v164, s[48:49]
	global_load_dword v226, v164, s[48:49] offset:128
	global_load_dword v145, v165, s[48:49]
	global_load_dword v227, v165, s[48:49] offset:128
	s_sub_u32 s48, s48, 0x18000
	s_subb_u32 s49, s49, 0
	s_waitcnt vmcnt(32)
	v_mul_f32_e32 v175, 0.5, v175
	v_mul_f32_e32 v176, 0.5, v176
	s_waitcnt vmcnt(30)
	v_fmac_f32_e32 v130, v2, v175
	v_fmac_f32_e32 v212, v18, v176
	global_store_dword v162, v130, s[48:49]
	global_store_dword v162, v212, s[48:49] offset:128
	s_waitcnt vmcnt(30)
	v_fmac_f32_e32 v131, v3, v175
	v_fmac_f32_e32 v213, v19, v176
	global_store_dword v163, v131, s[48:49]
	global_store_dword v163, v213, s[48:49] offset:128
	s_waitcnt vmcnt(30)
	v_fmac_f32_e32 v132, v4, v175
	v_fmac_f32_e32 v214, v20, v176
	global_store_dword v164, v132, s[48:49]
	global_store_dword v164, v214, s[48:49] offset:128
	s_waitcnt vmcnt(30)
	v_fmac_f32_e32 v133, v5, v175
	v_fmac_f32_e32 v215, v21, v176
	global_store_dword v165, v133, s[48:49]
	global_store_dword v165, v215, s[48:49] offset:128
	s_add_u32 s48, s48, 0x8000
	s_addc_u32 s49, s49, 0
	s_waitcnt vmcnt(30)
	v_fmac_f32_e32 v134, v6, v175
	v_fmac_f32_e32 v216, v22, v176
	global_store_dword v162, v134, s[48:49]
	global_store_dword v162, v216, s[48:49] offset:128
	s_waitcnt vmcnt(30)
	v_fmac_f32_e32 v135, v7, v175
	v_fmac_f32_e32 v217, v23, v176
	global_store_dword v163, v135, s[48:49]
	global_store_dword v163, v217, s[48:49] offset:128
	s_waitcnt vmcnt(30)
	v_fmac_f32_e32 v136, v8, v175
	v_fmac_f32_e32 v218, v24, v176
	global_store_dword v164, v136, s[48:49]
	global_store_dword v164, v218, s[48:49] offset:128
	s_waitcnt vmcnt(30)
	v_fmac_f32_e32 v137, v9, v175
	v_fmac_f32_e32 v219, v25, v176
	global_store_dword v165, v137, s[48:49]
	global_store_dword v165, v219, s[48:49] offset:128
	s_add_u32 s48, s48, 0x8000
	s_addc_u32 s49, s49, 0
	s_waitcnt vmcnt(30)
	v_fmac_f32_e32 v138, v10, v175
	v_fmac_f32_e32 v220, v26, v176
	global_store_dword v162, v138, s[48:49]
	global_store_dword v162, v220, s[48:49] offset:128
	s_waitcnt vmcnt(30)
	v_fmac_f32_e32 v139, v11, v175
	v_fmac_f32_e32 v221, v27, v176
	global_store_dword v163, v139, s[48:49]
	global_store_dword v163, v221, s[48:49] offset:128
	s_waitcnt vmcnt(30)
	v_fmac_f32_e32 v140, v12, v175
	v_fmac_f32_e32 v222, v28, v176
	global_store_dword v164, v140, s[48:49]
	global_store_dword v164, v222, s[48:49] offset:128
	s_waitcnt vmcnt(30)
	v_fmac_f32_e32 v141, v13, v175
	v_fmac_f32_e32 v223, v29, v176
	global_store_dword v165, v141, s[48:49]
	global_store_dword v165, v223, s[48:49] offset:128
	s_add_u32 s48, s48, 0x8000
	s_addc_u32 s49, s49, 0
	s_waitcnt vmcnt(30)
	v_fmac_f32_e32 v142, v14, v175
	v_fmac_f32_e32 v224, v30, v176
	global_store_dword v162, v142, s[48:49]
	global_store_dword v162, v224, s[48:49] offset:128
	s_waitcnt vmcnt(30)
	v_fmac_f32_e32 v143, v15, v175
	v_fmac_f32_e32 v225, v31, v176
	global_store_dword v163, v143, s[48:49]
	global_store_dword v163, v225, s[48:49] offset:128
	s_waitcnt vmcnt(30)
	v_fmac_f32_e32 v144, v16, v175
	v_fmac_f32_e32 v226, v32, v176
	global_store_dword v164, v144, s[48:49]
	global_store_dword v164, v226, s[48:49] offset:128
	s_waitcnt vmcnt(30)
	v_fmac_f32_e32 v145, v17, v175
	v_fmac_f32_e32 v227, v33, v176
	global_store_dword v165, v145, s[48:49]
	global_store_dword v165, v227, s[48:49] offset:128
	s_sub_u32 s48, s48, 0x18000
	s_subb_u32 s49, s49, 0
	v_mul_f32_e32 v130, v130, v130
	v_fmac_f32_e32 v130, v212, v212
	v_mul_f32_e32 v131, v131, v131
	v_fmac_f32_e32 v131, v213, v213
	v_mul_f32_e32 v132, v132, v132
	v_fmac_f32_e32 v132, v214, v214
	v_mul_f32_e32 v133, v133, v133
	v_fmac_f32_e32 v133, v215, v215
	v_mul_f32_e32 v134, v134, v134
	v_fmac_f32_e32 v134, v216, v216
	v_mul_f32_e32 v135, v135, v135
	v_fmac_f32_e32 v135, v217, v217
	v_mul_f32_e32 v136, v136, v136
	v_fmac_f32_e32 v136, v218, v218
	v_mul_f32_e32 v137, v137, v137
	v_fmac_f32_e32 v137, v219, v219
	v_mul_f32_e32 v138, v138, v138
	v_fmac_f32_e32 v138, v220, v220
	v_mul_f32_e32 v139, v139, v139
	v_fmac_f32_e32 v139, v221, v221
	v_mul_f32_e32 v140, v140, v140
	v_fmac_f32_e32 v140, v222, v222
	v_mul_f32_e32 v141, v141, v141
	v_fmac_f32_e32 v141, v223, v223
	v_mul_f32_e32 v142, v142, v142
	v_fmac_f32_e32 v142, v224, v224
	v_mul_f32_e32 v143, v143, v143
	v_fmac_f32_e32 v143, v225, v225
	v_mul_f32_e32 v144, v144, v144
	v_fmac_f32_e32 v144, v226, v226
	v_mul_f32_e32 v145, v145, v145
	v_fmac_f32_e32 v145, v227, v227
	s_waitcnt lgkmcnt(0)
	ds_bpermute_b32 v212, v168, v130
	ds_bpermute_b32 v213, v168, v131
	ds_bpermute_b32 v214, v168, v132
	ds_bpermute_b32 v215, v168, v133
	ds_bpermute_b32 v216, v168, v134
	ds_bpermute_b32 v217, v168, v135
	ds_bpermute_b32 v218, v168, v136
	ds_bpermute_b32 v219, v168, v137
	s_waitcnt lgkmcnt(7)
	v_add_f32_e32 v130, v130, v212
	s_waitcnt lgkmcnt(6)
	v_add_f32_e32 v131, v131, v213
	s_waitcnt lgkmcnt(5)
	v_add_f32_e32 v132, v132, v214
	s_waitcnt lgkmcnt(4)
	v_add_f32_e32 v133, v133, v215
	s_waitcnt lgkmcnt(3)
	v_add_f32_e32 v134, v134, v216
	s_waitcnt lgkmcnt(2)
	v_add_f32_e32 v135, v135, v217
	s_waitcnt lgkmcnt(1)
	v_add_f32_e32 v136, v136, v218
	s_waitcnt lgkmcnt(0)
	v_add_f32_e32 v137, v137, v219
	ds_bpermute_b32 v212, v169, v130
	ds_bpermute_b32 v213, v169, v131
	ds_bpermute_b32 v214, v169, v132
	ds_bpermute_b32 v215, v169, v133
	ds_bpermute_b32 v216, v169, v134
	ds_bpermute_b32 v217, v169, v135
	ds_bpermute_b32 v218, v169, v136
	ds_bpermute_b32 v219, v169, v137
	s_waitcnt lgkmcnt(7)
	v_add_f32_e32 v130, v130, v212
	s_waitcnt lgkmcnt(6)
	v_add_f32_e32 v131, v131, v213
	s_waitcnt lgkmcnt(5)
	v_add_f32_e32 v132, v132, v214
	s_waitcnt lgkmcnt(4)
	v_add_f32_e32 v133, v133, v215
	s_waitcnt lgkmcnt(3)
	v_add_f32_e32 v134, v134, v216
	s_waitcnt lgkmcnt(2)
	v_add_f32_e32 v135, v135, v217
	s_waitcnt lgkmcnt(1)
	v_add_f32_e32 v136, v136, v218
	s_waitcnt lgkmcnt(0)
	v_add_f32_e32 v137, v137, v219
	ds_bpermute_b32 v212, v171, v130
	ds_bpermute_b32 v213, v171, v131
	ds_bpermute_b32 v214, v171, v132
	ds_bpermute_b32 v215, v171, v133
	ds_bpermute_b32 v216, v171, v134
	ds_bpermute_b32 v217, v171, v135
	ds_bpermute_b32 v218, v171, v136
	ds_bpermute_b32 v219, v171, v137
	s_waitcnt lgkmcnt(7)
	v_add_f32_e32 v130, v130, v212
	s_waitcnt lgkmcnt(6)
	v_add_f32_e32 v131, v131, v213
	s_waitcnt lgkmcnt(5)
	v_add_f32_e32 v132, v132, v214
	s_waitcnt lgkmcnt(4)
	v_add_f32_e32 v133, v133, v215
	s_waitcnt lgkmcnt(3)
	v_add_f32_e32 v134, v134, v216
	s_waitcnt lgkmcnt(2)
	v_add_f32_e32 v135, v135, v217
	s_waitcnt lgkmcnt(1)
	v_add_f32_e32 v136, v136, v218
	s_waitcnt lgkmcnt(0)
	v_add_f32_e32 v137, v137, v219
	ds_bpermute_b32 v212, v172, v130
	ds_bpermute_b32 v213, v172, v131
	ds_bpermute_b32 v214, v172, v132
	ds_bpermute_b32 v215, v172, v133
	ds_bpermute_b32 v216, v172, v134
	ds_bpermute_b32 v217, v172, v135
	ds_bpermute_b32 v218, v172, v136
	ds_bpermute_b32 v219, v172, v137
	s_waitcnt lgkmcnt(7)
	v_add_f32_e32 v130, v130, v212
	s_waitcnt lgkmcnt(6)
	v_add_f32_e32 v131, v131, v213
	s_waitcnt lgkmcnt(5)
	v_add_f32_e32 v132, v132, v214
	s_waitcnt lgkmcnt(4)
	v_add_f32_e32 v133, v133, v215
	s_waitcnt lgkmcnt(3)
	v_add_f32_e32 v134, v134, v216
	s_waitcnt lgkmcnt(2)
	v_add_f32_e32 v135, v135, v217
	s_waitcnt lgkmcnt(1)
	v_add_f32_e32 v136, v136, v218
	s_waitcnt lgkmcnt(0)
	v_add_f32_e32 v137, v137, v219
	ds_bpermute_b32 v212, v173, v130
	ds_bpermute_b32 v213, v173, v131
	ds_bpermute_b32 v214, v173, v132
	ds_bpermute_b32 v215, v173, v133
	ds_bpermute_b32 v216, v173, v134
	ds_bpermute_b32 v217, v173, v135
	ds_bpermute_b32 v218, v173, v136
	ds_bpermute_b32 v219, v173, v137
	s_waitcnt lgkmcnt(7)
	v_add_f32_e32 v130, v130, v212
	s_waitcnt lgkmcnt(6)
	v_add_f32_e32 v131, v131, v213
	s_waitcnt lgkmcnt(5)
	v_add_f32_e32 v132, v132, v214
	s_waitcnt lgkmcnt(4)
	v_add_f32_e32 v133, v133, v215
	s_waitcnt lgkmcnt(3)
	v_add_f32_e32 v134, v134, v216
	s_waitcnt lgkmcnt(2)
	v_add_f32_e32 v135, v135, v217
	s_waitcnt lgkmcnt(1)
	v_add_f32_e32 v136, v136, v218
	s_waitcnt lgkmcnt(0)
	v_add_f32_e32 v137, v137, v219
	ds_bpermute_b32 v220, v168, v138
	ds_bpermute_b32 v221, v168, v139
	ds_bpermute_b32 v222, v168, v140
	ds_bpermute_b32 v223, v168, v141
	ds_bpermute_b32 v224, v168, v142
	ds_bpermute_b32 v225, v168, v143
	ds_bpermute_b32 v226, v168, v144
	ds_bpermute_b32 v227, v168, v145
	s_waitcnt lgkmcnt(7)
	v_add_f32_e32 v138, v138, v220
	s_waitcnt lgkmcnt(6)
	v_add_f32_e32 v139, v139, v221
	s_waitcnt lgkmcnt(5)
	v_add_f32_e32 v140, v140, v222
	s_waitcnt lgkmcnt(4)
	v_add_f32_e32 v141, v141, v223
	s_waitcnt lgkmcnt(3)
	v_add_f32_e32 v142, v142, v224
	s_waitcnt lgkmcnt(2)
	v_add_f32_e32 v143, v143, v225
	s_waitcnt lgkmcnt(1)
	v_add_f32_e32 v144, v144, v226
	s_waitcnt lgkmcnt(0)
	v_add_f32_e32 v145, v145, v227
	ds_bpermute_b32 v220, v169, v138
	ds_bpermute_b32 v221, v169, v139
	ds_bpermute_b32 v222, v169, v140
	ds_bpermute_b32 v223, v169, v141
	ds_bpermute_b32 v224, v169, v142
	ds_bpermute_b32 v225, v169, v143
	ds_bpermute_b32 v226, v169, v144
	ds_bpermute_b32 v227, v169, v145
	s_waitcnt lgkmcnt(7)
	v_add_f32_e32 v138, v138, v220
	s_waitcnt lgkmcnt(6)
	v_add_f32_e32 v139, v139, v221
	s_waitcnt lgkmcnt(5)
	v_add_f32_e32 v140, v140, v222
	s_waitcnt lgkmcnt(4)
	v_add_f32_e32 v141, v141, v223
	s_waitcnt lgkmcnt(3)
	v_add_f32_e32 v142, v142, v224
	s_waitcnt lgkmcnt(2)
	v_add_f32_e32 v143, v143, v225
	s_waitcnt lgkmcnt(1)
	v_add_f32_e32 v144, v144, v226
	s_waitcnt lgkmcnt(0)
	v_add_f32_e32 v145, v145, v227
	ds_bpermute_b32 v220, v171, v138
	ds_bpermute_b32 v221, v171, v139
	ds_bpermute_b32 v222, v171, v140
	ds_bpermute_b32 v223, v171, v141
	ds_bpermute_b32 v224, v171, v142
	ds_bpermute_b32 v225, v171, v143
	ds_bpermute_b32 v226, v171, v144
	ds_bpermute_b32 v227, v171, v145
	s_waitcnt lgkmcnt(7)
	v_add_f32_e32 v138, v138, v220
	s_waitcnt lgkmcnt(6)
	v_add_f32_e32 v139, v139, v221
	s_waitcnt lgkmcnt(5)
	v_add_f32_e32 v140, v140, v222
	s_waitcnt lgkmcnt(4)
	v_add_f32_e32 v141, v141, v223
	s_waitcnt lgkmcnt(3)
	v_add_f32_e32 v142, v142, v224
	s_waitcnt lgkmcnt(2)
	v_add_f32_e32 v143, v143, v225
	s_waitcnt lgkmcnt(1)
	v_add_f32_e32 v144, v144, v226
	s_waitcnt lgkmcnt(0)
	v_add_f32_e32 v145, v145, v227
	ds_bpermute_b32 v220, v172, v138
	ds_bpermute_b32 v221, v172, v139
	ds_bpermute_b32 v222, v172, v140
	ds_bpermute_b32 v223, v172, v141
	ds_bpermute_b32 v224, v172, v142
	ds_bpermute_b32 v225, v172, v143
	ds_bpermute_b32 v226, v172, v144
	ds_bpermute_b32 v227, v172, v145
	s_waitcnt lgkmcnt(7)
	v_add_f32_e32 v138, v138, v220
	s_waitcnt lgkmcnt(6)
	v_add_f32_e32 v139, v139, v221
	s_waitcnt lgkmcnt(5)
	v_add_f32_e32 v140, v140, v222
	s_waitcnt lgkmcnt(4)
	v_add_f32_e32 v141, v141, v223
	s_waitcnt lgkmcnt(3)
	v_add_f32_e32 v142, v142, v224
	s_waitcnt lgkmcnt(2)
	v_add_f32_e32 v143, v143, v225
	s_waitcnt lgkmcnt(1)
	v_add_f32_e32 v144, v144, v226
	s_waitcnt lgkmcnt(0)
	v_add_f32_e32 v145, v145, v227
	ds_bpermute_b32 v220, v173, v138
	ds_bpermute_b32 v221, v173, v139
	ds_bpermute_b32 v222, v173, v140
	ds_bpermute_b32 v223, v173, v141
	ds_bpermute_b32 v224, v173, v142
	ds_bpermute_b32 v225, v173, v143
	ds_bpermute_b32 v226, v173, v144
	ds_bpermute_b32 v227, v173, v145
	s_waitcnt lgkmcnt(7)
	v_add_f32_e32 v138, v138, v220
	s_waitcnt lgkmcnt(6)
	v_add_f32_e32 v139, v139, v221
	s_waitcnt lgkmcnt(5)
	v_add_f32_e32 v140, v140, v222
	s_waitcnt lgkmcnt(4)
	v_add_f32_e32 v141, v141, v223
	s_waitcnt lgkmcnt(3)
	v_add_f32_e32 v142, v142, v224
	s_waitcnt lgkmcnt(2)
	v_add_f32_e32 v143, v143, v225
	s_waitcnt lgkmcnt(1)
	v_add_f32_e32 v144, v144, v226
	s_waitcnt lgkmcnt(0)
	v_add_f32_e32 v145, v145, v227
	v_cmp_eq_u32_e32 vcc, 0, v174
	s_and_saveexec_b64 s[58:59], vcc
	global_store_dword v167, v130, s[10:11]
	global_store_dword v167, v131, s[10:11] offset:4
	global_store_dword v167, v132, s[10:11] offset:8
	global_store_dword v167, v133, s[10:11] offset:12
	global_store_dword v167, v134, s[10:11] offset:32
	global_store_dword v167, v135, s[10:11] offset:36
	global_store_dword v167, v136, s[10:11] offset:40
	global_store_dword v167, v137, s[10:11] offset:44
	global_store_dword v167, v138, s[10:11] offset:64
	global_store_dword v167, v139, s[10:11] offset:68
	global_store_dword v167, v140, s[10:11] offset:72
	global_store_dword v167, v141, s[10:11] offset:76
	global_store_dword v167, v142, s[10:11] offset:96
	global_store_dword v167, v143, s[10:11] offset:100
	global_store_dword v167, v144, s[10:11] offset:104
	global_store_dword v167, v145, s[10:11] offset:108
	s_mov_b64 exec, -1
	s_add_u32 s48, s48, 0x20000
	s_addc_u32 s49, s49, 0
	global_load_dword v130, v162, s[48:49]
	global_load_dword v212, v162, s[48:49] offset:128
	global_load_dword v131, v163, s[48:49]
	global_load_dword v213, v163, s[48:49] offset:128
	global_load_dword v132, v164, s[48:49]
	global_load_dword v214, v164, s[48:49] offset:128
	global_load_dword v133, v165, s[48:49]
	global_load_dword v215, v165, s[48:49] offset:128
	s_add_u32 s48, s48, 0x8000
	s_addc_u32 s49, s49, 0
	global_load_dword v134, v162, s[48:49]
	global_load_dword v216, v162, s[48:49] offset:128
	global_load_dword v135, v163, s[48:49]
	global_load_dword v217, v163, s[48:49] offset:128
	global_load_dword v136, v164, s[48:49]
	global_load_dword v218, v164, s[48:49] offset:128
	global_load_dword v137, v165, s[48:49]
	global_load_dword v219, v165, s[48:49] offset:128
	s_add_u32 s48, s48, 0x8000
	s_addc_u32 s49, s49, 0
	global_load_dword v138, v162, s[48:49]
	global_load_dword v220, v162, s[48:49] offset:128
	global_load_dword v139, v163, s[48:49]
	global_load_dword v221, v163, s[48:49] offset:128
	global_load_dword v140, v164, s[48:49]
	global_load_dword v222, v164, s[48:49] offset:128
	global_load_dword v141, v165, s[48:49]
	global_load_dword v223, v165, s[48:49] offset:128
	s_add_u32 s48, s48, 0x8000
	s_addc_u32 s49, s49, 0
	global_load_dword v142, v162, s[48:49]
	global_load_dword v224, v162, s[48:49] offset:128
	global_load_dword v143, v163, s[48:49]
	global_load_dword v225, v163, s[48:49] offset:128
	global_load_dword v144, v164, s[48:49]
	global_load_dword v226, v164, s[48:49] offset:128
	global_load_dword v145, v165, s[48:49]
	global_load_dword v227, v165, s[48:49] offset:128
	s_sub_u32 s48, s48, 0x18000
	s_subb_u32 s49, s49, 0
	s_waitcnt vmcnt(30)
	v_fmac_f32_e32 v130, v34, v175
	v_fmac_f32_e32 v212, v50, v176
	global_store_dword v162, v130, s[48:49]
	global_store_dword v162, v212, s[48:49] offset:128
	s_waitcnt vmcnt(30)
	v_fmac_f32_e32 v131, v35, v175
	v_fmac_f32_e32 v213, v51, v176
	global_store_dword v163, v131, s[48:49]
	global_store_dword v163, v213, s[48:49] offset:128
	s_waitcnt vmcnt(30)
	v_fmac_f32_e32 v132, v36, v175
	v_fmac_f32_e32 v214, v52, v176
	global_store_dword v164, v132, s[48:49]
	global_store_dword v164, v214, s[48:49] offset:128
	s_waitcnt vmcnt(30)
	v_fmac_f32_e32 v133, v37, v175
	v_fmac_f32_e32 v215, v53, v176
	global_store_dword v165, v133, s[48:49]
	global_store_dword v165, v215, s[48:49] offset:128
	s_add_u32 s48, s48, 0x8000
	s_addc_u32 s49, s49, 0
	s_waitcnt vmcnt(30)
	v_fmac_f32_e32 v134, v38, v175
	v_fmac_f32_e32 v216, v54, v176
	global_store_dword v162, v134, s[48:49]
	global_store_dword v162, v216, s[48:49] offset:128
	s_waitcnt vmcnt(30)
	v_fmac_f32_e32 v135, v39, v175
	v_fmac_f32_e32 v217, v55, v176
	global_store_dword v163, v135, s[48:49]
	global_store_dword v163, v217, s[48:49] offset:128
	s_waitcnt vmcnt(30)
	v_fmac_f32_e32 v136, v40, v175
	v_fmac_f32_e32 v218, v56, v176
	global_store_dword v164, v136, s[48:49]
	global_store_dword v164, v218, s[48:49] offset:128
	s_waitcnt vmcnt(30)
	v_fmac_f32_e32 v137, v41, v175
	v_fmac_f32_e32 v219, v57, v176
	global_store_dword v165, v137, s[48:49]
	global_store_dword v165, v219, s[48:49] offset:128
	s_add_u32 s48, s48, 0x8000
	s_addc_u32 s49, s49, 0
	s_waitcnt vmcnt(30)
	v_fmac_f32_e32 v138, v42, v175
	v_fmac_f32_e32 v220, v58, v176
	global_store_dword v162, v138, s[48:49]
	global_store_dword v162, v220, s[48:49] offset:128
	s_waitcnt vmcnt(30)
	v_fmac_f32_e32 v139, v43, v175
	v_fmac_f32_e32 v221, v59, v176
	global_store_dword v163, v139, s[48:49]
	global_store_dword v163, v221, s[48:49] offset:128
	s_waitcnt vmcnt(30)
	v_fmac_f32_e32 v140, v44, v175
	v_fmac_f32_e32 v222, v60, v176
	global_store_dword v164, v140, s[48:49]
	global_store_dword v164, v222, s[48:49] offset:128
	s_waitcnt vmcnt(30)
	v_fmac_f32_e32 v141, v45, v175
	v_fmac_f32_e32 v223, v61, v176
	global_store_dword v165, v141, s[48:49]
	global_store_dword v165, v223, s[48:49] offset:128
	s_add_u32 s48, s48, 0x8000
	s_addc_u32 s49, s49, 0
	s_waitcnt vmcnt(30)
	v_fmac_f32_e32 v142, v46, v175
	v_fmac_f32_e32 v224, v62, v176
	global_store_dword v162, v142, s[48:49]
	global_store_dword v162, v224, s[48:49] offset:128
	s_waitcnt vmcnt(30)
	v_fmac_f32_e32 v143, v47, v175
	v_fmac_f32_e32 v225, v63, v176
	global_store_dword v163, v143, s[48:49]
	global_store_dword v163, v225, s[48:49] offset:128
	s_waitcnt vmcnt(30)
	v_fmac_f32_e32 v144, v48, v175
	v_fmac_f32_e32 v226, v64, v176
	global_store_dword v164, v144, s[48:49]
	global_store_dword v164, v226, s[48:49] offset:128
	s_waitcnt vmcnt(30)
	v_fmac_f32_e32 v145, v49, v175
	v_fmac_f32_e32 v227, v65, v176
	global_store_dword v165, v145, s[48:49]
	global_store_dword v165, v227, s[48:49] offset:128
	s_sub_u32 s48, s48, 0x18000
	s_subb_u32 s49, s49, 0
	v_mul_f32_e32 v130, v130, v130
	v_fmac_f32_e32 v130, v212, v212
	v_mul_f32_e32 v131, v131, v131
	v_fmac_f32_e32 v131, v213, v213
	v_mul_f32_e32 v132, v132, v132
	v_fmac_f32_e32 v132, v214, v214
	v_mul_f32_e32 v133, v133, v133
	v_fmac_f32_e32 v133, v215, v215
	v_mul_f32_e32 v134, v134, v134
	v_fmac_f32_e32 v134, v216, v216
	v_mul_f32_e32 v135, v135, v135
	v_fmac_f32_e32 v135, v217, v217
	v_mul_f32_e32 v136, v136, v136
	v_fmac_f32_e32 v136, v218, v218
	v_mul_f32_e32 v137, v137, v137
	v_fmac_f32_e32 v137, v219, v219
	v_mul_f32_e32 v138, v138, v138
	v_fmac_f32_e32 v138, v220, v220
	v_mul_f32_e32 v139, v139, v139
	v_fmac_f32_e32 v139, v221, v221
	v_mul_f32_e32 v140, v140, v140
	v_fmac_f32_e32 v140, v222, v222
	v_mul_f32_e32 v141, v141, v141
	v_fmac_f32_e32 v141, v223, v223
	v_mul_f32_e32 v142, v142, v142
	v_fmac_f32_e32 v142, v224, v224
	v_mul_f32_e32 v143, v143, v143
	v_fmac_f32_e32 v143, v225, v225
	v_mul_f32_e32 v144, v144, v144
	v_fmac_f32_e32 v144, v226, v226
	v_mul_f32_e32 v145, v145, v145
	v_fmac_f32_e32 v145, v227, v227
	s_waitcnt lgkmcnt(0)
	ds_bpermute_b32 v212, v168, v130
	ds_bpermute_b32 v213, v168, v131
	ds_bpermute_b32 v214, v168, v132
	ds_bpermute_b32 v215, v168, v133
	ds_bpermute_b32 v216, v168, v134
	ds_bpermute_b32 v217, v168, v135
	ds_bpermute_b32 v218, v168, v136
	ds_bpermute_b32 v219, v168, v137
	s_waitcnt lgkmcnt(7)
	v_add_f32_e32 v130, v130, v212
	s_waitcnt lgkmcnt(6)
	v_add_f32_e32 v131, v131, v213
	s_waitcnt lgkmcnt(5)
	v_add_f32_e32 v132, v132, v214
	s_waitcnt lgkmcnt(4)
	v_add_f32_e32 v133, v133, v215
	s_waitcnt lgkmcnt(3)
	v_add_f32_e32 v134, v134, v216
	s_waitcnt lgkmcnt(2)
	v_add_f32_e32 v135, v135, v217
	s_waitcnt lgkmcnt(1)
	v_add_f32_e32 v136, v136, v218
	s_waitcnt lgkmcnt(0)
	v_add_f32_e32 v137, v137, v219
	ds_bpermute_b32 v212, v169, v130
	ds_bpermute_b32 v213, v169, v131
	ds_bpermute_b32 v214, v169, v132
	ds_bpermute_b32 v215, v169, v133
	ds_bpermute_b32 v216, v169, v134
	ds_bpermute_b32 v217, v169, v135
	ds_bpermute_b32 v218, v169, v136
	ds_bpermute_b32 v219, v169, v137
	s_waitcnt lgkmcnt(7)
	v_add_f32_e32 v130, v130, v212
	s_waitcnt lgkmcnt(6)
	v_add_f32_e32 v131, v131, v213
	s_waitcnt lgkmcnt(5)
	v_add_f32_e32 v132, v132, v214
	s_waitcnt lgkmcnt(4)
	v_add_f32_e32 v133, v133, v215
	s_waitcnt lgkmcnt(3)
	v_add_f32_e32 v134, v134, v216
	s_waitcnt lgkmcnt(2)
	v_add_f32_e32 v135, v135, v217
	s_waitcnt lgkmcnt(1)
	v_add_f32_e32 v136, v136, v218
	s_waitcnt lgkmcnt(0)
	v_add_f32_e32 v137, v137, v219
	ds_bpermute_b32 v212, v171, v130
	ds_bpermute_b32 v213, v171, v131
	ds_bpermute_b32 v214, v171, v132
	ds_bpermute_b32 v215, v171, v133
	ds_bpermute_b32 v216, v171, v134
	ds_bpermute_b32 v217, v171, v135
	ds_bpermute_b32 v218, v171, v136
	ds_bpermute_b32 v219, v171, v137
	s_waitcnt lgkmcnt(7)
	v_add_f32_e32 v130, v130, v212
	s_waitcnt lgkmcnt(6)
	v_add_f32_e32 v131, v131, v213
	s_waitcnt lgkmcnt(5)
	v_add_f32_e32 v132, v132, v214
	s_waitcnt lgkmcnt(4)
	v_add_f32_e32 v133, v133, v215
	s_waitcnt lgkmcnt(3)
	v_add_f32_e32 v134, v134, v216
	s_waitcnt lgkmcnt(2)
	v_add_f32_e32 v135, v135, v217
	s_waitcnt lgkmcnt(1)
	v_add_f32_e32 v136, v136, v218
	s_waitcnt lgkmcnt(0)
	v_add_f32_e32 v137, v137, v219
	ds_bpermute_b32 v212, v172, v130
	ds_bpermute_b32 v213, v172, v131
	ds_bpermute_b32 v214, v172, v132
	ds_bpermute_b32 v215, v172, v133
	ds_bpermute_b32 v216, v172, v134
	ds_bpermute_b32 v217, v172, v135
	ds_bpermute_b32 v218, v172, v136
	ds_bpermute_b32 v219, v172, v137
	s_waitcnt lgkmcnt(7)
	v_add_f32_e32 v130, v130, v212
	s_waitcnt lgkmcnt(6)
	v_add_f32_e32 v131, v131, v213
	s_waitcnt lgkmcnt(5)
	v_add_f32_e32 v132, v132, v214
	s_waitcnt lgkmcnt(4)
	v_add_f32_e32 v133, v133, v215
	s_waitcnt lgkmcnt(3)
	v_add_f32_e32 v134, v134, v216
	s_waitcnt lgkmcnt(2)
	v_add_f32_e32 v135, v135, v217
	s_waitcnt lgkmcnt(1)
	v_add_f32_e32 v136, v136, v218
	s_waitcnt lgkmcnt(0)
	v_add_f32_e32 v137, v137, v219
	ds_bpermute_b32 v212, v173, v130
	ds_bpermute_b32 v213, v173, v131
	ds_bpermute_b32 v214, v173, v132
	ds_bpermute_b32 v215, v173, v133
	ds_bpermute_b32 v216, v173, v134
	ds_bpermute_b32 v217, v173, v135
	ds_bpermute_b32 v218, v173, v136
	ds_bpermute_b32 v219, v173, v137
	s_waitcnt lgkmcnt(7)
	v_add_f32_e32 v130, v130, v212
	s_waitcnt lgkmcnt(6)
	v_add_f32_e32 v131, v131, v213
	s_waitcnt lgkmcnt(5)
	v_add_f32_e32 v132, v132, v214
	s_waitcnt lgkmcnt(4)
	v_add_f32_e32 v133, v133, v215
	s_waitcnt lgkmcnt(3)
	v_add_f32_e32 v134, v134, v216
	s_waitcnt lgkmcnt(2)
	v_add_f32_e32 v135, v135, v217
	s_waitcnt lgkmcnt(1)
	v_add_f32_e32 v136, v136, v218
	s_waitcnt lgkmcnt(0)
	v_add_f32_e32 v137, v137, v219
	ds_bpermute_b32 v220, v168, v138
	ds_bpermute_b32 v221, v168, v139
	ds_bpermute_b32 v222, v168, v140
	ds_bpermute_b32 v223, v168, v141
	ds_bpermute_b32 v224, v168, v142
	ds_bpermute_b32 v225, v168, v143
	ds_bpermute_b32 v226, v168, v144
	ds_bpermute_b32 v227, v168, v145
	s_waitcnt lgkmcnt(7)
	v_add_f32_e32 v138, v138, v220
	s_waitcnt lgkmcnt(6)
	v_add_f32_e32 v139, v139, v221
	s_waitcnt lgkmcnt(5)
	v_add_f32_e32 v140, v140, v222
	s_waitcnt lgkmcnt(4)
	v_add_f32_e32 v141, v141, v223
	s_waitcnt lgkmcnt(3)
	v_add_f32_e32 v142, v142, v224
	s_waitcnt lgkmcnt(2)
	v_add_f32_e32 v143, v143, v225
	s_waitcnt lgkmcnt(1)
	v_add_f32_e32 v144, v144, v226
	s_waitcnt lgkmcnt(0)
	v_add_f32_e32 v145, v145, v227
	ds_bpermute_b32 v220, v169, v138
	ds_bpermute_b32 v221, v169, v139
	ds_bpermute_b32 v222, v169, v140
	ds_bpermute_b32 v223, v169, v141
	ds_bpermute_b32 v224, v169, v142
	ds_bpermute_b32 v225, v169, v143
	ds_bpermute_b32 v226, v169, v144
	ds_bpermute_b32 v227, v169, v145
	s_waitcnt lgkmcnt(7)
	v_add_f32_e32 v138, v138, v220
	s_waitcnt lgkmcnt(6)
	v_add_f32_e32 v139, v139, v221
	s_waitcnt lgkmcnt(5)
	v_add_f32_e32 v140, v140, v222
	s_waitcnt lgkmcnt(4)
	v_add_f32_e32 v141, v141, v223
	s_waitcnt lgkmcnt(3)
	v_add_f32_e32 v142, v142, v224
	s_waitcnt lgkmcnt(2)
	v_add_f32_e32 v143, v143, v225
	s_waitcnt lgkmcnt(1)
	v_add_f32_e32 v144, v144, v226
	s_waitcnt lgkmcnt(0)
	v_add_f32_e32 v145, v145, v227
	ds_bpermute_b32 v220, v171, v138
	ds_bpermute_b32 v221, v171, v139
	ds_bpermute_b32 v222, v171, v140
	ds_bpermute_b32 v223, v171, v141
	ds_bpermute_b32 v224, v171, v142
	ds_bpermute_b32 v225, v171, v143
	ds_bpermute_b32 v226, v171, v144
	ds_bpermute_b32 v227, v171, v145
	s_waitcnt lgkmcnt(7)
	v_add_f32_e32 v138, v138, v220
	s_waitcnt lgkmcnt(6)
	v_add_f32_e32 v139, v139, v221
	s_waitcnt lgkmcnt(5)
	v_add_f32_e32 v140, v140, v222
	s_waitcnt lgkmcnt(4)
	v_add_f32_e32 v141, v141, v223
	s_waitcnt lgkmcnt(3)
	v_add_f32_e32 v142, v142, v224
	s_waitcnt lgkmcnt(2)
	v_add_f32_e32 v143, v143, v225
	s_waitcnt lgkmcnt(1)
	v_add_f32_e32 v144, v144, v226
	s_waitcnt lgkmcnt(0)
	v_add_f32_e32 v145, v145, v227
	ds_bpermute_b32 v220, v172, v138
	ds_bpermute_b32 v221, v172, v139
	ds_bpermute_b32 v222, v172, v140
	ds_bpermute_b32 v223, v172, v141
	ds_bpermute_b32 v224, v172, v142
	ds_bpermute_b32 v225, v172, v143
	ds_bpermute_b32 v226, v172, v144
	ds_bpermute_b32 v227, v172, v145
	s_waitcnt lgkmcnt(7)
	v_add_f32_e32 v138, v138, v220
	s_waitcnt lgkmcnt(6)
	v_add_f32_e32 v139, v139, v221
	s_waitcnt lgkmcnt(5)
	v_add_f32_e32 v140, v140, v222
	s_waitcnt lgkmcnt(4)
	v_add_f32_e32 v141, v141, v223
	s_waitcnt lgkmcnt(3)
	v_add_f32_e32 v142, v142, v224
	s_waitcnt lgkmcnt(2)
	v_add_f32_e32 v143, v143, v225
	s_waitcnt lgkmcnt(1)
	v_add_f32_e32 v144, v144, v226
	s_waitcnt lgkmcnt(0)
	v_add_f32_e32 v145, v145, v227
	ds_bpermute_b32 v220, v173, v138
	ds_bpermute_b32 v221, v173, v139
	ds_bpermute_b32 v222, v173, v140
	ds_bpermute_b32 v223, v173, v141
	ds_bpermute_b32 v224, v173, v142
	ds_bpermute_b32 v225, v173, v143
	ds_bpermute_b32 v226, v173, v144
	ds_bpermute_b32 v227, v173, v145
	s_waitcnt lgkmcnt(7)
	v_add_f32_e32 v138, v138, v220
	s_waitcnt lgkmcnt(6)
	v_add_f32_e32 v139, v139, v221
	s_waitcnt lgkmcnt(5)
	v_add_f32_e32 v140, v140, v222
	s_waitcnt lgkmcnt(4)
	v_add_f32_e32 v141, v141, v223
	s_waitcnt lgkmcnt(3)
	v_add_f32_e32 v142, v142, v224
	s_waitcnt lgkmcnt(2)
	v_add_f32_e32 v143, v143, v225
	s_waitcnt lgkmcnt(1)
	v_add_f32_e32 v144, v144, v226
	s_waitcnt lgkmcnt(0)
	v_add_f32_e32 v145, v145, v227
	v_cmp_eq_u32_e32 vcc, 0, v174
	s_and_saveexec_b64 s[58:59], vcc
	global_store_dword v167, v130, s[10:11] offset:128
	global_store_dword v167, v131, s[10:11] offset:132
	global_store_dword v167, v132, s[10:11] offset:136
	global_store_dword v167, v133, s[10:11] offset:140
	global_store_dword v167, v134, s[10:11] offset:160
	global_store_dword v167, v135, s[10:11] offset:164
	global_store_dword v167, v136, s[10:11] offset:168
	global_store_dword v167, v137, s[10:11] offset:172
	global_store_dword v167, v138, s[10:11] offset:192
	global_store_dword v167, v139, s[10:11] offset:196
	global_store_dword v167, v140, s[10:11] offset:200
	global_store_dword v167, v141, s[10:11] offset:204
	global_store_dword v167, v142, s[10:11] offset:224
	global_store_dword v167, v143, s[10:11] offset:228
	global_store_dword v167, v144, s[10:11] offset:232
	global_store_dword v167, v145, s[10:11] offset:236
	s_mov_b64 exec, -1
	s_sub_u32 s48, s48, 0x20000
	s_subb_u32 s49, s49, 0
	s_add_u32 s60, s60, 0x200
	s_addc_u32 s61, s61, 0
	s_add_u32 s10, s10, 0x18000
	s_addc_u32 s11, s11, 0
	s_add_u32 s48, s48, 0x200
	s_addc_u32 s49, s49, 0
	global_load_dword v175, v166, s[60:61]
	global_load_dword v176, v166, s[60:61] offset:128
	global_load_dword v130, v162, s[48:49]
	global_load_dword v212, v162, s[48:49] offset:128
	global_load_dword v131, v163, s[48:49]
	global_load_dword v213, v163, s[48:49] offset:128
	global_load_dword v132, v164, s[48:49]
	global_load_dword v214, v164, s[48:49] offset:128
	global_load_dword v133, v165, s[48:49]
	global_load_dword v215, v165, s[48:49] offset:128
	s_add_u32 s48, s48, 0x8000
	s_addc_u32 s49, s49, 0
	global_load_dword v134, v162, s[48:49]
	global_load_dword v216, v162, s[48:49] offset:128
	global_load_dword v135, v163, s[48:49]
	global_load_dword v217, v163, s[48:49] offset:128
	global_load_dword v136, v164, s[48:49]
	global_load_dword v218, v164, s[48:49] offset:128
	global_load_dword v137, v165, s[48:49]
	global_load_dword v219, v165, s[48:49] offset:128
	s_add_u32 s48, s48, 0x8000
	s_addc_u32 s49, s49, 0
	global_load_dword v138, v162, s[48:49]
	global_load_dword v220, v162, s[48:49] offset:128
	global_load_dword v139, v163, s[48:49]
	global_load_dword v221, v163, s[48:49] offset:128
	global_load_dword v140, v164, s[48:49]
	global_load_dword v222, v164, s[48:49] offset:128
	global_load_dword v141, v165, s[48:49]
	global_load_dword v223, v165, s[48:49] offset:128
	s_add_u32 s48, s48, 0x8000
	s_addc_u32 s49, s49, 0
	global_load_dword v142, v162, s[48:49]
	global_load_dword v224, v162, s[48:49] offset:128
	global_load_dword v143, v163, s[48:49]
	global_load_dword v225, v163, s[48:49] offset:128
	global_load_dword v144, v164, s[48:49]
	global_load_dword v226, v164, s[48:49] offset:128
	global_load_dword v145, v165, s[48:49]
	global_load_dword v227, v165, s[48:49] offset:128
	s_sub_u32 s48, s48, 0x18000
	s_subb_u32 s49, s49, 0
	s_waitcnt vmcnt(32)
	v_mul_f32_e32 v175, 0.5, v175
	v_mul_f32_e32 v176, 0.5, v176
	s_waitcnt vmcnt(30)
	v_fmac_f32_e32 v130, v66, v175
	v_fmac_f32_e32 v212, v82, v176
	global_store_dword v162, v130, s[48:49]
	global_store_dword v162, v212, s[48:49] offset:128
	s_waitcnt vmcnt(30)
	v_fmac_f32_e32 v131, v67, v175
	v_fmac_f32_e32 v213, v83, v176
	global_store_dword v163, v131, s[48:49]
	global_store_dword v163, v213, s[48:49] offset:128
	s_waitcnt vmcnt(30)
	v_fmac_f32_e32 v132, v68, v175
	v_fmac_f32_e32 v214, v84, v176
	global_store_dword v164, v132, s[48:49]
	global_store_dword v164, v214, s[48:49] offset:128
	s_waitcnt vmcnt(30)
	v_fmac_f32_e32 v133, v69, v175
	v_fmac_f32_e32 v215, v85, v176
	global_store_dword v165, v133, s[48:49]
	global_store_dword v165, v215, s[48:49] offset:128
	s_add_u32 s48, s48, 0x8000
	s_addc_u32 s49, s49, 0
	s_waitcnt vmcnt(30)
	v_fmac_f32_e32 v134, v70, v175
	v_fmac_f32_e32 v216, v86, v176
	global_store_dword v162, v134, s[48:49]
	global_store_dword v162, v216, s[48:49] offset:128
	s_waitcnt vmcnt(30)
	v_fmac_f32_e32 v135, v71, v175
	v_fmac_f32_e32 v217, v87, v176
	global_store_dword v163, v135, s[48:49]
	global_store_dword v163, v217, s[48:49] offset:128
	s_waitcnt vmcnt(30)
	v_fmac_f32_e32 v136, v72, v175
	v_fmac_f32_e32 v218, v88, v176
	global_store_dword v164, v136, s[48:49]
	global_store_dword v164, v218, s[48:49] offset:128
	s_waitcnt vmcnt(30)
	v_fmac_f32_e32 v137, v73, v175
	v_fmac_f32_e32 v219, v89, v176
	global_store_dword v165, v137, s[48:49]
	global_store_dword v165, v219, s[48:49] offset:128
	s_add_u32 s48, s48, 0x8000
	s_addc_u32 s49, s49, 0
	s_waitcnt vmcnt(30)
	v_fmac_f32_e32 v138, v74, v175
	v_fmac_f32_e32 v220, v90, v176
	global_store_dword v162, v138, s[48:49]
	global_store_dword v162, v220, s[48:49] offset:128
	s_waitcnt vmcnt(30)
	v_fmac_f32_e32 v139, v75, v175
	v_fmac_f32_e32 v221, v91, v176
	global_store_dword v163, v139, s[48:49]
	global_store_dword v163, v221, s[48:49] offset:128
	s_waitcnt vmcnt(30)
	v_fmac_f32_e32 v140, v76, v175
	v_fmac_f32_e32 v222, v92, v176
	global_store_dword v164, v140, s[48:49]
	global_store_dword v164, v222, s[48:49] offset:128
	s_waitcnt vmcnt(30)
	v_fmac_f32_e32 v141, v77, v175
	v_fmac_f32_e32 v223, v93, v176
	global_store_dword v165, v141, s[48:49]
	global_store_dword v165, v223, s[48:49] offset:128
	s_add_u32 s48, s48, 0x8000
	s_addc_u32 s49, s49, 0
	s_waitcnt vmcnt(30)
	v_fmac_f32_e32 v142, v78, v175
	v_fmac_f32_e32 v224, v94, v176
	global_store_dword v162, v142, s[48:49]
	global_store_dword v162, v224, s[48:49] offset:128
	s_waitcnt vmcnt(30)
	v_fmac_f32_e32 v143, v79, v175
	v_fmac_f32_e32 v225, v95, v176
	global_store_dword v163, v143, s[48:49]
	global_store_dword v163, v225, s[48:49] offset:128
	s_waitcnt vmcnt(30)
	v_fmac_f32_e32 v144, v80, v175
	v_fmac_f32_e32 v226, v96, v176
	global_store_dword v164, v144, s[48:49]
	global_store_dword v164, v226, s[48:49] offset:128
	s_waitcnt vmcnt(30)
	v_fmac_f32_e32 v145, v81, v175
	v_fmac_f32_e32 v227, v97, v176
	global_store_dword v165, v145, s[48:49]
	global_store_dword v165, v227, s[48:49] offset:128
	s_sub_u32 s48, s48, 0x18000
	s_subb_u32 s49, s49, 0
	v_mul_f32_e32 v130, v130, v130
	v_fmac_f32_e32 v130, v212, v212
	v_mul_f32_e32 v131, v131, v131
	v_fmac_f32_e32 v131, v213, v213
	v_mul_f32_e32 v132, v132, v132
	v_fmac_f32_e32 v132, v214, v214
	v_mul_f32_e32 v133, v133, v133
	v_fmac_f32_e32 v133, v215, v215
	v_mul_f32_e32 v134, v134, v134
	v_fmac_f32_e32 v134, v216, v216
	v_mul_f32_e32 v135, v135, v135
	v_fmac_f32_e32 v135, v217, v217
	v_mul_f32_e32 v136, v136, v136
	v_fmac_f32_e32 v136, v218, v218
	v_mul_f32_e32 v137, v137, v137
	v_fmac_f32_e32 v137, v219, v219
	v_mul_f32_e32 v138, v138, v138
	v_fmac_f32_e32 v138, v220, v220
	v_mul_f32_e32 v139, v139, v139
	v_fmac_f32_e32 v139, v221, v221
	v_mul_f32_e32 v140, v140, v140
	v_fmac_f32_e32 v140, v222, v222
	v_mul_f32_e32 v141, v141, v141
	v_fmac_f32_e32 v141, v223, v223
	v_mul_f32_e32 v142, v142, v142
	v_fmac_f32_e32 v142, v224, v224
	v_mul_f32_e32 v143, v143, v143
	v_fmac_f32_e32 v143, v225, v225
	v_mul_f32_e32 v144, v144, v144
	v_fmac_f32_e32 v144, v226, v226
	v_mul_f32_e32 v145, v145, v145
	v_fmac_f32_e32 v145, v227, v227
	s_waitcnt lgkmcnt(0)
	ds_bpermute_b32 v212, v168, v130
	ds_bpermute_b32 v213, v168, v131
	ds_bpermute_b32 v214, v168, v132
	ds_bpermute_b32 v215, v168, v133
	ds_bpermute_b32 v216, v168, v134
	ds_bpermute_b32 v217, v168, v135
	ds_bpermute_b32 v218, v168, v136
	ds_bpermute_b32 v219, v168, v137
	s_waitcnt lgkmcnt(7)
	v_add_f32_e32 v130, v130, v212
	s_waitcnt lgkmcnt(6)
	v_add_f32_e32 v131, v131, v213
	s_waitcnt lgkmcnt(5)
	v_add_f32_e32 v132, v132, v214
	s_waitcnt lgkmcnt(4)
	v_add_f32_e32 v133, v133, v215
	s_waitcnt lgkmcnt(3)
	v_add_f32_e32 v134, v134, v216
	s_waitcnt lgkmcnt(2)
	v_add_f32_e32 v135, v135, v217
	s_waitcnt lgkmcnt(1)
	v_add_f32_e32 v136, v136, v218
	s_waitcnt lgkmcnt(0)
	v_add_f32_e32 v137, v137, v219
	ds_bpermute_b32 v212, v169, v130
	ds_bpermute_b32 v213, v169, v131
	ds_bpermute_b32 v214, v169, v132
	ds_bpermute_b32 v215, v169, v133
	ds_bpermute_b32 v216, v169, v134
	ds_bpermute_b32 v217, v169, v135
	ds_bpermute_b32 v218, v169, v136
	ds_bpermute_b32 v219, v169, v137
	s_waitcnt lgkmcnt(7)
	v_add_f32_e32 v130, v130, v212
	s_waitcnt lgkmcnt(6)
	v_add_f32_e32 v131, v131, v213
	s_waitcnt lgkmcnt(5)
	v_add_f32_e32 v132, v132, v214
	s_waitcnt lgkmcnt(4)
	v_add_f32_e32 v133, v133, v215
	s_waitcnt lgkmcnt(3)
	v_add_f32_e32 v134, v134, v216
	s_waitcnt lgkmcnt(2)
	v_add_f32_e32 v135, v135, v217
	s_waitcnt lgkmcnt(1)
	v_add_f32_e32 v136, v136, v218
	s_waitcnt lgkmcnt(0)
	v_add_f32_e32 v137, v137, v219
	ds_bpermute_b32 v212, v171, v130
	ds_bpermute_b32 v213, v171, v131
	ds_bpermute_b32 v214, v171, v132
	ds_bpermute_b32 v215, v171, v133
	ds_bpermute_b32 v216, v171, v134
	ds_bpermute_b32 v217, v171, v135
	ds_bpermute_b32 v218, v171, v136
	ds_bpermute_b32 v219, v171, v137
	s_waitcnt lgkmcnt(7)
	v_add_f32_e32 v130, v130, v212
	s_waitcnt lgkmcnt(6)
	v_add_f32_e32 v131, v131, v213
	s_waitcnt lgkmcnt(5)
	v_add_f32_e32 v132, v132, v214
	s_waitcnt lgkmcnt(4)
	v_add_f32_e32 v133, v133, v215
	s_waitcnt lgkmcnt(3)
	v_add_f32_e32 v134, v134, v216
	s_waitcnt lgkmcnt(2)
	v_add_f32_e32 v135, v135, v217
	s_waitcnt lgkmcnt(1)
	v_add_f32_e32 v136, v136, v218
	s_waitcnt lgkmcnt(0)
	v_add_f32_e32 v137, v137, v219
	ds_bpermute_b32 v212, v172, v130
	ds_bpermute_b32 v213, v172, v131
	ds_bpermute_b32 v214, v172, v132
	ds_bpermute_b32 v215, v172, v133
	ds_bpermute_b32 v216, v172, v134
	ds_bpermute_b32 v217, v172, v135
	ds_bpermute_b32 v218, v172, v136
	ds_bpermute_b32 v219, v172, v137
	s_waitcnt lgkmcnt(7)
	v_add_f32_e32 v130, v130, v212
	s_waitcnt lgkmcnt(6)
	v_add_f32_e32 v131, v131, v213
	s_waitcnt lgkmcnt(5)
	v_add_f32_e32 v132, v132, v214
	s_waitcnt lgkmcnt(4)
	v_add_f32_e32 v133, v133, v215
	s_waitcnt lgkmcnt(3)
	v_add_f32_e32 v134, v134, v216
	s_waitcnt lgkmcnt(2)
	v_add_f32_e32 v135, v135, v217
	s_waitcnt lgkmcnt(1)
	v_add_f32_e32 v136, v136, v218
	s_waitcnt lgkmcnt(0)
	v_add_f32_e32 v137, v137, v219
	ds_bpermute_b32 v212, v173, v130
	ds_bpermute_b32 v213, v173, v131
	ds_bpermute_b32 v214, v173, v132
	ds_bpermute_b32 v215, v173, v133
	ds_bpermute_b32 v216, v173, v134
	ds_bpermute_b32 v217, v173, v135
	ds_bpermute_b32 v218, v173, v136
	ds_bpermute_b32 v219, v173, v137
	s_waitcnt lgkmcnt(7)
	v_add_f32_e32 v130, v130, v212
	s_waitcnt lgkmcnt(6)
	v_add_f32_e32 v131, v131, v213
	s_waitcnt lgkmcnt(5)
	v_add_f32_e32 v132, v132, v214
	s_waitcnt lgkmcnt(4)
	v_add_f32_e32 v133, v133, v215
	s_waitcnt lgkmcnt(3)
	v_add_f32_e32 v134, v134, v216
	s_waitcnt lgkmcnt(2)
	v_add_f32_e32 v135, v135, v217
	s_waitcnt lgkmcnt(1)
	v_add_f32_e32 v136, v136, v218
	s_waitcnt lgkmcnt(0)
	v_add_f32_e32 v137, v137, v219
	ds_bpermute_b32 v220, v168, v138
	ds_bpermute_b32 v221, v168, v139
	ds_bpermute_b32 v222, v168, v140
	ds_bpermute_b32 v223, v168, v141
	ds_bpermute_b32 v224, v168, v142
	ds_bpermute_b32 v225, v168, v143
	ds_bpermute_b32 v226, v168, v144
	ds_bpermute_b32 v227, v168, v145
	s_waitcnt lgkmcnt(7)
	v_add_f32_e32 v138, v138, v220
	s_waitcnt lgkmcnt(6)
	v_add_f32_e32 v139, v139, v221
	s_waitcnt lgkmcnt(5)
	v_add_f32_e32 v140, v140, v222
	s_waitcnt lgkmcnt(4)
	v_add_f32_e32 v141, v141, v223
	s_waitcnt lgkmcnt(3)
	v_add_f32_e32 v142, v142, v224
	s_waitcnt lgkmcnt(2)
	v_add_f32_e32 v143, v143, v225
	s_waitcnt lgkmcnt(1)
	v_add_f32_e32 v144, v144, v226
	s_waitcnt lgkmcnt(0)
	v_add_f32_e32 v145, v145, v227
	ds_bpermute_b32 v220, v169, v138
	ds_bpermute_b32 v221, v169, v139
	ds_bpermute_b32 v222, v169, v140
	ds_bpermute_b32 v223, v169, v141
	ds_bpermute_b32 v224, v169, v142
	ds_bpermute_b32 v225, v169, v143
	ds_bpermute_b32 v226, v169, v144
	ds_bpermute_b32 v227, v169, v145
	s_waitcnt lgkmcnt(7)
	v_add_f32_e32 v138, v138, v220
	s_waitcnt lgkmcnt(6)
	v_add_f32_e32 v139, v139, v221
	s_waitcnt lgkmcnt(5)
	v_add_f32_e32 v140, v140, v222
	s_waitcnt lgkmcnt(4)
	v_add_f32_e32 v141, v141, v223
	s_waitcnt lgkmcnt(3)
	v_add_f32_e32 v142, v142, v224
	s_waitcnt lgkmcnt(2)
	v_add_f32_e32 v143, v143, v225
	s_waitcnt lgkmcnt(1)
	v_add_f32_e32 v144, v144, v226
	s_waitcnt lgkmcnt(0)
	v_add_f32_e32 v145, v145, v227
	ds_bpermute_b32 v220, v171, v138
	ds_bpermute_b32 v221, v171, v139
	ds_bpermute_b32 v222, v171, v140
	ds_bpermute_b32 v223, v171, v141
	ds_bpermute_b32 v224, v171, v142
	ds_bpermute_b32 v225, v171, v143
	ds_bpermute_b32 v226, v171, v144
	ds_bpermute_b32 v227, v171, v145
	s_waitcnt lgkmcnt(7)
	v_add_f32_e32 v138, v138, v220
	s_waitcnt lgkmcnt(6)
	v_add_f32_e32 v139, v139, v221
	s_waitcnt lgkmcnt(5)
	v_add_f32_e32 v140, v140, v222
	s_waitcnt lgkmcnt(4)
	v_add_f32_e32 v141, v141, v223
	s_waitcnt lgkmcnt(3)
	v_add_f32_e32 v142, v142, v224
	s_waitcnt lgkmcnt(2)
	v_add_f32_e32 v143, v143, v225
	s_waitcnt lgkmcnt(1)
	v_add_f32_e32 v144, v144, v226
	s_waitcnt lgkmcnt(0)
	v_add_f32_e32 v145, v145, v227
	ds_bpermute_b32 v220, v172, v138
	ds_bpermute_b32 v221, v172, v139
	ds_bpermute_b32 v222, v172, v140
	ds_bpermute_b32 v223, v172, v141
	ds_bpermute_b32 v224, v172, v142
	ds_bpermute_b32 v225, v172, v143
	ds_bpermute_b32 v226, v172, v144
	ds_bpermute_b32 v227, v172, v145
	s_waitcnt lgkmcnt(7)
	v_add_f32_e32 v138, v138, v220
	s_waitcnt lgkmcnt(6)
	v_add_f32_e32 v139, v139, v221
	s_waitcnt lgkmcnt(5)
	v_add_f32_e32 v140, v140, v222
	s_waitcnt lgkmcnt(4)
	v_add_f32_e32 v141, v141, v223
	s_waitcnt lgkmcnt(3)
	v_add_f32_e32 v142, v142, v224
	s_waitcnt lgkmcnt(2)
	v_add_f32_e32 v143, v143, v225
	s_waitcnt lgkmcnt(1)
	v_add_f32_e32 v144, v144, v226
	s_waitcnt lgkmcnt(0)
	v_add_f32_e32 v145, v145, v227
	ds_bpermute_b32 v220, v173, v138
	ds_bpermute_b32 v221, v173, v139
	ds_bpermute_b32 v222, v173, v140
	ds_bpermute_b32 v223, v173, v141
	ds_bpermute_b32 v224, v173, v142
	ds_bpermute_b32 v225, v173, v143
	ds_bpermute_b32 v226, v173, v144
	ds_bpermute_b32 v227, v173, v145
	s_waitcnt lgkmcnt(7)
	v_add_f32_e32 v138, v138, v220
	s_waitcnt lgkmcnt(6)
	v_add_f32_e32 v139, v139, v221
	s_waitcnt lgkmcnt(5)
	v_add_f32_e32 v140, v140, v222
	s_waitcnt lgkmcnt(4)
	v_add_f32_e32 v141, v141, v223
	s_waitcnt lgkmcnt(3)
	v_add_f32_e32 v142, v142, v224
	s_waitcnt lgkmcnt(2)
	v_add_f32_e32 v143, v143, v225
	s_waitcnt lgkmcnt(1)
	v_add_f32_e32 v144, v144, v226
	s_waitcnt lgkmcnt(0)
	v_add_f32_e32 v145, v145, v227
	v_cmp_eq_u32_e32 vcc, 0, v174
	s_and_saveexec_b64 s[58:59], vcc
	global_store_dword v167, v130, s[10:11]
	global_store_dword v167, v131, s[10:11] offset:4
	global_store_dword v167, v132, s[10:11] offset:8
	global_store_dword v167, v133, s[10:11] offset:12
	global_store_dword v167, v134, s[10:11] offset:32
	global_store_dword v167, v135, s[10:11] offset:36
	global_store_dword v167, v136, s[10:11] offset:40
	global_store_dword v167, v137, s[10:11] offset:44
	global_store_dword v167, v138, s[10:11] offset:64
	global_store_dword v167, v139, s[10:11] offset:68
	global_store_dword v167, v140, s[10:11] offset:72
	global_store_dword v167, v141, s[10:11] offset:76
	global_store_dword v167, v142, s[10:11] offset:96
	global_store_dword v167, v143, s[10:11] offset:100
	global_store_dword v167, v144, s[10:11] offset:104
	global_store_dword v167, v145, s[10:11] offset:108
	s_mov_b64 exec, -1
	s_add_u32 s48, s48, 0x20000
	s_addc_u32 s49, s49, 0
	global_load_dword v130, v162, s[48:49]
	global_load_dword v212, v162, s[48:49] offset:128
	global_load_dword v131, v163, s[48:49]
	global_load_dword v213, v163, s[48:49] offset:128
	global_load_dword v132, v164, s[48:49]
	global_load_dword v214, v164, s[48:49] offset:128
	global_load_dword v133, v165, s[48:49]
	global_load_dword v215, v165, s[48:49] offset:128
	s_add_u32 s48, s48, 0x8000
	s_addc_u32 s49, s49, 0
	global_load_dword v134, v162, s[48:49]
	global_load_dword v216, v162, s[48:49] offset:128
	global_load_dword v135, v163, s[48:49]
	global_load_dword v217, v163, s[48:49] offset:128
	global_load_dword v136, v164, s[48:49]
	global_load_dword v218, v164, s[48:49] offset:128
	global_load_dword v137, v165, s[48:49]
	global_load_dword v219, v165, s[48:49] offset:128
	s_add_u32 s48, s48, 0x8000
	s_addc_u32 s49, s49, 0
	global_load_dword v138, v162, s[48:49]
	global_load_dword v220, v162, s[48:49] offset:128
	global_load_dword v139, v163, s[48:49]
	global_load_dword v221, v163, s[48:49] offset:128
	global_load_dword v140, v164, s[48:49]
	global_load_dword v222, v164, s[48:49] offset:128
	global_load_dword v141, v165, s[48:49]
	global_load_dword v223, v165, s[48:49] offset:128
	s_add_u32 s48, s48, 0x8000
	s_addc_u32 s49, s49, 0
	global_load_dword v142, v162, s[48:49]
	global_load_dword v224, v162, s[48:49] offset:128
	global_load_dword v143, v163, s[48:49]
	global_load_dword v225, v163, s[48:49] offset:128
	global_load_dword v144, v164, s[48:49]
	global_load_dword v226, v164, s[48:49] offset:128
	global_load_dword v145, v165, s[48:49]
	global_load_dword v227, v165, s[48:49] offset:128
	s_sub_u32 s48, s48, 0x18000
	s_subb_u32 s49, s49, 0
	s_waitcnt vmcnt(30)
	v_fmac_f32_e32 v130, v98, v175
	v_fmac_f32_e32 v212, v114, v176
	global_store_dword v162, v130, s[48:49]
	global_store_dword v162, v212, s[48:49] offset:128
	s_waitcnt vmcnt(30)
	v_fmac_f32_e32 v131, v99, v175
	v_fmac_f32_e32 v213, v115, v176
	global_store_dword v163, v131, s[48:49]
	global_store_dword v163, v213, s[48:49] offset:128
	s_waitcnt vmcnt(30)
	v_fmac_f32_e32 v132, v100, v175
	v_fmac_f32_e32 v214, v116, v176
	global_store_dword v164, v132, s[48:49]
	global_store_dword v164, v214, s[48:49] offset:128
	s_waitcnt vmcnt(30)
	v_fmac_f32_e32 v133, v101, v175
	v_fmac_f32_e32 v215, v117, v176
	global_store_dword v165, v133, s[48:49]
	global_store_dword v165, v215, s[48:49] offset:128
	s_add_u32 s48, s48, 0x8000
	s_addc_u32 s49, s49, 0
	s_waitcnt vmcnt(30)
	v_fmac_f32_e32 v134, v102, v175
	v_fmac_f32_e32 v216, v118, v176
	global_store_dword v162, v134, s[48:49]
	global_store_dword v162, v216, s[48:49] offset:128
	s_waitcnt vmcnt(30)
	v_fmac_f32_e32 v135, v103, v175
	v_fmac_f32_e32 v217, v119, v176
	global_store_dword v163, v135, s[48:49]
	global_store_dword v163, v217, s[48:49] offset:128
	s_waitcnt vmcnt(30)
	v_fmac_f32_e32 v136, v104, v175
	v_fmac_f32_e32 v218, v120, v176
	global_store_dword v164, v136, s[48:49]
	global_store_dword v164, v218, s[48:49] offset:128
	s_waitcnt vmcnt(30)
	v_fmac_f32_e32 v137, v105, v175
	v_fmac_f32_e32 v219, v121, v176
	global_store_dword v165, v137, s[48:49]
	global_store_dword v165, v219, s[48:49] offset:128
	s_add_u32 s48, s48, 0x8000
	s_addc_u32 s49, s49, 0
	s_waitcnt vmcnt(30)
	v_fmac_f32_e32 v138, v106, v175
	v_fmac_f32_e32 v220, v122, v176
	global_store_dword v162, v138, s[48:49]
	global_store_dword v162, v220, s[48:49] offset:128
	s_waitcnt vmcnt(30)
	v_fmac_f32_e32 v139, v107, v175
	v_fmac_f32_e32 v221, v123, v176
	global_store_dword v163, v139, s[48:49]
	global_store_dword v163, v221, s[48:49] offset:128
	s_waitcnt vmcnt(30)
	v_fmac_f32_e32 v140, v108, v175
	v_fmac_f32_e32 v222, v124, v176
	global_store_dword v164, v140, s[48:49]
	global_store_dword v164, v222, s[48:49] offset:128
	s_waitcnt vmcnt(30)
	v_fmac_f32_e32 v141, v109, v175
	v_fmac_f32_e32 v223, v125, v176
	global_store_dword v165, v141, s[48:49]
	global_store_dword v165, v223, s[48:49] offset:128
	s_add_u32 s48, s48, 0x8000
	s_addc_u32 s49, s49, 0
	s_waitcnt vmcnt(30)
	v_fmac_f32_e32 v142, v110, v175
	v_fmac_f32_e32 v224, v126, v176
	global_store_dword v162, v142, s[48:49]
	global_store_dword v162, v224, s[48:49] offset:128
	s_waitcnt vmcnt(30)
	v_fmac_f32_e32 v143, v111, v175
	v_fmac_f32_e32 v225, v127, v176
	global_store_dword v163, v143, s[48:49]
	global_store_dword v163, v225, s[48:49] offset:128
	s_waitcnt vmcnt(30)
	v_fmac_f32_e32 v144, v112, v175
	v_fmac_f32_e32 v226, v128, v176
	global_store_dword v164, v144, s[48:49]
	global_store_dword v164, v226, s[48:49] offset:128
	s_waitcnt vmcnt(30)
	v_fmac_f32_e32 v145, v113, v175
	v_fmac_f32_e32 v227, v129, v176
	global_store_dword v165, v145, s[48:49]
	global_store_dword v165, v227, s[48:49] offset:128
	s_sub_u32 s48, s48, 0x18000
	s_subb_u32 s49, s49, 0
	v_mul_f32_e32 v130, v130, v130
	v_fmac_f32_e32 v130, v212, v212
	v_mul_f32_e32 v131, v131, v131
	v_fmac_f32_e32 v131, v213, v213
	v_mul_f32_e32 v132, v132, v132
	v_fmac_f32_e32 v132, v214, v214
	v_mul_f32_e32 v133, v133, v133
	v_fmac_f32_e32 v133, v215, v215
	v_mul_f32_e32 v134, v134, v134
	v_fmac_f32_e32 v134, v216, v216
	v_mul_f32_e32 v135, v135, v135
	v_fmac_f32_e32 v135, v217, v217
	v_mul_f32_e32 v136, v136, v136
	v_fmac_f32_e32 v136, v218, v218
	v_mul_f32_e32 v137, v137, v137
	v_fmac_f32_e32 v137, v219, v219
	v_mul_f32_e32 v138, v138, v138
	v_fmac_f32_e32 v138, v220, v220
	v_mul_f32_e32 v139, v139, v139
	v_fmac_f32_e32 v139, v221, v221
	v_mul_f32_e32 v140, v140, v140
	v_fmac_f32_e32 v140, v222, v222
	v_mul_f32_e32 v141, v141, v141
	v_fmac_f32_e32 v141, v223, v223
	v_mul_f32_e32 v142, v142, v142
	v_fmac_f32_e32 v142, v224, v224
	v_mul_f32_e32 v143, v143, v143
	v_fmac_f32_e32 v143, v225, v225
	v_mul_f32_e32 v144, v144, v144
	v_fmac_f32_e32 v144, v226, v226
	v_mul_f32_e32 v145, v145, v145
	v_fmac_f32_e32 v145, v227, v227
	s_waitcnt lgkmcnt(0)
	ds_bpermute_b32 v212, v168, v130
	ds_bpermute_b32 v213, v168, v131
	ds_bpermute_b32 v214, v168, v132
	ds_bpermute_b32 v215, v168, v133
	ds_bpermute_b32 v216, v168, v134
	ds_bpermute_b32 v217, v168, v135
	ds_bpermute_b32 v218, v168, v136
	ds_bpermute_b32 v219, v168, v137
	s_waitcnt lgkmcnt(7)
	v_add_f32_e32 v130, v130, v212
	s_waitcnt lgkmcnt(6)
	v_add_f32_e32 v131, v131, v213
	s_waitcnt lgkmcnt(5)
	v_add_f32_e32 v132, v132, v214
	s_waitcnt lgkmcnt(4)
	v_add_f32_e32 v133, v133, v215
	s_waitcnt lgkmcnt(3)
	v_add_f32_e32 v134, v134, v216
	s_waitcnt lgkmcnt(2)
	v_add_f32_e32 v135, v135, v217
	s_waitcnt lgkmcnt(1)
	v_add_f32_e32 v136, v136, v218
	s_waitcnt lgkmcnt(0)
	v_add_f32_e32 v137, v137, v219
	ds_bpermute_b32 v212, v169, v130
	ds_bpermute_b32 v213, v169, v131
	ds_bpermute_b32 v214, v169, v132
	ds_bpermute_b32 v215, v169, v133
	ds_bpermute_b32 v216, v169, v134
	ds_bpermute_b32 v217, v169, v135
	ds_bpermute_b32 v218, v169, v136
	ds_bpermute_b32 v219, v169, v137
	s_waitcnt lgkmcnt(7)
	v_add_f32_e32 v130, v130, v212
	s_waitcnt lgkmcnt(6)
	v_add_f32_e32 v131, v131, v213
	s_waitcnt lgkmcnt(5)
	v_add_f32_e32 v132, v132, v214
	s_waitcnt lgkmcnt(4)
	v_add_f32_e32 v133, v133, v215
	s_waitcnt lgkmcnt(3)
	v_add_f32_e32 v134, v134, v216
	s_waitcnt lgkmcnt(2)
	v_add_f32_e32 v135, v135, v217
	s_waitcnt lgkmcnt(1)
	v_add_f32_e32 v136, v136, v218
	s_waitcnt lgkmcnt(0)
	v_add_f32_e32 v137, v137, v219
	ds_bpermute_b32 v212, v171, v130
	ds_bpermute_b32 v213, v171, v131
	ds_bpermute_b32 v214, v171, v132
	ds_bpermute_b32 v215, v171, v133
	ds_bpermute_b32 v216, v171, v134
	ds_bpermute_b32 v217, v171, v135
	ds_bpermute_b32 v218, v171, v136
	ds_bpermute_b32 v219, v171, v137
	s_waitcnt lgkmcnt(7)
	v_add_f32_e32 v130, v130, v212
	s_waitcnt lgkmcnt(6)
	v_add_f32_e32 v131, v131, v213
	s_waitcnt lgkmcnt(5)
	v_add_f32_e32 v132, v132, v214
	s_waitcnt lgkmcnt(4)
	v_add_f32_e32 v133, v133, v215
	s_waitcnt lgkmcnt(3)
	v_add_f32_e32 v134, v134, v216
	s_waitcnt lgkmcnt(2)
	v_add_f32_e32 v135, v135, v217
	s_waitcnt lgkmcnt(1)
	v_add_f32_e32 v136, v136, v218
	s_waitcnt lgkmcnt(0)
	v_add_f32_e32 v137, v137, v219
	ds_bpermute_b32 v212, v172, v130
	ds_bpermute_b32 v213, v172, v131
	ds_bpermute_b32 v214, v172, v132
	ds_bpermute_b32 v215, v172, v133
	ds_bpermute_b32 v216, v172, v134
	ds_bpermute_b32 v217, v172, v135
	ds_bpermute_b32 v218, v172, v136
	ds_bpermute_b32 v219, v172, v137
	s_waitcnt lgkmcnt(7)
	v_add_f32_e32 v130, v130, v212
	s_waitcnt lgkmcnt(6)
	v_add_f32_e32 v131, v131, v213
	s_waitcnt lgkmcnt(5)
	v_add_f32_e32 v132, v132, v214
	s_waitcnt lgkmcnt(4)
	v_add_f32_e32 v133, v133, v215
	s_waitcnt lgkmcnt(3)
	v_add_f32_e32 v134, v134, v216
	s_waitcnt lgkmcnt(2)
	v_add_f32_e32 v135, v135, v217
	s_waitcnt lgkmcnt(1)
	v_add_f32_e32 v136, v136, v218
	s_waitcnt lgkmcnt(0)
	v_add_f32_e32 v137, v137, v219
	ds_bpermute_b32 v212, v173, v130
	ds_bpermute_b32 v213, v173, v131
	ds_bpermute_b32 v214, v173, v132
	ds_bpermute_b32 v215, v173, v133
	ds_bpermute_b32 v216, v173, v134
	ds_bpermute_b32 v217, v173, v135
	ds_bpermute_b32 v218, v173, v136
	ds_bpermute_b32 v219, v173, v137
	s_waitcnt lgkmcnt(7)
	v_add_f32_e32 v130, v130, v212
	s_waitcnt lgkmcnt(6)
	v_add_f32_e32 v131, v131, v213
	s_waitcnt lgkmcnt(5)
	v_add_f32_e32 v132, v132, v214
	s_waitcnt lgkmcnt(4)
	v_add_f32_e32 v133, v133, v215
	s_waitcnt lgkmcnt(3)
	v_add_f32_e32 v134, v134, v216
	s_waitcnt lgkmcnt(2)
	v_add_f32_e32 v135, v135, v217
	s_waitcnt lgkmcnt(1)
	v_add_f32_e32 v136, v136, v218
	s_waitcnt lgkmcnt(0)
	v_add_f32_e32 v137, v137, v219
	ds_bpermute_b32 v220, v168, v138
	ds_bpermute_b32 v221, v168, v139
	ds_bpermute_b32 v222, v168, v140
	ds_bpermute_b32 v223, v168, v141
	ds_bpermute_b32 v224, v168, v142
	ds_bpermute_b32 v225, v168, v143
	ds_bpermute_b32 v226, v168, v144
	ds_bpermute_b32 v227, v168, v145
	s_waitcnt lgkmcnt(7)
	v_add_f32_e32 v138, v138, v220
	s_waitcnt lgkmcnt(6)
	v_add_f32_e32 v139, v139, v221
	s_waitcnt lgkmcnt(5)
	v_add_f32_e32 v140, v140, v222
	s_waitcnt lgkmcnt(4)
	v_add_f32_e32 v141, v141, v223
	s_waitcnt lgkmcnt(3)
	v_add_f32_e32 v142, v142, v224
	s_waitcnt lgkmcnt(2)
	v_add_f32_e32 v143, v143, v225
	s_waitcnt lgkmcnt(1)
	v_add_f32_e32 v144, v144, v226
	s_waitcnt lgkmcnt(0)
	v_add_f32_e32 v145, v145, v227
	ds_bpermute_b32 v220, v169, v138
	ds_bpermute_b32 v221, v169, v139
	ds_bpermute_b32 v222, v169, v140
	ds_bpermute_b32 v223, v169, v141
	ds_bpermute_b32 v224, v169, v142
	ds_bpermute_b32 v225, v169, v143
	ds_bpermute_b32 v226, v169, v144
	ds_bpermute_b32 v227, v169, v145
	s_waitcnt lgkmcnt(7)
	v_add_f32_e32 v138, v138, v220
	s_waitcnt lgkmcnt(6)
	v_add_f32_e32 v139, v139, v221
	s_waitcnt lgkmcnt(5)
	v_add_f32_e32 v140, v140, v222
	s_waitcnt lgkmcnt(4)
	v_add_f32_e32 v141, v141, v223
	s_waitcnt lgkmcnt(3)
	v_add_f32_e32 v142, v142, v224
	s_waitcnt lgkmcnt(2)
	v_add_f32_e32 v143, v143, v225
	s_waitcnt lgkmcnt(1)
	v_add_f32_e32 v144, v144, v226
	s_waitcnt lgkmcnt(0)
	v_add_f32_e32 v145, v145, v227
	ds_bpermute_b32 v220, v171, v138
	ds_bpermute_b32 v221, v171, v139
	ds_bpermute_b32 v222, v171, v140
	ds_bpermute_b32 v223, v171, v141
	ds_bpermute_b32 v224, v171, v142
	ds_bpermute_b32 v225, v171, v143
	ds_bpermute_b32 v226, v171, v144
	ds_bpermute_b32 v227, v171, v145
	s_waitcnt lgkmcnt(7)
	v_add_f32_e32 v138, v138, v220
	s_waitcnt lgkmcnt(6)
	v_add_f32_e32 v139, v139, v221
	s_waitcnt lgkmcnt(5)
	v_add_f32_e32 v140, v140, v222
	s_waitcnt lgkmcnt(4)
	v_add_f32_e32 v141, v141, v223
	s_waitcnt lgkmcnt(3)
	v_add_f32_e32 v142, v142, v224
	s_waitcnt lgkmcnt(2)
	v_add_f32_e32 v143, v143, v225
	s_waitcnt lgkmcnt(1)
	v_add_f32_e32 v144, v144, v226
	s_waitcnt lgkmcnt(0)
	v_add_f32_e32 v145, v145, v227
	ds_bpermute_b32 v220, v172, v138
	ds_bpermute_b32 v221, v172, v139
	ds_bpermute_b32 v222, v172, v140
	ds_bpermute_b32 v223, v172, v141
	ds_bpermute_b32 v224, v172, v142
	ds_bpermute_b32 v225, v172, v143
	ds_bpermute_b32 v226, v172, v144
	ds_bpermute_b32 v227, v172, v145
	s_waitcnt lgkmcnt(7)
	v_add_f32_e32 v138, v138, v220
	s_waitcnt lgkmcnt(6)
	v_add_f32_e32 v139, v139, v221
	s_waitcnt lgkmcnt(5)
	v_add_f32_e32 v140, v140, v222
	s_waitcnt lgkmcnt(4)
	v_add_f32_e32 v141, v141, v223
	s_waitcnt lgkmcnt(3)
	v_add_f32_e32 v142, v142, v224
	s_waitcnt lgkmcnt(2)
	v_add_f32_e32 v143, v143, v225
	s_waitcnt lgkmcnt(1)
	v_add_f32_e32 v144, v144, v226
	s_waitcnt lgkmcnt(0)
	v_add_f32_e32 v145, v145, v227
	ds_bpermute_b32 v220, v173, v138
	ds_bpermute_b32 v221, v173, v139
	ds_bpermute_b32 v222, v173, v140
	ds_bpermute_b32 v223, v173, v141
	ds_bpermute_b32 v224, v173, v142
	ds_bpermute_b32 v225, v173, v143
	ds_bpermute_b32 v226, v173, v144
	ds_bpermute_b32 v227, v173, v145
	s_waitcnt lgkmcnt(7)
	v_add_f32_e32 v138, v138, v220
	s_waitcnt lgkmcnt(6)
	v_add_f32_e32 v139, v139, v221
	s_waitcnt lgkmcnt(5)
	v_add_f32_e32 v140, v140, v222
	s_waitcnt lgkmcnt(4)
	v_add_f32_e32 v141, v141, v223
	s_waitcnt lgkmcnt(3)
	v_add_f32_e32 v142, v142, v224
	s_waitcnt lgkmcnt(2)
	v_add_f32_e32 v143, v143, v225
	s_waitcnt lgkmcnt(1)
	v_add_f32_e32 v144, v144, v226
	s_waitcnt lgkmcnt(0)
	v_add_f32_e32 v145, v145, v227
	v_cmp_eq_u32_e32 vcc, 0, v174
	s_and_saveexec_b64 s[58:59], vcc
	global_store_dword v167, v130, s[10:11] offset:128
	global_store_dword v167, v131, s[10:11] offset:132
	global_store_dword v167, v132, s[10:11] offset:136
	global_store_dword v167, v133, s[10:11] offset:140
	global_store_dword v167, v134, s[10:11] offset:160
	global_store_dword v167, v135, s[10:11] offset:164
	global_store_dword v167, v136, s[10:11] offset:168
	global_store_dword v167, v137, s[10:11] offset:172
	global_store_dword v167, v138, s[10:11] offset:192
	global_store_dword v167, v139, s[10:11] offset:196
	global_store_dword v167, v140, s[10:11] offset:200
	global_store_dword v167, v141, s[10:11] offset:204
	global_store_dword v167, v142, s[10:11] offset:224
	global_store_dword v167, v143, s[10:11] offset:228
	global_store_dword v167, v144, s[10:11] offset:232
	global_store_dword v167, v145, s[10:11] offset:236
	s_mov_b64 exec, -1
	s_sub_u32 s48, s48, 0x20000
	s_subb_u32 s49, s49, 0
	v_readlane_b32 s2, v246, 14
	s_nop 0
	s_add_i32 s16, s16, s2
	s_branch .Lhw_ffndown_tloop
.Lhw_ffndown_exit:
	s_branch .LBB0_2365
.LBB0_2365:
	v_readlane_b32 s10, v246, 29
	v_readlane_b32 s11, v246, 30
	s_and_b64 vcc, exec, s[10:11]
	s_cbranch_vccz .LBB0_2456
	v_readlane_b32 s10, v247, 39
	v_readlane_b32 s11, v247, 40
	s_andn2_b64 vcc, exec, s[10:11]
	s_cbranch_vccnz .LBB0_2456
	s_and_b64 s[8:9], s[8:9], exec
	s_cselect_b32 s2, 6, 0
	s_cselect_b32 s6, 10, 4
	s_lshl_b64 s[8:9], s[88:89], 4
	s_add_u32 s23, s0, s8
	s_addc_u32 s24, s1, s9
	s_add_u32 s8, s0, 0x160
	s_addc_u32 s9, s1, 0
	s_add_u32 s10, s0, 0xffffffc0
	s_addc_u32 s11, s1, -1
	s_mov_b64 s[12:13], 0
	s_mov_b64 s[18:19], -1
	s_branch .LBB0_2369
